# GEMM K-loops: counter/pointer/exit-test block rotated in front of the loop-back barrier (back-edge rotation); bit-identical
# speedup vs baseline: 1.0029x; 1.0029x over previous
; #define PG8_STAGE2(bufoff, gbase, voff) do { _Pragma("unroll") for (int _i = 0; _i < 2; ++_i) \
;         __builtin_amdgcn_global_load_lds((const unsigned*)((const char*)(gbase) + (voff)[_i]), (LAS unsigned*)(lds + (bufoff) + ldsw + _i * 8192), 16, 0, 0); } while (0)
; #define PG8_LDA(dst, b, h) do { _Pragma("unroll") for (int m = 0; m < 4; ++m) _Pragma("unroll") for (int k = 0; k < 2; ++k) dst[m][k] = *(const LAS bf16x8*)(lds + PG8_SA(b, h) + aoff + m * 2048 + k * 1024); } while (0)
; #define PG8_LDB(dst, b, h) do { _Pragma("unroll") for (int n = 0; n < 2; ++n) _Pragma("unroll") for (int k = 0; k < 2; ++k) dst[n][k] = *(const LAS bf16x8*)(lds + PG8_SB(b, h) + boff + n * 2048 + k * 1024); } while (0)
; #define PG8_MMA(ai, bj, At, Bt) do { __builtin_amdgcn_s_setprio(1); _Pragma("unroll") for (int m = 0; m < 4; ++m) _Pragma("unroll") for (int n = 0; n < 2; ++n) _Pragma("unroll") for (int k = 0; k < 2; ++k) \
;         acc[ai][bj][m][n] = __builtin_amdgcn_mfma_f32_16x16x32_bf16(Bt[n][k], At[m][k], acc[ai][bj][m][n], 0, 0, 0); __builtin_amdgcn_s_setprio(0); } while (0)
; #define PG8_WAIT_V(n) asm volatile("s_waitcnt vmcnt(" #n ")" ::: "memory")
; #define PG8_WAIT_L(n) asm volatile("s_waitcnt lgkmcnt(" #n ")" ::: "memory")
; #define PG8_BAR __builtin_amdgcn_s_barrier()
; #define PG8_SCHED __builtin_amdgcn_sched_barrier(0)
; template <class Epi>
; __device__ __forceinline__ void gemm_phase(LAS unsigned char* lds, const Sched& S, const Epi& E) {
;     ...
;         for (int t = 0; t < nt; t += 2) {
;             const bool last = (t == nt - 2);
;             const char* a1 = cA + (size_t)(t + 1) * kstep;
;             const char* a2 = last ? nA : cA + (size_t)(t + 2) * kstep; const char* b2 = last ? nB : cB + (size_t)(t + 2) * kstep;
;             const char* a3 = a2 + kstep; const char* b3 = b2 + kstep;
;             PG8_LDB(B0, 0, 0); PG8_LDB(B1, 0, 1); PG8_SCHED; PG8_LDA(At, 0, 0); PG8_STAGE2(PG8_SA(1, 1), a1 + hstep, voffA);
;             PG8_WAIT_V(8); PG8_WAIT_L(0); PG8_BAR; PG8_MMA(0, 0, At, B0); PG8_MMA(0, 1, At, B1); PG8_BAR; PG8_SCHED;
;             PG8_LDA(At, 0, 1); PG8_STAGE2(PG8_SB(0, 0), b2, voffB); PG8_STAGE2(PG8_SB(0, 1), b2 + hstep, voffB); PG8_STAGE2(PG8_SA(0, 0), a2, voffA);
.LBB0_153:
	s_add_u32 s8, s42, 0xfff80080
	s_addc_u32 s9, s43, -1
	s_add_i32 s83, 0, 0x10000
	s_cmp_eq_u32 s82, 28
	s_cselect_b32 s61, s55, s9
	s_cselect_b32 s60, s73, s8
	v_add_u32_e32 v161, s83, v158
	s_cselect_b32 s45, s53, s81
	s_cselect_b32 s44, s76, s77
	s_add_i32 s8, 0, 0x14000
	ds_read_b128 v[146:149], v161
	ds_read_b128 v[150:153], v161 offset:1024
	ds_read_b128 v[154:157], v161 offset:2048
	ds_read_b128 v[162:165], v161 offset:3072
	v_add_u32_e32 v161, s8, v158
	ds_read_b128 v[166:169], v161
	ds_read_b128 v[170:173], v161 offset:1024
	ds_read_b128 v[174:177], v161 offset:2048
	ds_read_b128 v[178:181], v161 offset:3072
	v_lshl_add_u64 v[194:195], s[42:43], 0, v[142:143]
	s_add_i32 m0, s62, 0xc000
	ds_read_b128 v[182:185], v160
	ds_read_b128 v[186:189], v160 offset:1024
	ds_read_b128 v[190:193], v160 offset:2048
	ds_read_b128 v[228:231], v160 offset:3072
	ds_read_b128 v[232:235], v160 offset:4096
	ds_read_b128 v[236:239], v160 offset:5120
	ds_read_b128 v[240:243], v160 offset:6144
	ds_read_b128 v[244:247], v160 offset:7168
	global_load_lds_dwordx4 v[194:195], off
	v_lshl_add_u64 v[194:195], s[42:43], 0, v[144:145]
	s_add_i32 m0, s62, 0xe000
	s_nop 0
	global_load_lds_dwordx4 v[194:195], off
	s_waitcnt vmcnt(8)
	s_waitcnt lgkmcnt(0)
	s_barrier
	s_setprio 1
	s_waitcnt lgkmcnt(0)
	v_mfma_f32_16x16x32_bf16 v[126:129], v[146:149], v[182:185], v[126:129]
	v_mfma_f32_16x16x32_bf16 v[122:125], v[154:157], v[182:185], v[122:125]
	v_mfma_f32_16x16x32_bf16 v[110:113], v[146:149], v[190:193], v[110:113]
	v_mfma_f32_16x16x32_bf16 v[106:109], v[154:157], v[190:193], v[106:109]
	v_mfma_f32_16x16x32_bf16 v[94:97], v[146:149], v[232:235], v[94:97]
	v_mfma_f32_16x16x32_bf16 v[90:93], v[154:157], v[232:235], v[90:93]
	v_mfma_f32_16x16x32_bf16 v[78:81], v[146:149], v[240:243], v[78:81]
	v_mfma_f32_16x16x32_bf16 v[74:77], v[154:157], v[240:243], v[74:77]
	v_mfma_f32_16x16x32_bf16 v[126:129], v[150:153], v[186:189], v[126:129]
	v_mfma_f32_16x16x32_bf16 v[122:125], v[162:165], v[186:189], v[122:125]
	v_mfma_f32_16x16x32_bf16 v[110:113], v[150:153], v[228:231], v[110:113]
	v_mfma_f32_16x16x32_bf16 v[106:109], v[162:165], v[228:231], v[106:109]
	v_mfma_f32_16x16x32_bf16 v[94:97], v[150:153], v[236:239], v[94:97]
	v_mfma_f32_16x16x32_bf16 v[90:93], v[162:165], v[236:239], v[90:93]
	v_mfma_f32_16x16x32_bf16 v[78:81], v[150:153], v[244:247], v[78:81]
	v_mfma_f32_16x16x32_bf16 v[74:77], v[162:165], v[244:247], v[74:77]
	s_setprio 0
	s_setprio 1
	v_mfma_f32_16x16x32_bf16 v[118:121], v[166:169], v[182:185], v[118:121]
	v_mfma_f32_16x16x32_bf16 v[114:117], v[174:177], v[182:185], v[114:117]
	v_mfma_f32_16x16x32_bf16 v[102:105], v[166:169], v[190:193], v[102:105]
	v_mfma_f32_16x16x32_bf16 v[98:101], v[174:177], v[190:193], v[98:101]
	v_mfma_f32_16x16x32_bf16 v[86:89], v[166:169], v[232:235], v[86:89]
	v_mfma_f32_16x16x32_bf16 v[82:85], v[174:177], v[232:235], v[82:85]
	v_mfma_f32_16x16x32_bf16 v[70:73], v[166:169], v[240:243], v[70:73]
	v_mfma_f32_16x16x32_bf16 v[66:69], v[174:177], v[240:243], v[66:69]
	v_mfma_f32_16x16x32_bf16 v[118:121], v[170:173], v[186:189], v[118:121]
	v_mfma_f32_16x16x32_bf16 v[114:117], v[178:181], v[186:189], v[114:117]
	v_mfma_f32_16x16x32_bf16 v[102:105], v[170:173], v[228:231], v[102:105]
	v_mfma_f32_16x16x32_bf16 v[98:101], v[178:181], v[228:231], v[98:101]
	v_mfma_f32_16x16x32_bf16 v[86:89], v[170:173], v[236:239], v[86:89]
	v_mfma_f32_16x16x32_bf16 v[82:85], v[178:181], v[236:239], v[82:85]
	v_mfma_f32_16x16x32_bf16 v[70:73], v[170:173], v[244:247], v[70:73]
	v_mfma_f32_16x16x32_bf16 v[66:69], v[178:181], v[244:247], v[66:69]
	s_setprio 0
	s_barrier
	s_add_i32 s9, s83, s36
	v_lshl_add_u64 v[194:195], s[44:45], 0, v[134:135]
	s_mov_b32 m0, s9
	ds_read_b128 v[182:185], v160 offset:16384
	ds_read_b128 v[186:189], v160 offset:17408
	ds_read_b128 v[190:193], v160 offset:18432
	ds_read_b128 v[228:231], v160 offset:19456
	ds_read_b128 v[232:235], v160 offset:20480
	ds_read_b128 v[236:239], v160 offset:21504
	ds_read_b128 v[240:243], v160 offset:22528
	ds_read_b128 v[244:247], v160 offset:23552
	global_load_lds_dwordx4 v[194:195], off
	s_add_i32 m0, s9, 0x2000
	s_add_u32 s84, s44, 0x80000
	v_lshl_add_u64 v[196:197], s[44:45], 0, v[130:131]
	s_addc_u32 s85, s45, 0
	s_add_i32 s8, s8, s36
	global_load_lds_dwordx4 v[196:197], off
	v_lshl_add_u64 v[198:199], s[84:85], 0, v[134:135]
	s_mov_b32 m0, s8
	v_lshl_add_u64 v[200:201], s[60:61], 0, v[132:133]
	global_load_lds_dwordx4 v[198:199], off
	v_lshl_add_u64 v[198:199], s[84:85], 0, v[130:131]
	s_add_i32 m0, s8, 0x2000
	s_nop 0
	global_load_lds_dwordx4 v[198:199], off
	v_lshl_add_u64 v[198:199], s[60:61], 0, v[136:137]
	s_mov_b32 m0, s62
	s_nop 0
	global_load_lds_dwordx4 v[198:199], off
	s_mov_b32 m0, s63
	s_nop 0
	global_load_lds_dwordx4 v[200:201], off
	s_waitcnt vmcnt(8)
	s_waitcnt lgkmcnt(0)
	s_barrier
; #define PG8_STAGE2(bufoff, gbase, voff) do { _Pragma("unroll") for (int _i = 0; _i < 2; ++_i) \
;         __builtin_amdgcn_global_load_lds((const unsigned*)((const char*)(gbase) + (voff)[_i]), (LAS unsigned*)(lds + (bufoff) + ldsw + _i * 8192), 16, 0, 0); } while (0)
; #define PG8_LDA(dst, b, h) do { _Pragma("unroll") for (int m = 0; m < 4; ++m) _Pragma("unroll") for (int k = 0; k < 2; ++k) dst[m][k] = *(const LAS bf16x8*)(lds + PG8_SA(b, h) + aoff + m * 2048 + k * 1024); } while (0)
; #define PG8_LDB(dst, b, h) do { _Pragma("unroll") for (int n = 0; n < 2; ++n) _Pragma("unroll") for (int k = 0; k < 2; ++k) dst[n][k] = *(const LAS bf16x8*)(lds + PG8_SB(b, h) + boff + n * 2048 + k * 1024); } while (0)
; #define PG8_MMA(ai, bj, At, Bt) do { __builtin_amdgcn_s_setprio(1); _Pragma("unroll") for (int m = 0; m < 4; ++m) _Pragma("unroll") for (int n = 0; n < 2; ++n) _Pragma("unroll") for (int k = 0; k < 2; ++k) \
;         acc[ai][bj][m][n] = __builtin_amdgcn_mfma_f32_16x16x32_bf16(Bt[n][k], At[m][k], acc[ai][bj][m][n], 0, 0, 0); __builtin_amdgcn_s_setprio(0); } while (0)
; #define PG8_WAIT_V(n) asm volatile("s_waitcnt vmcnt(" #n ")" ::: "memory")
; #define PG8_WAIT_L(n) asm volatile("s_waitcnt lgkmcnt(" #n ")" ::: "memory")
; #define PG8_BAR __builtin_amdgcn_s_barrier()
; #define PG8_SCHED __builtin_amdgcn_sched_barrier(0)
; template <class Epi>
; __device__ __forceinline__ void gemm_phase(LAS unsigned char* lds, const Sched& S, const Epi& E) {
;     ...
;             PG8_WAIT_V(8); PG8_WAIT_L(0); PG8_BAR; PG8_MMA(1, 0, At, B0); PG8_MMA(1, 1, At, B1); PG8_BAR; PG8_SCHED;
;             PG8_LDB(B0, 1, 0); PG8_LDB(B1, 1, 1); PG8_SCHED; PG8_LDA(At, 1, 0); PG8_STAGE2(PG8_SA(0, 1), a2 + hstep, voffA);
;             PG8_WAIT_V(8); PG8_WAIT_L(0); PG8_BAR; PG8_MMA(0, 0, At, B0); PG8_MMA(0, 1, At, B1); PG8_BAR; PG8_SCHED;
	s_setprio 1
	s_waitcnt lgkmcnt(0)
	v_mfma_f32_16x16x32_bf16 v[62:65], v[146:149], v[182:185], v[62:65]
	v_mfma_f32_16x16x32_bf16 v[58:61], v[154:157], v[182:185], v[58:61]
	v_mfma_f32_16x16x32_bf16 v[46:49], v[146:149], v[190:193], v[46:49]
	v_mfma_f32_16x16x32_bf16 v[42:45], v[154:157], v[190:193], v[42:45]
	v_mfma_f32_16x16x32_bf16 v[30:33], v[146:149], v[232:235], v[30:33]
	v_mfma_f32_16x16x32_bf16 v[26:29], v[154:157], v[232:235], v[26:29]
	v_mfma_f32_16x16x32_bf16 v[14:17], v[146:149], v[240:243], v[14:17]
	v_mfma_f32_16x16x32_bf16 v[10:13], v[154:157], v[240:243], v[10:13]
	v_mfma_f32_16x16x32_bf16 v[62:65], v[150:153], v[186:189], v[62:65]
	v_mfma_f32_16x16x32_bf16 v[58:61], v[162:165], v[186:189], v[58:61]
	v_mfma_f32_16x16x32_bf16 v[46:49], v[150:153], v[228:231], v[46:49]
	v_mfma_f32_16x16x32_bf16 v[42:45], v[162:165], v[228:231], v[42:45]
	v_mfma_f32_16x16x32_bf16 v[30:33], v[150:153], v[236:239], v[30:33]
	v_mfma_f32_16x16x32_bf16 v[26:29], v[162:165], v[236:239], v[26:29]
	v_mfma_f32_16x16x32_bf16 v[14:17], v[150:153], v[244:247], v[14:17]
	v_mfma_f32_16x16x32_bf16 v[10:13], v[162:165], v[244:247], v[10:13]
	s_setprio 0
	s_setprio 1
	v_mfma_f32_16x16x32_bf16 v[54:57], v[166:169], v[182:185], v[54:57]
	v_mfma_f32_16x16x32_bf16 v[50:53], v[174:177], v[182:185], v[50:53]
	v_mfma_f32_16x16x32_bf16 v[38:41], v[166:169], v[190:193], v[38:41]
	v_mfma_f32_16x16x32_bf16 v[34:37], v[174:177], v[190:193], v[34:37]
	v_mfma_f32_16x16x32_bf16 v[22:25], v[166:169], v[232:235], v[22:25]
	v_mfma_f32_16x16x32_bf16 v[18:21], v[174:177], v[232:235], v[18:21]
	v_mfma_f32_16x16x32_bf16 v[6:9], v[166:169], v[240:243], v[6:9]
	v_mfma_f32_16x16x32_bf16 v[2:5], v[174:177], v[240:243], v[2:5]
	v_mfma_f32_16x16x32_bf16 v[54:57], v[170:173], v[186:189], v[54:57]
	v_mfma_f32_16x16x32_bf16 v[50:53], v[178:181], v[186:189], v[50:53]
	v_mfma_f32_16x16x32_bf16 v[38:41], v[170:173], v[228:231], v[38:41]
	v_mfma_f32_16x16x32_bf16 v[34:37], v[178:181], v[228:231], v[34:37]
	v_mfma_f32_16x16x32_bf16 v[22:25], v[170:173], v[236:239], v[22:25]
	v_mfma_f32_16x16x32_bf16 v[18:21], v[178:181], v[236:239], v[18:21]
	v_mfma_f32_16x16x32_bf16 v[6:9], v[170:173], v[244:247], v[6:9]
	v_mfma_f32_16x16x32_bf16 v[2:5], v[178:181], v[244:247], v[2:5]
	s_setprio 0
	s_barrier
	s_add_i32 s8, 0, 0x18000
	v_add_u32_e32 v161, s8, v158
	s_add_i32 s9, 0, 0x1c000
	ds_read_b128 v[146:149], v161
	ds_read_b128 v[150:153], v161 offset:1024
	ds_read_b128 v[154:157], v161 offset:2048
	ds_read_b128 v[162:165], v161 offset:3072
	v_add_u32_e32 v161, s9, v158
	ds_read_b128 v[166:169], v161
	ds_read_b128 v[170:173], v161 offset:1024
	ds_read_b128 v[174:177], v161 offset:2048
	ds_read_b128 v[178:181], v161 offset:3072
	s_add_u32 s60, s60, 0x80000
	s_addc_u32 s61, s61, 0
	s_mov_b32 m0, s64
	v_lshl_add_u64 v[206:207], s[60:61], 0, v[136:137]
	ds_read_b128 v[182:185], v160 offset:32768
	ds_read_b128 v[186:189], v160 offset:33792
	ds_read_b128 v[190:193], v160 offset:34816
	ds_read_b128 v[228:231], v160 offset:35840
	ds_read_b128 v[232:235], v160 offset:36864
	ds_read_b128 v[236:239], v160 offset:37888
	ds_read_b128 v[240:243], v160 offset:38912
	ds_read_b128 v[244:247], v160 offset:39936
	global_load_lds_dwordx4 v[206:207], off
	v_lshl_add_u64 v[206:207], s[60:61], 0, v[132:133]
	s_mov_b32 m0, s65
	s_nop 0
	global_load_lds_dwordx4 v[206:207], off
	s_waitcnt vmcnt(8)
	s_waitcnt lgkmcnt(0)
	s_barrier
	s_setprio 1
	s_waitcnt lgkmcnt(0)
	v_mfma_f32_16x16x32_bf16 v[126:129], v[146:149], v[182:185], v[126:129]
	v_mfma_f32_16x16x32_bf16 v[122:125], v[154:157], v[182:185], v[122:125]
	v_mfma_f32_16x16x32_bf16 v[110:113], v[146:149], v[190:193], v[110:113]
	v_mfma_f32_16x16x32_bf16 v[106:109], v[154:157], v[190:193], v[106:109]
	v_mfma_f32_16x16x32_bf16 v[94:97], v[146:149], v[232:235], v[94:97]
	v_mfma_f32_16x16x32_bf16 v[90:93], v[154:157], v[232:235], v[90:93]
	v_mfma_f32_16x16x32_bf16 v[78:81], v[146:149], v[240:243], v[78:81]
	v_mfma_f32_16x16x32_bf16 v[74:77], v[154:157], v[240:243], v[74:77]
	v_mfma_f32_16x16x32_bf16 v[126:129], v[150:153], v[186:189], v[126:129]
	v_mfma_f32_16x16x32_bf16 v[122:125], v[162:165], v[186:189], v[122:125]
	v_mfma_f32_16x16x32_bf16 v[110:113], v[150:153], v[228:231], v[110:113]
	v_mfma_f32_16x16x32_bf16 v[106:109], v[162:165], v[228:231], v[106:109]
	v_mfma_f32_16x16x32_bf16 v[94:97], v[150:153], v[236:239], v[94:97]
	v_mfma_f32_16x16x32_bf16 v[90:93], v[162:165], v[236:239], v[90:93]
	v_mfma_f32_16x16x32_bf16 v[78:81], v[150:153], v[244:247], v[78:81]
	v_mfma_f32_16x16x32_bf16 v[74:77], v[162:165], v[244:247], v[74:77]
	s_setprio 0
	s_setprio 1
	v_mfma_f32_16x16x32_bf16 v[118:121], v[166:169], v[182:185], v[118:121]
	v_mfma_f32_16x16x32_bf16 v[114:117], v[174:177], v[182:185], v[114:117]
	v_mfma_f32_16x16x32_bf16 v[102:105], v[166:169], v[190:193], v[102:105]
	v_mfma_f32_16x16x32_bf16 v[98:101], v[174:177], v[190:193], v[98:101]
	v_mfma_f32_16x16x32_bf16 v[86:89], v[166:169], v[232:235], v[86:89]
	v_mfma_f32_16x16x32_bf16 v[82:85], v[174:177], v[232:235], v[82:85]
	v_mfma_f32_16x16x32_bf16 v[70:73], v[166:169], v[240:243], v[70:73]
	v_mfma_f32_16x16x32_bf16 v[66:69], v[174:177], v[240:243], v[66:69]
	v_mfma_f32_16x16x32_bf16 v[118:121], v[170:173], v[186:189], v[118:121]
	v_mfma_f32_16x16x32_bf16 v[114:117], v[178:181], v[186:189], v[114:117]
	v_mfma_f32_16x16x32_bf16 v[102:105], v[170:173], v[228:231], v[102:105]
	v_mfma_f32_16x16x32_bf16 v[98:101], v[178:181], v[228:231], v[98:101]
	v_mfma_f32_16x16x32_bf16 v[86:89], v[170:173], v[236:239], v[86:89]
	v_mfma_f32_16x16x32_bf16 v[82:85], v[178:181], v[236:239], v[82:85]
	v_mfma_f32_16x16x32_bf16 v[70:73], v[170:173], v[244:247], v[70:73]
	v_mfma_f32_16x16x32_bf16 v[66:69], v[178:181], v[244:247], v[66:69]
	s_setprio 0
	s_barrier
; #define PG8_STAGE2(bufoff, gbase, voff) do { _Pragma("unroll") for (int _i = 0; _i < 2; ++_i) \
;         __builtin_amdgcn_global_load_lds((const unsigned*)((const char*)(gbase) + (voff)[_i]), (LAS unsigned*)(lds + (bufoff) + ldsw + _i * 8192), 16, 0, 0); } while (0)
; #define PG8_LDA(dst, b, h) do { _Pragma("unroll") for (int m = 0; m < 4; ++m) _Pragma("unroll") for (int k = 0; k < 2; ++k) dst[m][k] = *(const LAS bf16x8*)(lds + PG8_SA(b, h) + aoff + m * 2048 + k * 1024); } while (0)
; #define PG8_MMA(ai, bj, At, Bt) do { __builtin_amdgcn_s_setprio(1); _Pragma("unroll") for (int m = 0; m < 4; ++m) _Pragma("unroll") for (int n = 0; n < 2; ++n) _Pragma("unroll") for (int k = 0; k < 2; ++k) \
;         acc[ai][bj][m][n] = __builtin_amdgcn_mfma_f32_16x16x32_bf16(Bt[n][k], At[m][k], acc[ai][bj][m][n], 0, 0, 0); __builtin_amdgcn_s_setprio(0); } while (0)
; #define PG8_WAIT_V(n) asm volatile("s_waitcnt vmcnt(" #n ")" ::: "memory")
; #define PG8_WAIT_L(n) asm volatile("s_waitcnt lgkmcnt(" #n ")" ::: "memory")
; #define PG8_BAR __builtin_amdgcn_s_barrier()
; #define PG8_SCHED __builtin_amdgcn_sched_barrier(0)
; template <class Epi>
; __device__ __forceinline__ void gemm_phase(LAS unsigned char* lds, const Sched& S, const Epi& E) {
;     ...
;             PG8_LDA(At, 1, 1); PG8_STAGE2(PG8_SB(1, 0), b3, voffB); PG8_STAGE2(PG8_SB(1, 1), b3 + hstep, voffB); PG8_STAGE2(PG8_SA(1, 0), a3, voffA);
;             PG8_WAIT_V(8); PG8_WAIT_L(0); PG8_BAR; PG8_MMA(1, 0, At, B0); PG8_MMA(1, 1, At, B1); PG8_BAR; PG8_SCHED;
;         }
;         if (wr == 0) PG8_BAR;
	s_add_i32 s8, s8, s36
	v_lshl_add_u64 v[194:195], v[194:195], 0, s[22:23]
	s_mov_b32 m0, s8
	ds_read_b128 v[182:185], v160 offset:49152
	ds_read_b128 v[186:189], v160 offset:50176
	ds_read_b128 v[190:193], v160 offset:51200
	ds_read_b128 v[228:231], v160 offset:52224
	ds_read_b128 v[232:235], v160 offset:53248
	ds_read_b128 v[236:239], v160 offset:54272
	ds_read_b128 v[240:243], v160 offset:55296
	ds_read_b128 v[244:247], v160 offset:56320
	global_load_lds_dwordx4 v[194:195], off
	s_add_i32 m0, s8, 0x2000
	s_add_u32 s44, s44, 0x80080
	v_lshl_add_u64 v[194:195], v[196:197], 0, s[22:23]
	s_addc_u32 s45, s45, 0
	s_add_i32 s8, s9, s36
	global_load_lds_dwordx4 v[194:195], off
	v_lshl_add_u64 v[194:195], s[44:45], 0, v[134:135]
	s_mov_b32 m0, s8
	s_nop 0
	global_load_lds_dwordx4 v[194:195], off
	v_lshl_add_u64 v[194:195], s[44:45], 0, v[130:131]
	s_add_i32 m0, s8, 0x2000
	s_nop 0
	global_load_lds_dwordx4 v[194:195], off
	v_lshl_add_u64 v[194:195], v[198:199], 0, s[22:23]
	s_mov_b32 m0, s66
	s_nop 0
	global_load_lds_dwordx4 v[194:195], off
	v_lshl_add_u64 v[194:195], v[200:201], 0, s[22:23]
	s_mov_b32 m0, s67
	s_nop 0
	global_load_lds_dwordx4 v[194:195], off
	s_waitcnt vmcnt(8)
	s_waitcnt lgkmcnt(0)
	s_barrier
	s_setprio 1
	s_waitcnt lgkmcnt(0)
	v_mfma_f32_16x16x32_bf16 v[62:65], v[146:149], v[182:185], v[62:65]
	v_mfma_f32_16x16x32_bf16 v[58:61], v[154:157], v[182:185], v[58:61]
	v_mfma_f32_16x16x32_bf16 v[46:49], v[146:149], v[190:193], v[46:49]
	v_mfma_f32_16x16x32_bf16 v[42:45], v[154:157], v[190:193], v[42:45]
	v_mfma_f32_16x16x32_bf16 v[30:33], v[146:149], v[232:235], v[30:33]
	v_mfma_f32_16x16x32_bf16 v[26:29], v[154:157], v[232:235], v[26:29]
	v_mfma_f32_16x16x32_bf16 v[14:17], v[146:149], v[240:243], v[14:17]
	v_mfma_f32_16x16x32_bf16 v[10:13], v[154:157], v[240:243], v[10:13]
	v_mfma_f32_16x16x32_bf16 v[62:65], v[150:153], v[186:189], v[62:65]
	v_mfma_f32_16x16x32_bf16 v[58:61], v[162:165], v[186:189], v[58:61]
	v_mfma_f32_16x16x32_bf16 v[46:49], v[150:153], v[228:231], v[46:49]
	v_mfma_f32_16x16x32_bf16 v[42:45], v[162:165], v[228:231], v[42:45]
	v_mfma_f32_16x16x32_bf16 v[30:33], v[150:153], v[236:239], v[30:33]
	v_mfma_f32_16x16x32_bf16 v[26:29], v[162:165], v[236:239], v[26:29]
	v_mfma_f32_16x16x32_bf16 v[14:17], v[150:153], v[244:247], v[14:17]
	v_mfma_f32_16x16x32_bf16 v[10:13], v[162:165], v[244:247], v[10:13]
	s_setprio 0
	s_setprio 1
	v_mfma_f32_16x16x32_bf16 v[54:57], v[166:169], v[182:185], v[54:57]
	v_mfma_f32_16x16x32_bf16 v[50:53], v[174:177], v[182:185], v[50:53]
	v_mfma_f32_16x16x32_bf16 v[38:41], v[166:169], v[190:193], v[38:41]
	v_mfma_f32_16x16x32_bf16 v[34:37], v[174:177], v[190:193], v[34:37]
	v_mfma_f32_16x16x32_bf16 v[22:25], v[166:169], v[232:235], v[22:25]
	v_mfma_f32_16x16x32_bf16 v[18:21], v[174:177], v[232:235], v[18:21]
	v_mfma_f32_16x16x32_bf16 v[6:9], v[166:169], v[240:243], v[6:9]
	v_mfma_f32_16x16x32_bf16 v[2:5], v[174:177], v[240:243], v[2:5]
	v_mfma_f32_16x16x32_bf16 v[54:57], v[170:173], v[186:189], v[54:57]
	v_mfma_f32_16x16x32_bf16 v[50:53], v[178:181], v[186:189], v[50:53]
	v_mfma_f32_16x16x32_bf16 v[38:41], v[170:173], v[228:231], v[38:41]
	v_mfma_f32_16x16x32_bf16 v[34:37], v[178:181], v[228:231], v[34:37]
	v_mfma_f32_16x16x32_bf16 v[22:25], v[170:173], v[236:239], v[22:25]
	v_mfma_f32_16x16x32_bf16 v[18:21], v[178:181], v[236:239], v[18:21]
	v_mfma_f32_16x16x32_bf16 v[6:9], v[170:173], v[244:247], v[6:9]
	v_mfma_f32_16x16x32_bf16 v[2:5], v[178:181], v[244:247], v[2:5]
	s_setprio 0
	s_add_i32 s82, s82, 2
	s_add_u32 s42, s42, 0x100
	s_addc_u32 s43, s43, 0
	s_add_u32 s77, s77, 0x100
	s_addc_u32 s81, s81, 0
	s_cmp_gt_u32 s82, 29
	s_barrier
	s_cbranch_scc0 .LBB0_153
	s_and_b64 vcc, exec, s[48:49]
	s_cbranch_vccz .LBB0_156
	s_barrier

; #define PG8_STAGE2(bufoff, gbase, voff) do { _Pragma("unroll") for (int _i = 0; _i < 2; ++_i) \
;         __builtin_amdgcn_global_load_lds((const unsigned*)((const char*)(gbase) + (voff)[_i]), (LAS unsigned*)(lds + (bufoff) + ldsw + _i * 8192), 16, 0, 0); } while (0)
; #define PG8_LDA(dst, b, h) do { _Pragma("unroll") for (int m = 0; m < 4; ++m) _Pragma("unroll") for (int k = 0; k < 2; ++k) dst[m][k] = *(const LAS bf16x8*)(lds + PG8_SA(b, h) + aoff + m * 2048 + k * 1024); } while (0)
; #define PG8_LDB(dst, b, h) do { _Pragma("unroll") for (int n = 0; n < 2; ++n) _Pragma("unroll") for (int k = 0; k < 2; ++k) dst[n][k] = *(const LAS bf16x8*)(lds + PG8_SB(b, h) + boff + n * 2048 + k * 1024); } while (0)
; #define PG8_MMA(ai, bj, At, Bt) do { __builtin_amdgcn_s_setprio(1); _Pragma("unroll") for (int m = 0; m < 4; ++m) _Pragma("unroll") for (int n = 0; n < 2; ++n) _Pragma("unroll") for (int k = 0; k < 2; ++k) \
;         acc[ai][bj][m][n] = __builtin_amdgcn_mfma_f32_16x16x32_bf16(Bt[n][k], At[m][k], acc[ai][bj][m][n], 0, 0, 0); __builtin_amdgcn_s_setprio(0); } while (0)
; #define PG8_WAIT_V(n) asm volatile("s_waitcnt vmcnt(" #n ")" ::: "memory")
; #define PG8_WAIT_L(n) asm volatile("s_waitcnt lgkmcnt(" #n ")" ::: "memory")
; #define PG8_BAR __builtin_amdgcn_s_barrier()
; #define PG8_SCHED __builtin_amdgcn_sched_barrier(0)
; template <class Epi>
; __device__ __forceinline__ void gemm_phase(LAS unsigned char* lds, const Sched& S, const Epi& E) {
;     ...
;         for (int t = 0; t < nt; t += 2) {
;             const bool last = (t == nt - 2);
;             const char* a1 = cA + (size_t)(t + 1) * kstep;
;             const char* a2 = last ? nA : cA + (size_t)(t + 2) * kstep; const char* b2 = last ? nB : cB + (size_t)(t + 2) * kstep;
;             const char* a3 = a2 + kstep; const char* b3 = b2 + kstep;
;             PG8_LDB(B0, 0, 0); PG8_LDB(B1, 0, 1); PG8_SCHED; PG8_LDA(At, 0, 0); PG8_STAGE2(PG8_SA(1, 1), a1 + hstep, voffA);
;             PG8_WAIT_V(8); PG8_WAIT_L(0); PG8_BAR; PG8_MMA(0, 0, At, B0); PG8_MMA(0, 1, At, B1); PG8_BAR; PG8_SCHED;
;             PG8_LDA(At, 0, 1); PG8_STAGE2(PG8_SB(0, 0), b2, voffB); PG8_STAGE2(PG8_SB(0, 1), b2 + hstep, voffB); PG8_STAGE2(PG8_SA(0, 0), a2, voffA);
.LBB0_318:
	s_add_u32 s8, s42, 0xfff80080
	s_addc_u32 s9, s43, -1
	s_add_i32 s10, 0, 0x10000
	s_cmp_eq_u32 s81, 28
	s_cselect_b32 s61, s55, s9
	s_cselect_b32 s60, s73, s8
	v_add_u32_e32 v161, s10, v158
	s_cselect_b32 s45, s53, s80
	s_cselect_b32 s44, s76, s77
	s_add_i32 s11, 0, 0x14000
	ds_read_b128 v[146:149], v161
	ds_read_b128 v[150:153], v161 offset:1024
	ds_read_b128 v[154:157], v161 offset:2048
	ds_read_b128 v[162:165], v161 offset:3072
	v_add_u32_e32 v161, s11, v158
	ds_read_b128 v[166:169], v161
	ds_read_b128 v[170:173], v161 offset:1024
	ds_read_b128 v[174:177], v161 offset:2048
	ds_read_b128 v[178:181], v161 offset:3072
	v_lshl_add_u64 v[232:233], s[42:43], 0, v[142:143]
	s_add_i32 m0, s4, 0xc000
	ds_read_b128 v[182:185], v160
	ds_read_b128 v[186:189], v160 offset:1024
	ds_read_b128 v[190:193], v160 offset:2048
	ds_read_b128 v[194:197], v160 offset:3072
	ds_read_b128 v[198:201], v160 offset:4096
	ds_read_b128 v[206:209], v160 offset:5120
	ds_read_b128 v[210:213], v160 offset:6144
	ds_read_b128 v[228:231], v160 offset:7168
	global_load_lds_dwordx4 v[232:233], off
	v_lshl_add_u64 v[232:233], s[42:43], 0, v[144:145]
	s_add_i32 m0, s4, 0xe000
	s_nop 0
	global_load_lds_dwordx4 v[232:233], off
	s_waitcnt vmcnt(8)
	s_waitcnt lgkmcnt(0)
	s_barrier
	s_setprio 1
	s_waitcnt lgkmcnt(0)
	v_mfma_f32_16x16x32_bf16 v[126:129], v[146:149], v[182:185], v[126:129]
	v_mfma_f32_16x16x32_bf16 v[122:125], v[154:157], v[182:185], v[122:125]
	v_mfma_f32_16x16x32_bf16 v[110:113], v[146:149], v[190:193], v[110:113]
	v_mfma_f32_16x16x32_bf16 v[106:109], v[154:157], v[190:193], v[106:109]
	v_mfma_f32_16x16x32_bf16 v[94:97], v[146:149], v[198:201], v[94:97]
	v_mfma_f32_16x16x32_bf16 v[90:93], v[154:157], v[198:201], v[90:93]
	v_mfma_f32_16x16x32_bf16 v[78:81], v[146:149], v[210:213], v[78:81]
	v_mfma_f32_16x16x32_bf16 v[74:77], v[154:157], v[210:213], v[74:77]
	v_mfma_f32_16x16x32_bf16 v[126:129], v[150:153], v[186:189], v[126:129]
	v_mfma_f32_16x16x32_bf16 v[122:125], v[162:165], v[186:189], v[122:125]
	v_mfma_f32_16x16x32_bf16 v[110:113], v[150:153], v[194:197], v[110:113]
	v_mfma_f32_16x16x32_bf16 v[106:109], v[162:165], v[194:197], v[106:109]
	v_mfma_f32_16x16x32_bf16 v[94:97], v[150:153], v[206:209], v[94:97]
	v_mfma_f32_16x16x32_bf16 v[90:93], v[162:165], v[206:209], v[90:93]
	v_mfma_f32_16x16x32_bf16 v[78:81], v[150:153], v[228:231], v[78:81]
	v_mfma_f32_16x16x32_bf16 v[74:77], v[162:165], v[228:231], v[74:77]
	s_setprio 0
	s_setprio 1
	v_mfma_f32_16x16x32_bf16 v[118:121], v[166:169], v[182:185], v[118:121]
	v_mfma_f32_16x16x32_bf16 v[114:117], v[174:177], v[182:185], v[114:117]
	v_mfma_f32_16x16x32_bf16 v[102:105], v[166:169], v[190:193], v[102:105]
	v_mfma_f32_16x16x32_bf16 v[98:101], v[174:177], v[190:193], v[98:101]
	v_mfma_f32_16x16x32_bf16 v[86:89], v[166:169], v[198:201], v[86:89]
	v_mfma_f32_16x16x32_bf16 v[82:85], v[174:177], v[198:201], v[82:85]
	v_mfma_f32_16x16x32_bf16 v[70:73], v[166:169], v[210:213], v[70:73]
	v_mfma_f32_16x16x32_bf16 v[66:69], v[174:177], v[210:213], v[66:69]
	v_mfma_f32_16x16x32_bf16 v[118:121], v[170:173], v[186:189], v[118:121]
	v_mfma_f32_16x16x32_bf16 v[114:117], v[178:181], v[186:189], v[114:117]
	v_mfma_f32_16x16x32_bf16 v[102:105], v[170:173], v[194:197], v[102:105]
	v_mfma_f32_16x16x32_bf16 v[98:101], v[178:181], v[194:197], v[98:101]
	v_mfma_f32_16x16x32_bf16 v[86:89], v[170:173], v[206:209], v[86:89]
	v_mfma_f32_16x16x32_bf16 v[82:85], v[178:181], v[206:209], v[82:85]
	v_mfma_f32_16x16x32_bf16 v[70:73], v[170:173], v[228:231], v[70:73]
	v_mfma_f32_16x16x32_bf16 v[66:69], v[178:181], v[228:231], v[66:69]
	s_setprio 0
	s_barrier
	s_add_i32 s8, s10, s65
	v_lshl_add_u64 v[232:233], s[44:45], 0, v[134:135]
	s_mov_b32 m0, s8
	ds_read_b128 v[182:185], v160 offset:16384
	ds_read_b128 v[186:189], v160 offset:17408
	ds_read_b128 v[190:193], v160 offset:18432
	ds_read_b128 v[194:197], v160 offset:19456
	ds_read_b128 v[198:201], v160 offset:20480
	ds_read_b128 v[206:209], v160 offset:21504
	ds_read_b128 v[210:213], v160 offset:22528
	ds_read_b128 v[228:231], v160 offset:23552
	global_load_lds_dwordx4 v[232:233], off
	s_add_i32 m0, s8, 0x2000
	s_add_u32 s8, s44, 0x80000
	v_lshl_add_u64 v[234:235], s[44:45], 0, v[130:131]
	s_addc_u32 s9, s45, 0
	s_add_i32 s10, s11, s65
	global_load_lds_dwordx4 v[234:235], off
	v_lshl_add_u64 v[236:237], s[8:9], 0, v[134:135]
	s_mov_b32 m0, s10
	v_lshl_add_u64 v[238:239], s[60:61], 0, v[132:133]
	global_load_lds_dwordx4 v[236:237], off
	v_lshl_add_u64 v[236:237], s[8:9], 0, v[130:131]
	s_add_i32 m0, s10, 0x2000
	s_nop 0
	global_load_lds_dwordx4 v[236:237], off
	v_lshl_add_u64 v[236:237], s[60:61], 0, v[136:137]
	s_mov_b32 m0, s4
	s_nop 0
	global_load_lds_dwordx4 v[236:237], off
	s_mov_b32 m0, s5
	s_nop 0
	global_load_lds_dwordx4 v[238:239], off
	s_waitcnt vmcnt(8)
	s_waitcnt lgkmcnt(0)
	s_barrier
; #define PG8_STAGE2(bufoff, gbase, voff) do { _Pragma("unroll") for (int _i = 0; _i < 2; ++_i) \
;         __builtin_amdgcn_global_load_lds((const unsigned*)((const char*)(gbase) + (voff)[_i]), (LAS unsigned*)(lds + (bufoff) + ldsw + _i * 8192), 16, 0, 0); } while (0)
; #define PG8_LDA(dst, b, h) do { _Pragma("unroll") for (int m = 0; m < 4; ++m) _Pragma("unroll") for (int k = 0; k < 2; ++k) dst[m][k] = *(const LAS bf16x8*)(lds + PG8_SA(b, h) + aoff + m * 2048 + k * 1024); } while (0)
; #define PG8_LDB(dst, b, h) do { _Pragma("unroll") for (int n = 0; n < 2; ++n) _Pragma("unroll") for (int k = 0; k < 2; ++k) dst[n][k] = *(const LAS bf16x8*)(lds + PG8_SB(b, h) + boff + n * 2048 + k * 1024); } while (0)
; #define PG8_MMA(ai, bj, At, Bt) do { __builtin_amdgcn_s_setprio(1); _Pragma("unroll") for (int m = 0; m < 4; ++m) _Pragma("unroll") for (int n = 0; n < 2; ++n) _Pragma("unroll") for (int k = 0; k < 2; ++k) \
;         acc[ai][bj][m][n] = __builtin_amdgcn_mfma_f32_16x16x32_bf16(Bt[n][k], At[m][k], acc[ai][bj][m][n], 0, 0, 0); __builtin_amdgcn_s_setprio(0); } while (0)
; #define PG8_WAIT_V(n) asm volatile("s_waitcnt vmcnt(" #n ")" ::: "memory")
; #define PG8_WAIT_L(n) asm volatile("s_waitcnt lgkmcnt(" #n ")" ::: "memory")
; #define PG8_BAR __builtin_amdgcn_s_barrier()
; #define PG8_SCHED __builtin_amdgcn_sched_barrier(0)
; template <class Epi>
; __device__ __forceinline__ void gemm_phase(LAS unsigned char* lds, const Sched& S, const Epi& E) {
;     ...
;             PG8_WAIT_V(8); PG8_WAIT_L(0); PG8_BAR; PG8_MMA(1, 0, At, B0); PG8_MMA(1, 1, At, B1); PG8_BAR; PG8_SCHED;
;             PG8_LDB(B0, 1, 0); PG8_LDB(B1, 1, 1); PG8_SCHED; PG8_LDA(At, 1, 0); PG8_STAGE2(PG8_SA(0, 1), a2 + hstep, voffA);
;             PG8_WAIT_V(8); PG8_WAIT_L(0); PG8_BAR; PG8_MMA(0, 0, At, B0); PG8_MMA(0, 1, At, B1); PG8_BAR; PG8_SCHED;
	s_setprio 1
	s_waitcnt lgkmcnt(0)
	v_mfma_f32_16x16x32_bf16 v[62:65], v[146:149], v[182:185], v[62:65]
	v_mfma_f32_16x16x32_bf16 v[58:61], v[154:157], v[182:185], v[58:61]
	v_mfma_f32_16x16x32_bf16 v[46:49], v[146:149], v[190:193], v[46:49]
	v_mfma_f32_16x16x32_bf16 v[42:45], v[154:157], v[190:193], v[42:45]
	v_mfma_f32_16x16x32_bf16 v[30:33], v[146:149], v[198:201], v[30:33]
	v_mfma_f32_16x16x32_bf16 v[26:29], v[154:157], v[198:201], v[26:29]
	v_mfma_f32_16x16x32_bf16 v[14:17], v[146:149], v[210:213], v[14:17]
	v_mfma_f32_16x16x32_bf16 v[10:13], v[154:157], v[210:213], v[10:13]
	v_mfma_f32_16x16x32_bf16 v[62:65], v[150:153], v[186:189], v[62:65]
	v_mfma_f32_16x16x32_bf16 v[58:61], v[162:165], v[186:189], v[58:61]
	v_mfma_f32_16x16x32_bf16 v[46:49], v[150:153], v[194:197], v[46:49]
	v_mfma_f32_16x16x32_bf16 v[42:45], v[162:165], v[194:197], v[42:45]
	v_mfma_f32_16x16x32_bf16 v[30:33], v[150:153], v[206:209], v[30:33]
	v_mfma_f32_16x16x32_bf16 v[26:29], v[162:165], v[206:209], v[26:29]
	v_mfma_f32_16x16x32_bf16 v[14:17], v[150:153], v[228:231], v[14:17]
	v_mfma_f32_16x16x32_bf16 v[10:13], v[162:165], v[228:231], v[10:13]
	s_setprio 0
	s_setprio 1
	v_mfma_f32_16x16x32_bf16 v[54:57], v[166:169], v[182:185], v[54:57]
	v_mfma_f32_16x16x32_bf16 v[50:53], v[174:177], v[182:185], v[50:53]
	v_mfma_f32_16x16x32_bf16 v[38:41], v[166:169], v[190:193], v[38:41]
	v_mfma_f32_16x16x32_bf16 v[34:37], v[174:177], v[190:193], v[34:37]
	v_mfma_f32_16x16x32_bf16 v[22:25], v[166:169], v[198:201], v[22:25]
	v_mfma_f32_16x16x32_bf16 v[18:21], v[174:177], v[198:201], v[18:21]
	v_mfma_f32_16x16x32_bf16 v[6:9], v[166:169], v[210:213], v[6:9]
	v_mfma_f32_16x16x32_bf16 v[2:5], v[174:177], v[210:213], v[2:5]
	v_mfma_f32_16x16x32_bf16 v[54:57], v[170:173], v[186:189], v[54:57]
	v_mfma_f32_16x16x32_bf16 v[50:53], v[178:181], v[186:189], v[50:53]
	v_mfma_f32_16x16x32_bf16 v[38:41], v[170:173], v[194:197], v[38:41]
	v_mfma_f32_16x16x32_bf16 v[34:37], v[178:181], v[194:197], v[34:37]
	v_mfma_f32_16x16x32_bf16 v[22:25], v[170:173], v[206:209], v[22:25]
	v_mfma_f32_16x16x32_bf16 v[18:21], v[178:181], v[206:209], v[18:21]
	v_mfma_f32_16x16x32_bf16 v[6:9], v[170:173], v[228:231], v[6:9]
	v_mfma_f32_16x16x32_bf16 v[2:5], v[178:181], v[228:231], v[2:5]
	s_setprio 0
	s_barrier
	s_add_i32 s10, 0, 0x18000
	v_add_u32_e32 v161, s10, v158
	s_add_i32 s11, 0, 0x1c000
	ds_read_b128 v[146:149], v161
	ds_read_b128 v[150:153], v161 offset:1024
	ds_read_b128 v[154:157], v161 offset:2048
	ds_read_b128 v[162:165], v161 offset:3072
	v_add_u32_e32 v161, s11, v158
	ds_read_b128 v[166:169], v161
	ds_read_b128 v[170:173], v161 offset:1024
	ds_read_b128 v[174:177], v161 offset:2048
	ds_read_b128 v[178:181], v161 offset:3072
	s_add_u32 s8, s60, 0x80000
	s_addc_u32 s9, s61, 0
	s_mov_b32 m0, s6
	v_lshl_add_u64 v[240:241], s[8:9], 0, v[136:137]
	ds_read_b128 v[182:185], v160 offset:32768
	ds_read_b128 v[186:189], v160 offset:33792
	ds_read_b128 v[190:193], v160 offset:34816
	ds_read_b128 v[194:197], v160 offset:35840
	ds_read_b128 v[198:201], v160 offset:36864
	ds_read_b128 v[206:209], v160 offset:37888
	ds_read_b128 v[210:213], v160 offset:38912
	ds_read_b128 v[228:231], v160 offset:39936
	global_load_lds_dwordx4 v[240:241], off
	v_lshl_add_u64 v[240:241], s[8:9], 0, v[132:133]
	s_mov_b32 m0, s7
	s_nop 0
	global_load_lds_dwordx4 v[240:241], off
	s_waitcnt vmcnt(8)
	s_waitcnt lgkmcnt(0)
	s_barrier
	s_setprio 1
	s_waitcnt lgkmcnt(0)
	v_mfma_f32_16x16x32_bf16 v[126:129], v[146:149], v[182:185], v[126:129]
	v_mfma_f32_16x16x32_bf16 v[122:125], v[154:157], v[182:185], v[122:125]
	v_mfma_f32_16x16x32_bf16 v[110:113], v[146:149], v[190:193], v[110:113]
	v_mfma_f32_16x16x32_bf16 v[106:109], v[154:157], v[190:193], v[106:109]
	v_mfma_f32_16x16x32_bf16 v[94:97], v[146:149], v[198:201], v[94:97]
	v_mfma_f32_16x16x32_bf16 v[90:93], v[154:157], v[198:201], v[90:93]
	v_mfma_f32_16x16x32_bf16 v[78:81], v[146:149], v[210:213], v[78:81]
	v_mfma_f32_16x16x32_bf16 v[74:77], v[154:157], v[210:213], v[74:77]
	v_mfma_f32_16x16x32_bf16 v[126:129], v[150:153], v[186:189], v[126:129]
	v_mfma_f32_16x16x32_bf16 v[122:125], v[162:165], v[186:189], v[122:125]
	v_mfma_f32_16x16x32_bf16 v[110:113], v[150:153], v[194:197], v[110:113]
	v_mfma_f32_16x16x32_bf16 v[106:109], v[162:165], v[194:197], v[106:109]
	v_mfma_f32_16x16x32_bf16 v[94:97], v[150:153], v[206:209], v[94:97]
	v_mfma_f32_16x16x32_bf16 v[90:93], v[162:165], v[206:209], v[90:93]
	v_mfma_f32_16x16x32_bf16 v[78:81], v[150:153], v[228:231], v[78:81]
	v_mfma_f32_16x16x32_bf16 v[74:77], v[162:165], v[228:231], v[74:77]
	s_setprio 0
	s_setprio 1
	v_mfma_f32_16x16x32_bf16 v[118:121], v[166:169], v[182:185], v[118:121]
	v_mfma_f32_16x16x32_bf16 v[114:117], v[174:177], v[182:185], v[114:117]
	v_mfma_f32_16x16x32_bf16 v[102:105], v[166:169], v[190:193], v[102:105]
	v_mfma_f32_16x16x32_bf16 v[98:101], v[174:177], v[190:193], v[98:101]
	v_mfma_f32_16x16x32_bf16 v[86:89], v[166:169], v[198:201], v[86:89]
	v_mfma_f32_16x16x32_bf16 v[82:85], v[174:177], v[198:201], v[82:85]
	v_mfma_f32_16x16x32_bf16 v[70:73], v[166:169], v[210:213], v[70:73]
	v_mfma_f32_16x16x32_bf16 v[66:69], v[174:177], v[210:213], v[66:69]
	v_mfma_f32_16x16x32_bf16 v[118:121], v[170:173], v[186:189], v[118:121]
	v_mfma_f32_16x16x32_bf16 v[114:117], v[178:181], v[186:189], v[114:117]
	v_mfma_f32_16x16x32_bf16 v[102:105], v[170:173], v[194:197], v[102:105]
	v_mfma_f32_16x16x32_bf16 v[98:101], v[178:181], v[194:197], v[98:101]
	v_mfma_f32_16x16x32_bf16 v[86:89], v[170:173], v[206:209], v[86:89]
	v_mfma_f32_16x16x32_bf16 v[82:85], v[178:181], v[206:209], v[82:85]
	v_mfma_f32_16x16x32_bf16 v[70:73], v[170:173], v[228:231], v[70:73]
	v_mfma_f32_16x16x32_bf16 v[66:69], v[178:181], v[228:231], v[66:69]
	s_setprio 0
	s_barrier
; #define PG8_STAGE2(bufoff, gbase, voff) do { _Pragma("unroll") for (int _i = 0; _i < 2; ++_i) \
;         __builtin_amdgcn_global_load_lds((const unsigned*)((const char*)(gbase) + (voff)[_i]), (LAS unsigned*)(lds + (bufoff) + ldsw + _i * 8192), 16, 0, 0); } while (0)
; #define PG8_LDA(dst, b, h) do { _Pragma("unroll") for (int m = 0; m < 4; ++m) _Pragma("unroll") for (int k = 0; k < 2; ++k) dst[m][k] = *(const LAS bf16x8*)(lds + PG8_SA(b, h) + aoff + m * 2048 + k * 1024); } while (0)
; #define PG8_MMA(ai, bj, At, Bt) do { __builtin_amdgcn_s_setprio(1); _Pragma("unroll") for (int m = 0; m < 4; ++m) _Pragma("unroll") for (int n = 0; n < 2; ++n) _Pragma("unroll") for (int k = 0; k < 2; ++k) \
;         acc[ai][bj][m][n] = __builtin_amdgcn_mfma_f32_16x16x32_bf16(Bt[n][k], At[m][k], acc[ai][bj][m][n], 0, 0, 0); __builtin_amdgcn_s_setprio(0); } while (0)
; #define PG8_WAIT_V(n) asm volatile("s_waitcnt vmcnt(" #n ")" ::: "memory")
; #define PG8_WAIT_L(n) asm volatile("s_waitcnt lgkmcnt(" #n ")" ::: "memory")
; #define PG8_BAR __builtin_amdgcn_s_barrier()
; #define PG8_SCHED __builtin_amdgcn_sched_barrier(0)
; template <class Epi>
; __device__ __forceinline__ void gemm_phase(LAS unsigned char* lds, const Sched& S, const Epi& E) {
;     ...
;             PG8_LDA(At, 1, 1); PG8_STAGE2(PG8_SB(1, 0), b3, voffB); PG8_STAGE2(PG8_SB(1, 1), b3 + hstep, voffB); PG8_STAGE2(PG8_SA(1, 0), a3, voffA);
;             PG8_WAIT_V(8); PG8_WAIT_L(0); PG8_BAR; PG8_MMA(1, 0, At, B0); PG8_MMA(1, 1, At, B1); PG8_BAR; PG8_SCHED;
;         }
;         if (wr == 0) PG8_BAR;
	s_add_i32 s8, s10, s65
	v_lshl_add_u64 v[232:233], v[232:233], 0, s[22:23]
	s_mov_b32 m0, s8
	ds_read_b128 v[182:185], v160 offset:49152
	ds_read_b128 v[186:189], v160 offset:50176
	ds_read_b128 v[190:193], v160 offset:51200
	ds_read_b128 v[194:197], v160 offset:52224
	ds_read_b128 v[198:201], v160 offset:53248
	ds_read_b128 v[206:209], v160 offset:54272
	ds_read_b128 v[210:213], v160 offset:55296
	ds_read_b128 v[228:231], v160 offset:56320
	global_load_lds_dwordx4 v[232:233], off
	s_add_i32 m0, s8, 0x2000
	s_add_u32 s8, s44, 0x80080
	v_lshl_add_u64 v[232:233], v[234:235], 0, s[22:23]
	s_addc_u32 s9, s45, 0
	s_add_i32 s10, s11, s65
	global_load_lds_dwordx4 v[232:233], off
	v_lshl_add_u64 v[232:233], s[8:9], 0, v[134:135]
	s_mov_b32 m0, s10
	s_nop 0
	global_load_lds_dwordx4 v[232:233], off
	v_lshl_add_u64 v[232:233], s[8:9], 0, v[130:131]
	s_add_i32 m0, s10, 0x2000
	s_nop 0
	global_load_lds_dwordx4 v[232:233], off
	v_lshl_add_u64 v[232:233], v[236:237], 0, s[22:23]
	s_mov_b32 m0, s66
	s_nop 0
	global_load_lds_dwordx4 v[232:233], off
	v_lshl_add_u64 v[232:233], v[238:239], 0, s[22:23]
	s_mov_b32 m0, s67
	s_nop 0
	global_load_lds_dwordx4 v[232:233], off
	s_waitcnt vmcnt(8)
	s_waitcnt lgkmcnt(0)
	s_barrier
	s_setprio 1
	s_waitcnt lgkmcnt(0)
	v_mfma_f32_16x16x32_bf16 v[62:65], v[146:149], v[182:185], v[62:65]
	v_mfma_f32_16x16x32_bf16 v[58:61], v[154:157], v[182:185], v[58:61]
	v_mfma_f32_16x16x32_bf16 v[46:49], v[146:149], v[190:193], v[46:49]
	v_mfma_f32_16x16x32_bf16 v[42:45], v[154:157], v[190:193], v[42:45]
	v_mfma_f32_16x16x32_bf16 v[30:33], v[146:149], v[198:201], v[30:33]
	v_mfma_f32_16x16x32_bf16 v[26:29], v[154:157], v[198:201], v[26:29]
	v_mfma_f32_16x16x32_bf16 v[14:17], v[146:149], v[210:213], v[14:17]
	v_mfma_f32_16x16x32_bf16 v[10:13], v[154:157], v[210:213], v[10:13]
	v_mfma_f32_16x16x32_bf16 v[62:65], v[150:153], v[186:189], v[62:65]
	v_mfma_f32_16x16x32_bf16 v[58:61], v[162:165], v[186:189], v[58:61]
	v_mfma_f32_16x16x32_bf16 v[46:49], v[150:153], v[194:197], v[46:49]
	v_mfma_f32_16x16x32_bf16 v[42:45], v[162:165], v[194:197], v[42:45]
	v_mfma_f32_16x16x32_bf16 v[30:33], v[150:153], v[206:209], v[30:33]
	v_mfma_f32_16x16x32_bf16 v[26:29], v[162:165], v[206:209], v[26:29]
	v_mfma_f32_16x16x32_bf16 v[14:17], v[150:153], v[228:231], v[14:17]
	v_mfma_f32_16x16x32_bf16 v[10:13], v[162:165], v[228:231], v[10:13]
	s_setprio 0
	s_setprio 1
	v_mfma_f32_16x16x32_bf16 v[54:57], v[166:169], v[182:185], v[54:57]
	v_mfma_f32_16x16x32_bf16 v[50:53], v[174:177], v[182:185], v[50:53]
	v_mfma_f32_16x16x32_bf16 v[38:41], v[166:169], v[190:193], v[38:41]
	v_mfma_f32_16x16x32_bf16 v[34:37], v[174:177], v[190:193], v[34:37]
	v_mfma_f32_16x16x32_bf16 v[22:25], v[166:169], v[198:201], v[22:25]
	v_mfma_f32_16x16x32_bf16 v[18:21], v[174:177], v[198:201], v[18:21]
	v_mfma_f32_16x16x32_bf16 v[6:9], v[166:169], v[210:213], v[6:9]
	v_mfma_f32_16x16x32_bf16 v[2:5], v[174:177], v[210:213], v[2:5]
	v_mfma_f32_16x16x32_bf16 v[54:57], v[170:173], v[186:189], v[54:57]
	v_mfma_f32_16x16x32_bf16 v[50:53], v[178:181], v[186:189], v[50:53]
	v_mfma_f32_16x16x32_bf16 v[38:41], v[170:173], v[194:197], v[38:41]
	v_mfma_f32_16x16x32_bf16 v[34:37], v[178:181], v[194:197], v[34:37]
	v_mfma_f32_16x16x32_bf16 v[22:25], v[170:173], v[206:209], v[22:25]
	v_mfma_f32_16x16x32_bf16 v[18:21], v[178:181], v[206:209], v[18:21]
	v_mfma_f32_16x16x32_bf16 v[6:9], v[170:173], v[228:231], v[6:9]
	v_mfma_f32_16x16x32_bf16 v[2:5], v[178:181], v[228:231], v[2:5]
	s_setprio 0
	s_add_i32 s81, s81, 2
	s_add_u32 s42, s42, 0x100
	s_addc_u32 s43, s43, 0
	s_add_u32 s77, s77, 0x100
	s_addc_u32 s80, s80, 0
	s_cmp_gt_u32 s81, 29
	s_barrier
	s_cbranch_scc0 .LBB0_318
	s_and_b64 vcc, exec, s[48:49]
	s_cbranch_vccz .LBB0_321
	s_barrier

; #define PG8_STAGE2(bufoff, gbase, voff) do { _Pragma("unroll") for (int _i = 0; _i < 2; ++_i) \
;         __builtin_amdgcn_global_load_lds((const unsigned*)((const char*)(gbase) + (voff)[_i]), (LAS unsigned*)(lds + (bufoff) + ldsw + _i * 8192), 16, 0, 0); } while (0)
; #define PG8_LDA(dst, b, h) do { _Pragma("unroll") for (int m = 0; m < 4; ++m) _Pragma("unroll") for (int k = 0; k < 2; ++k) dst[m][k] = *(const LAS bf16x8*)(lds + PG8_SA(b, h) + aoff + m * 2048 + k * 1024); } while (0)
; #define PG8_LDB(dst, b, h) do { _Pragma("unroll") for (int n = 0; n < 2; ++n) _Pragma("unroll") for (int k = 0; k < 2; ++k) dst[n][k] = *(const LAS bf16x8*)(lds + PG8_SB(b, h) + boff + n * 2048 + k * 1024); } while (0)
; #define PG8_MMA(ai, bj, At, Bt) do { __builtin_amdgcn_s_setprio(1); _Pragma("unroll") for (int m = 0; m < 4; ++m) _Pragma("unroll") for (int n = 0; n < 2; ++n) _Pragma("unroll") for (int k = 0; k < 2; ++k) \
;         acc[ai][bj][m][n] = __builtin_amdgcn_mfma_f32_16x16x32_bf16(Bt[n][k], At[m][k], acc[ai][bj][m][n], 0, 0, 0); __builtin_amdgcn_s_setprio(0); } while (0)
; #define PG8_WAIT_V(n) asm volatile("s_waitcnt vmcnt(" #n ")" ::: "memory")
; #define PG8_WAIT_L(n) asm volatile("s_waitcnt lgkmcnt(" #n ")" ::: "memory")
; #define PG8_BAR __builtin_amdgcn_s_barrier()
; #define PG8_SCHED __builtin_amdgcn_sched_barrier(0)
; template <class Epi>
; __device__ __forceinline__ void gemm_phase(LAS unsigned char* lds, const Sched& S, const Epi& E) {
;     ...
;         for (int t = 0; t < nt; t += 2) {
;             const bool last = (t == nt - 2);
;             const char* a1 = cA + (size_t)(t + 1) * kstep;
;             const char* a2 = last ? nA : cA + (size_t)(t + 2) * kstep; const char* b2 = last ? nB : cB + (size_t)(t + 2) * kstep;
;             const char* a3 = a2 + kstep; const char* b3 = b2 + kstep;
;             PG8_LDB(B0, 0, 0); PG8_LDB(B1, 0, 1); PG8_SCHED; PG8_LDA(At, 0, 0); PG8_STAGE2(PG8_SA(1, 1), a1 + hstep, voffA);
;             PG8_WAIT_V(8); PG8_WAIT_L(0); PG8_BAR; PG8_MMA(0, 0, At, B0); PG8_MMA(0, 1, At, B1); PG8_BAR; PG8_SCHED;
;             PG8_LDA(At, 0, 1); PG8_STAGE2(PG8_SB(0, 0), b2, voffB); PG8_STAGE2(PG8_SB(0, 1), b2 + hstep, voffB); PG8_STAGE2(PG8_SA(0, 0), a2, voffA);
.LBB0_619:
	s_add_u32 s8, s28, 0xfffc0080
	s_addc_u32 s9, s29, -1
	s_add_i32 s10, 0, 0x10000
	s_cmp_eq_u32 s43, 12
	s_cselect_b32 s41, s59, s9
	s_cselect_b32 s40, s58, s8
	v_add_u32_e32 v1, s10, v159
	s_cselect_b32 s35, s61, s42
	s_cselect_b32 s34, s60, s7
	s_add_i32 s11, 0, 0x14000
	ds_read_b128 v[132:135], v1
	ds_read_b128 v[136:139], v1 offset:1024
	ds_read_b128 v[152:155], v1 offset:2048
	ds_read_b128 v[162:165], v1 offset:3072
	v_add_u32_e32 v1, s11, v159
	ds_read_b128 v[166:169], v1
	ds_read_b128 v[170:173], v1 offset:1024
	ds_read_b128 v[174:177], v1 offset:2048
	ds_read_b128 v[178:181], v1 offset:3072
	v_lshl_add_u64 v[2:3], s[28:29], 0, v[148:149]
	s_add_i32 m0, s68, 0xc000
	ds_read_b128 v[182:185], v161
	ds_read_b128 v[186:189], v161 offset:1024
	ds_read_b128 v[190:193], v161 offset:2048
	ds_read_b128 v[194:197], v161 offset:3072
	ds_read_b128 v[198:201], v161 offset:4096
	ds_read_b128 v[206:209], v161 offset:5120
	ds_read_b128 v[210:213], v161 offset:6144
	ds_read_b128 v[228:231], v161 offset:7168
	global_load_lds_dwordx4 v[2:3], off
	v_lshl_add_u64 v[2:3], s[28:29], 0, v[150:151]
	s_add_i32 m0, s68, 0xe000
	s_nop 0
	global_load_lds_dwordx4 v[2:3], off
	s_waitcnt vmcnt(8)
	s_waitcnt lgkmcnt(0)
	s_barrier
	s_setprio 1
	s_waitcnt lgkmcnt(0)
	v_mfma_f32_16x16x32_bf16 v[128:131], v[132:135], v[182:185], v[128:131]
	v_mfma_f32_16x16x32_bf16 v[124:127], v[152:155], v[182:185], v[124:127]
	v_mfma_f32_16x16x32_bf16 v[120:123], v[132:135], v[190:193], v[120:123]
	v_mfma_f32_16x16x32_bf16 v[116:119], v[152:155], v[190:193], v[116:119]
	v_mfma_f32_16x16x32_bf16 v[112:115], v[132:135], v[198:201], v[112:115]
	v_mfma_f32_16x16x32_bf16 v[108:111], v[152:155], v[198:201], v[108:111]
	v_mfma_f32_16x16x32_bf16 v[104:107], v[132:135], v[210:213], v[104:107]
	v_mfma_f32_16x16x32_bf16 v[100:103], v[152:155], v[210:213], v[100:103]
	v_mfma_f32_16x16x32_bf16 v[128:131], v[136:139], v[186:189], v[128:131]
	v_mfma_f32_16x16x32_bf16 v[124:127], v[162:165], v[186:189], v[124:127]
	v_mfma_f32_16x16x32_bf16 v[120:123], v[136:139], v[194:197], v[120:123]
	v_mfma_f32_16x16x32_bf16 v[116:119], v[162:165], v[194:197], v[116:119]
	v_mfma_f32_16x16x32_bf16 v[112:115], v[136:139], v[206:209], v[112:115]
	v_mfma_f32_16x16x32_bf16 v[108:111], v[162:165], v[206:209], v[108:111]
	v_mfma_f32_16x16x32_bf16 v[104:107], v[136:139], v[228:231], v[104:107]
	v_mfma_f32_16x16x32_bf16 v[100:103], v[162:165], v[228:231], v[100:103]
	s_setprio 0
	s_setprio 1
	v_mfma_f32_16x16x32_bf16 v[96:99], v[166:169], v[182:185], v[96:99]
	v_mfma_f32_16x16x32_bf16 v[92:95], v[174:177], v[182:185], v[92:95]
	v_mfma_f32_16x16x32_bf16 v[88:91], v[166:169], v[190:193], v[88:91]
	v_mfma_f32_16x16x32_bf16 v[84:87], v[174:177], v[190:193], v[84:87]
	v_mfma_f32_16x16x32_bf16 v[80:83], v[166:169], v[198:201], v[80:83]
	v_mfma_f32_16x16x32_bf16 v[76:79], v[174:177], v[198:201], v[76:79]
	v_mfma_f32_16x16x32_bf16 v[72:75], v[166:169], v[210:213], v[72:75]
	v_mfma_f32_16x16x32_bf16 v[68:71], v[174:177], v[210:213], v[68:71]
	v_mfma_f32_16x16x32_bf16 v[96:99], v[170:173], v[186:189], v[96:99]
	v_mfma_f32_16x16x32_bf16 v[92:95], v[178:181], v[186:189], v[92:95]
	v_mfma_f32_16x16x32_bf16 v[88:91], v[170:173], v[194:197], v[88:91]
	v_mfma_f32_16x16x32_bf16 v[84:87], v[178:181], v[194:197], v[84:87]
	v_mfma_f32_16x16x32_bf16 v[80:83], v[170:173], v[206:209], v[80:83]
	v_mfma_f32_16x16x32_bf16 v[76:79], v[178:181], v[206:209], v[76:79]
	v_mfma_f32_16x16x32_bf16 v[72:75], v[170:173], v[228:231], v[72:75]
	v_mfma_f32_16x16x32_bf16 v[68:71], v[178:181], v[228:231], v[68:71]
	s_setprio 0
	s_barrier
	s_add_i32 s8, s10, s67
	v_lshl_add_u64 v[156:157], s[34:35], 0, v[144:145]
	s_mov_b32 m0, s8
	ds_read_b128 v[182:185], v161 offset:16384
	ds_read_b128 v[186:189], v161 offset:17408
	ds_read_b128 v[190:193], v161 offset:18432
	ds_read_b128 v[194:197], v161 offset:19456
	ds_read_b128 v[198:201], v161 offset:20480
	ds_read_b128 v[206:209], v161 offset:21504
	ds_read_b128 v[210:213], v161 offset:22528
	ds_read_b128 v[228:231], v161 offset:23552
	global_load_lds_dwordx4 v[156:157], off
	s_add_i32 m0, s8, 0x2000
	s_add_u32 s8, s34, 0x40000
	v_lshl_add_u64 v[232:233], s[34:35], 0, v[140:141]
	s_addc_u32 s9, s35, 0
	s_add_i32 s10, s11, s67
	global_load_lds_dwordx4 v[232:233], off
	v_lshl_add_u64 v[2:3], s[8:9], 0, v[144:145]
	s_mov_b32 m0, s10
	v_lshl_add_u64 v[234:235], s[40:41], 0, v[146:147]
	global_load_lds_dwordx4 v[2:3], off
	v_lshl_add_u64 v[2:3], s[8:9], 0, v[140:141]
	s_add_i32 m0, s10, 0x2000
	v_lshl_add_u64 v[236:237], s[40:41], 0, v[142:143]
	global_load_lds_dwordx4 v[2:3], off
	s_mov_b32 m0, s68
	s_nop 0
	global_load_lds_dwordx4 v[234:235], off
	s_mov_b32 m0, s69
	s_nop 0
	global_load_lds_dwordx4 v[236:237], off
	s_waitcnt vmcnt(8)
	s_waitcnt lgkmcnt(0)
	s_barrier
; #define PG8_STAGE2(bufoff, gbase, voff) do { _Pragma("unroll") for (int _i = 0; _i < 2; ++_i) \
;         __builtin_amdgcn_global_load_lds((const unsigned*)((const char*)(gbase) + (voff)[_i]), (LAS unsigned*)(lds + (bufoff) + ldsw + _i * 8192), 16, 0, 0); } while (0)
; #define PG8_LDA(dst, b, h) do { _Pragma("unroll") for (int m = 0; m < 4; ++m) _Pragma("unroll") for (int k = 0; k < 2; ++k) dst[m][k] = *(const LAS bf16x8*)(lds + PG8_SA(b, h) + aoff + m * 2048 + k * 1024); } while (0)
; #define PG8_LDB(dst, b, h) do { _Pragma("unroll") for (int n = 0; n < 2; ++n) _Pragma("unroll") for (int k = 0; k < 2; ++k) dst[n][k] = *(const LAS bf16x8*)(lds + PG8_SB(b, h) + boff + n * 2048 + k * 1024); } while (0)
; #define PG8_MMA(ai, bj, At, Bt) do { __builtin_amdgcn_s_setprio(1); _Pragma("unroll") for (int m = 0; m < 4; ++m) _Pragma("unroll") for (int n = 0; n < 2; ++n) _Pragma("unroll") for (int k = 0; k < 2; ++k) \
;         acc[ai][bj][m][n] = __builtin_amdgcn_mfma_f32_16x16x32_bf16(Bt[n][k], At[m][k], acc[ai][bj][m][n], 0, 0, 0); __builtin_amdgcn_s_setprio(0); } while (0)
; #define PG8_WAIT_V(n) asm volatile("s_waitcnt vmcnt(" #n ")" ::: "memory")
; #define PG8_WAIT_L(n) asm volatile("s_waitcnt lgkmcnt(" #n ")" ::: "memory")
; #define PG8_BAR __builtin_amdgcn_s_barrier()
; #define PG8_SCHED __builtin_amdgcn_sched_barrier(0)
; template <class Epi>
; __device__ __forceinline__ void gemm_phase(LAS unsigned char* lds, const Sched& S, const Epi& E) {
;     ...
;             PG8_WAIT_V(8); PG8_WAIT_L(0); PG8_BAR; PG8_MMA(1, 0, At, B0); PG8_MMA(1, 1, At, B1); PG8_BAR; PG8_SCHED;
;             PG8_LDB(B0, 1, 0); PG8_LDB(B1, 1, 1); PG8_SCHED; PG8_LDA(At, 1, 0); PG8_STAGE2(PG8_SA(0, 1), a2 + hstep, voffA);
;             PG8_WAIT_V(8); PG8_WAIT_L(0); PG8_BAR; PG8_MMA(0, 0, At, B0); PG8_MMA(0, 1, At, B1); PG8_BAR; PG8_SCHED;
	s_setprio 1
	s_waitcnt lgkmcnt(0)
	v_mfma_f32_16x16x32_bf16 v[64:67], v[132:135], v[182:185], v[64:67]
	v_mfma_f32_16x16x32_bf16 v[60:63], v[152:155], v[182:185], v[60:63]
	v_mfma_f32_16x16x32_bf16 v[56:59], v[132:135], v[190:193], v[56:59]
	v_mfma_f32_16x16x32_bf16 v[52:55], v[152:155], v[190:193], v[52:55]
	v_mfma_f32_16x16x32_bf16 v[48:51], v[132:135], v[198:201], v[48:51]
	v_mfma_f32_16x16x32_bf16 v[44:47], v[152:155], v[198:201], v[44:47]
	v_mfma_f32_16x16x32_bf16 v[40:43], v[132:135], v[210:213], v[40:43]
	v_mfma_f32_16x16x32_bf16 v[36:39], v[152:155], v[210:213], v[36:39]
	v_mfma_f32_16x16x32_bf16 v[64:67], v[136:139], v[186:189], v[64:67]
	v_mfma_f32_16x16x32_bf16 v[60:63], v[162:165], v[186:189], v[60:63]
	v_mfma_f32_16x16x32_bf16 v[56:59], v[136:139], v[194:197], v[56:59]
	v_mfma_f32_16x16x32_bf16 v[52:55], v[162:165], v[194:197], v[52:55]
	v_mfma_f32_16x16x32_bf16 v[48:51], v[136:139], v[206:209], v[48:51]
	v_mfma_f32_16x16x32_bf16 v[44:47], v[162:165], v[206:209], v[44:47]
	v_mfma_f32_16x16x32_bf16 v[40:43], v[136:139], v[228:231], v[40:43]
	v_mfma_f32_16x16x32_bf16 v[36:39], v[162:165], v[228:231], v[36:39]
	s_setprio 0
	s_setprio 1
	v_mfma_f32_16x16x32_bf16 v[32:35], v[166:169], v[182:185], v[32:35]
	v_mfma_f32_16x16x32_bf16 v[28:31], v[174:177], v[182:185], v[28:31]
	v_mfma_f32_16x16x32_bf16 v[24:27], v[166:169], v[190:193], v[24:27]
	v_mfma_f32_16x16x32_bf16 v[20:23], v[174:177], v[190:193], v[20:23]
	v_mfma_f32_16x16x32_bf16 v[16:19], v[166:169], v[198:201], v[16:19]
	v_mfma_f32_16x16x32_bf16 v[12:15], v[174:177], v[198:201], v[12:15]
	v_mfma_f32_16x16x32_bf16 v[8:11], v[166:169], v[210:213], v[8:11]
	v_mfma_f32_16x16x32_bf16 v[2:5], v[174:177], v[210:213], v[4:7]
	v_mfma_f32_16x16x32_bf16 v[32:35], v[170:173], v[186:189], v[32:35]
	v_mfma_f32_16x16x32_bf16 v[28:31], v[178:181], v[186:189], v[28:31]
	v_mfma_f32_16x16x32_bf16 v[24:27], v[170:173], v[194:197], v[24:27]
	v_mfma_f32_16x16x32_bf16 v[20:23], v[178:181], v[194:197], v[20:23]
	v_mfma_f32_16x16x32_bf16 v[16:19], v[170:173], v[206:209], v[16:19]
	v_mfma_f32_16x16x32_bf16 v[12:15], v[178:181], v[206:209], v[12:15]
	v_mfma_f32_16x16x32_bf16 v[8:11], v[170:173], v[228:231], v[8:11]
	v_mfma_f32_16x16x32_bf16 v[2:5], v[178:181], v[228:231], v[2:5]
	s_setprio 0
	s_barrier
	s_add_i32 s10, 0, 0x18000
	v_add_u32_e32 v1, s10, v159
	s_add_i32 s11, 0, 0x1c000
	ds_read_b128 v[132:135], v1
	ds_read_b128 v[136:139], v1 offset:1024
	ds_read_b128 v[152:155], v1 offset:2048
	ds_read_b128 v[162:165], v1 offset:3072
	v_add_u32_e32 v1, s11, v159
	ds_read_b128 v[166:169], v1
	ds_read_b128 v[170:173], v1 offset:1024
	ds_read_b128 v[174:177], v1 offset:2048
	ds_read_b128 v[178:181], v1 offset:3072
	s_add_u32 s8, s40, 0x40000
	s_addc_u32 s9, s41, 0
	s_mov_b32 m0, s70
	v_lshl_add_u64 v[6:7], s[8:9], 0, v[146:147]
	ds_read_b128 v[182:185], v161 offset:32768
	ds_read_b128 v[186:189], v161 offset:33792
	ds_read_b128 v[190:193], v161 offset:34816
	ds_read_b128 v[194:197], v161 offset:35840
	ds_read_b128 v[198:201], v161 offset:36864
	ds_read_b128 v[206:209], v161 offset:37888
	ds_read_b128 v[210:213], v161 offset:38912
	ds_read_b128 v[228:231], v161 offset:39936
	global_load_lds_dwordx4 v[6:7], off
	v_lshl_add_u64 v[6:7], s[8:9], 0, v[142:143]
	s_mov_b32 m0, s71
	s_nop 0
	global_load_lds_dwordx4 v[6:7], off
	s_waitcnt vmcnt(8)
	s_waitcnt lgkmcnt(0)
	s_barrier
	s_setprio 1
	s_waitcnt lgkmcnt(0)
	v_mfma_f32_16x16x32_bf16 v[128:131], v[132:135], v[182:185], v[128:131]
	v_mfma_f32_16x16x32_bf16 v[124:127], v[152:155], v[182:185], v[124:127]
	v_mfma_f32_16x16x32_bf16 v[120:123], v[132:135], v[190:193], v[120:123]
	v_mfma_f32_16x16x32_bf16 v[116:119], v[152:155], v[190:193], v[116:119]
	v_mfma_f32_16x16x32_bf16 v[112:115], v[132:135], v[198:201], v[112:115]
	v_mfma_f32_16x16x32_bf16 v[108:111], v[152:155], v[198:201], v[108:111]
	v_mfma_f32_16x16x32_bf16 v[104:107], v[132:135], v[210:213], v[104:107]
	v_mfma_f32_16x16x32_bf16 v[100:103], v[152:155], v[210:213], v[100:103]
	v_mfma_f32_16x16x32_bf16 v[128:131], v[136:139], v[186:189], v[128:131]
	v_mfma_f32_16x16x32_bf16 v[124:127], v[162:165], v[186:189], v[124:127]
	v_mfma_f32_16x16x32_bf16 v[120:123], v[136:139], v[194:197], v[120:123]
	v_mfma_f32_16x16x32_bf16 v[116:119], v[162:165], v[194:197], v[116:119]
	v_mfma_f32_16x16x32_bf16 v[112:115], v[136:139], v[206:209], v[112:115]
	v_mfma_f32_16x16x32_bf16 v[108:111], v[162:165], v[206:209], v[108:111]
	v_mfma_f32_16x16x32_bf16 v[104:107], v[136:139], v[228:231], v[104:107]
	v_mfma_f32_16x16x32_bf16 v[100:103], v[162:165], v[228:231], v[100:103]
	s_setprio 0
	s_setprio 1
	v_mfma_f32_16x16x32_bf16 v[96:99], v[166:169], v[182:185], v[96:99]
	v_mfma_f32_16x16x32_bf16 v[92:95], v[174:177], v[182:185], v[92:95]
	v_mfma_f32_16x16x32_bf16 v[88:91], v[166:169], v[190:193], v[88:91]
	v_mfma_f32_16x16x32_bf16 v[84:87], v[174:177], v[190:193], v[84:87]
	v_mfma_f32_16x16x32_bf16 v[80:83], v[166:169], v[198:201], v[80:83]
	v_mfma_f32_16x16x32_bf16 v[76:79], v[174:177], v[198:201], v[76:79]
	v_mfma_f32_16x16x32_bf16 v[72:75], v[166:169], v[210:213], v[72:75]
	v_mfma_f32_16x16x32_bf16 v[68:71], v[174:177], v[210:213], v[68:71]
	v_mfma_f32_16x16x32_bf16 v[96:99], v[170:173], v[186:189], v[96:99]
	v_mfma_f32_16x16x32_bf16 v[92:95], v[178:181], v[186:189], v[92:95]
	v_mfma_f32_16x16x32_bf16 v[88:91], v[170:173], v[194:197], v[88:91]
	v_mfma_f32_16x16x32_bf16 v[84:87], v[178:181], v[194:197], v[84:87]
	v_mfma_f32_16x16x32_bf16 v[80:83], v[170:173], v[206:209], v[80:83]
	v_mfma_f32_16x16x32_bf16 v[76:79], v[178:181], v[206:209], v[76:79]
	v_mfma_f32_16x16x32_bf16 v[72:75], v[170:173], v[228:231], v[72:75]
	v_mfma_f32_16x16x32_bf16 v[68:71], v[178:181], v[228:231], v[68:71]
	s_setprio 0
	s_barrier
; #define PG8_STAGE2(bufoff, gbase, voff) do { _Pragma("unroll") for (int _i = 0; _i < 2; ++_i) \
;         __builtin_amdgcn_global_load_lds((const unsigned*)((const char*)(gbase) + (voff)[_i]), (LAS unsigned*)(lds + (bufoff) + ldsw + _i * 8192), 16, 0, 0); } while (0)
; #define PG8_LDA(dst, b, h) do { _Pragma("unroll") for (int m = 0; m < 4; ++m) _Pragma("unroll") for (int k = 0; k < 2; ++k) dst[m][k] = *(const LAS bf16x8*)(lds + PG8_SA(b, h) + aoff + m * 2048 + k * 1024); } while (0)
; #define PG8_MMA(ai, bj, At, Bt) do { __builtin_amdgcn_s_setprio(1); _Pragma("unroll") for (int m = 0; m < 4; ++m) _Pragma("unroll") for (int n = 0; n < 2; ++n) _Pragma("unroll") for (int k = 0; k < 2; ++k) \
;         acc[ai][bj][m][n] = __builtin_amdgcn_mfma_f32_16x16x32_bf16(Bt[n][k], At[m][k], acc[ai][bj][m][n], 0, 0, 0); __builtin_amdgcn_s_setprio(0); } while (0)
; #define PG8_WAIT_V(n) asm volatile("s_waitcnt vmcnt(" #n ")" ::: "memory")
; #define PG8_WAIT_L(n) asm volatile("s_waitcnt lgkmcnt(" #n ")" ::: "memory")
; #define PG8_BAR __builtin_amdgcn_s_barrier()
; #define PG8_SCHED __builtin_amdgcn_sched_barrier(0)
; template <class Epi>
; __device__ __forceinline__ void gemm_phase(LAS unsigned char* lds, const Sched& S, const Epi& E) {
;     ...
;             PG8_LDA(At, 1, 1); PG8_STAGE2(PG8_SB(1, 0), b3, voffB); PG8_STAGE2(PG8_SB(1, 1), b3 + hstep, voffB); PG8_STAGE2(PG8_SA(1, 0), a3, voffA);
;             PG8_WAIT_V(8); PG8_WAIT_L(0); PG8_BAR; PG8_MMA(1, 0, At, B0); PG8_MMA(1, 1, At, B1); PG8_BAR; PG8_SCHED;
;         }
;         if (wr == 0) PG8_BAR;
	s_add_i32 s8, s10, s67
	v_lshl_add_u64 v[6:7], v[156:157], 0, s[22:23]
	s_mov_b32 m0, s8
	ds_read_b128 v[182:185], v161 offset:49152
	ds_read_b128 v[186:189], v161 offset:50176
	ds_read_b128 v[190:193], v161 offset:51200
	ds_read_b128 v[194:197], v161 offset:52224
	ds_read_b128 v[198:201], v161 offset:53248
	ds_read_b128 v[206:209], v161 offset:54272
	ds_read_b128 v[210:213], v161 offset:55296
	ds_read_b128 v[228:231], v161 offset:56320
	global_load_lds_dwordx4 v[6:7], off
	s_add_i32 m0, s8, 0x2000
	s_add_u32 s8, s34, 0x40080
	v_lshl_add_u64 v[6:7], v[232:233], 0, s[22:23]
	s_addc_u32 s9, s35, 0
	s_add_i32 s10, s11, s67
	global_load_lds_dwordx4 v[6:7], off
	v_lshl_add_u64 v[6:7], s[8:9], 0, v[144:145]
	s_mov_b32 m0, s10
	s_nop 0
	global_load_lds_dwordx4 v[6:7], off
	v_lshl_add_u64 v[6:7], s[8:9], 0, v[140:141]
	s_add_i32 m0, s10, 0x2000
	s_nop 0
	global_load_lds_dwordx4 v[6:7], off
	v_lshl_add_u64 v[6:7], v[234:235], 0, s[22:23]
	s_mov_b32 m0, s72
	s_nop 0
	global_load_lds_dwordx4 v[6:7], off
	v_lshl_add_u64 v[6:7], v[236:237], 0, s[22:23]
	s_mov_b32 m0, s73
	s_nop 0
	global_load_lds_dwordx4 v[6:7], off
	s_waitcnt vmcnt(8)
	s_waitcnt lgkmcnt(0)
	s_barrier
	s_setprio 1
	s_waitcnt lgkmcnt(0)
	v_mfma_f32_16x16x32_bf16 v[64:67], v[132:135], v[182:185], v[64:67]
	v_mfma_f32_16x16x32_bf16 v[60:63], v[152:155], v[182:185], v[60:63]
	v_mfma_f32_16x16x32_bf16 v[56:59], v[132:135], v[190:193], v[56:59]
	v_mfma_f32_16x16x32_bf16 v[52:55], v[152:155], v[190:193], v[52:55]
	v_mfma_f32_16x16x32_bf16 v[48:51], v[132:135], v[198:201], v[48:51]
	v_mfma_f32_16x16x32_bf16 v[44:47], v[152:155], v[198:201], v[44:47]
	v_mfma_f32_16x16x32_bf16 v[40:43], v[132:135], v[210:213], v[40:43]
	v_mfma_f32_16x16x32_bf16 v[36:39], v[152:155], v[210:213], v[36:39]
	v_mfma_f32_16x16x32_bf16 v[64:67], v[136:139], v[186:189], v[64:67]
	v_mfma_f32_16x16x32_bf16 v[60:63], v[162:165], v[186:189], v[60:63]
	v_mfma_f32_16x16x32_bf16 v[56:59], v[136:139], v[194:197], v[56:59]
	v_mfma_f32_16x16x32_bf16 v[52:55], v[162:165], v[194:197], v[52:55]
	v_mfma_f32_16x16x32_bf16 v[48:51], v[136:139], v[206:209], v[48:51]
	v_mfma_f32_16x16x32_bf16 v[44:47], v[162:165], v[206:209], v[44:47]
	v_mfma_f32_16x16x32_bf16 v[40:43], v[136:139], v[228:231], v[40:43]
	v_mfma_f32_16x16x32_bf16 v[36:39], v[162:165], v[228:231], v[36:39]
	s_setprio 0
	s_setprio 1
	v_mfma_f32_16x16x32_bf16 v[32:35], v[166:169], v[182:185], v[32:35]
	v_mfma_f32_16x16x32_bf16 v[28:31], v[174:177], v[182:185], v[28:31]
	v_mfma_f32_16x16x32_bf16 v[24:27], v[166:169], v[190:193], v[24:27]
	v_mfma_f32_16x16x32_bf16 v[20:23], v[174:177], v[190:193], v[20:23]
	v_mfma_f32_16x16x32_bf16 v[16:19], v[166:169], v[198:201], v[16:19]
	v_mfma_f32_16x16x32_bf16 v[12:15], v[174:177], v[198:201], v[12:15]
	v_mfma_f32_16x16x32_bf16 v[6:9], v[166:169], v[210:213], v[8:11]
	v_mfma_f32_16x16x32_bf16 v[2:5], v[174:177], v[210:213], v[2:5]
	v_mfma_f32_16x16x32_bf16 v[32:35], v[170:173], v[186:189], v[32:35]
	v_mfma_f32_16x16x32_bf16 v[28:31], v[178:181], v[186:189], v[28:31]
	v_mfma_f32_16x16x32_bf16 v[24:27], v[170:173], v[194:197], v[24:27]
	v_mfma_f32_16x16x32_bf16 v[20:23], v[178:181], v[194:197], v[20:23]
	v_mfma_f32_16x16x32_bf16 v[16:19], v[170:173], v[206:209], v[16:19]
	v_mfma_f32_16x16x32_bf16 v[12:15], v[178:181], v[206:209], v[12:15]
	v_mfma_f32_16x16x32_bf16 v[8:11], v[170:173], v[228:231], v[6:9]
	v_mfma_f32_16x16x32_bf16 v[4:7], v[178:181], v[228:231], v[2:5]
	s_setprio 0
	s_add_i32 s43, s43, 2
	s_add_u32 s28, s28, 0x100
	s_addc_u32 s29, s29, 0
	s_add_u32 s7, s7, 0x100
	s_addc_u32 s42, s42, 0
	s_cmp_gt_u32 s43, 13
	s_barrier
	s_cbranch_scc0 .LBB0_619
	s_and_b64 vcc, exec, s[50:51]
	s_cbranch_vccz .LBB0_622
	s_barrier

; #define PG8_STAGE2(bufoff, gbase, voff) do { _Pragma("unroll") for (int _i = 0; _i < 2; ++_i) \
;         __builtin_amdgcn_global_load_lds((const unsigned*)((const char*)(gbase) + (voff)[_i]), (LAS unsigned*)(lds + (bufoff) + ldsw + _i * 8192), 16, 0, 0); } while (0)
; #define PG8_LDA(dst, b, h) do { _Pragma("unroll") for (int m = 0; m < 4; ++m) _Pragma("unroll") for (int k = 0; k < 2; ++k) dst[m][k] = *(const LAS bf16x8*)(lds + PG8_SA(b, h) + aoff + m * 2048 + k * 1024); } while (0)
; #define PG8_LDB(dst, b, h) do { _Pragma("unroll") for (int n = 0; n < 2; ++n) _Pragma("unroll") for (int k = 0; k < 2; ++k) dst[n][k] = *(const LAS bf16x8*)(lds + PG8_SB(b, h) + boff + n * 2048 + k * 1024); } while (0)
; #define PG8_MMA(ai, bj, At, Bt) do { __builtin_amdgcn_s_setprio(1); _Pragma("unroll") for (int m = 0; m < 4; ++m) _Pragma("unroll") for (int n = 0; n < 2; ++n) _Pragma("unroll") for (int k = 0; k < 2; ++k) \
;         acc[ai][bj][m][n] = __builtin_amdgcn_mfma_f32_16x16x32_bf16(Bt[n][k], At[m][k], acc[ai][bj][m][n], 0, 0, 0); __builtin_amdgcn_s_setprio(0); } while (0)
; #define PG8_WAIT_V(n) asm volatile("s_waitcnt vmcnt(" #n ")" ::: "memory")
; #define PG8_WAIT_L(n) asm volatile("s_waitcnt lgkmcnt(" #n ")" ::: "memory")
; #define PG8_BAR __builtin_amdgcn_s_barrier()
; #define PG8_SCHED __builtin_amdgcn_sched_barrier(0)
; template <class Epi>
; __device__ __forceinline__ void gemm_phase(LAS unsigned char* lds, const Sched& S, const Epi& E) {
;     ...
;         for (int t = 0; t < nt; t += 2) {
;             const bool last = (t == nt - 2);
;             const char* a1 = cA + (size_t)(t + 1) * kstep;
;             const char* a2 = last ? nA : cA + (size_t)(t + 2) * kstep; const char* b2 = last ? nB : cB + (size_t)(t + 2) * kstep;
;             const char* a3 = a2 + kstep; const char* b3 = b2 + kstep;
;             PG8_LDB(B0, 0, 0); PG8_LDB(B1, 0, 1); PG8_SCHED; PG8_LDA(At, 0, 0); PG8_STAGE2(PG8_SA(1, 1), a1 + hstep, voffA);
;             PG8_WAIT_V(8); PG8_WAIT_L(0); PG8_BAR; PG8_MMA(0, 0, At, B0); PG8_MMA(0, 1, At, B1); PG8_BAR; PG8_SCHED;
;             PG8_LDA(At, 0, 1); PG8_STAGE2(PG8_SB(0, 0), b2, voffB); PG8_STAGE2(PG8_SB(0, 1), b2 + hstep, voffB); PG8_STAGE2(PG8_SA(0, 0), a2, voffA);
.LBB0_774:
	s_add_u32 s8, s66, s68
	s_addc_u32 s9, s67, s69
	s_add_u32 s8, s8, 0x100
	s_addc_u32 s9, s9, 0
	s_add_u32 s10, s38, s68
	s_addc_u32 s11, s39, s69
	s_add_i32 s12, 0, 0x10000
	s_cmpk_eq_i32 s68, 0xf00
	s_cselect_b32 s73, s61, s9
	s_cselect_b32 s72, s91, s8
	v_add_u32_e32 v1, s12, v146
	s_cselect_b32 s71, s59, s11
	s_cselect_b32 s70, vcc_lo, s10
	s_add_i32 s10, 0, 0x14000
	ds_read_b128 v[148:151], v1
	ds_read_b128 v[152:155], v1 offset:1024
	ds_read_b128 v[156:159], v1 offset:2048
	ds_read_b128 v[160:163], v1 offset:3072
	v_add_u32_e32 v1, s10, v146
	ds_read_b128 v[164:167], v1
	ds_read_b128 v[168:171], v1 offset:1024
	ds_read_b128 v[172:175], v1 offset:2048
	ds_read_b128 v[176:179], v1 offset:3072
	v_lshl_add_u64 v[200:201], v[2:3], 0, s[68:69]
	s_add_i32 m0, s83, 0xc000
	ds_read_b128 v[180:183], v147
	ds_read_b128 v[184:187], v147 offset:1024
	ds_read_b128 v[188:191], v147 offset:2048
	ds_read_b128 v[196:199], v147 offset:3072
	ds_read_b128 v[206:209], v147 offset:4096
	ds_read_b128 v[210:213], v147 offset:5120
	ds_read_b128 v[228:231], v147 offset:6144
	ds_read_b128 v[232:235], v147 offset:7168
	global_load_lds_dwordx4 v[200:201], off
	v_lshl_add_u64 v[200:201], v[144:145], 0, s[68:69]
	s_add_i32 m0, s83, 0xe000
	s_nop 0
	global_load_lds_dwordx4 v[200:201], off
	s_waitcnt vmcnt(8)
	s_waitcnt lgkmcnt(0)
	s_barrier
	s_setprio 1
	s_waitcnt lgkmcnt(0)
	v_mfma_f32_16x16x32_bf16 v[128:131], v[148:151], v[180:183], v[128:131]
	v_mfma_f32_16x16x32_bf16 v[124:127], v[156:159], v[180:183], v[124:127]
	v_mfma_f32_16x16x32_bf16 v[112:115], v[148:151], v[188:191], v[112:115]
	v_mfma_f32_16x16x32_bf16 v[108:111], v[156:159], v[188:191], v[108:111]
	v_mfma_f32_16x16x32_bf16 v[96:99], v[148:151], v[206:209], v[96:99]
	v_mfma_f32_16x16x32_bf16 v[92:95], v[156:159], v[206:209], v[92:95]
	v_mfma_f32_16x16x32_bf16 v[80:83], v[148:151], v[228:231], v[80:83]
	v_mfma_f32_16x16x32_bf16 v[76:79], v[156:159], v[228:231], v[76:79]
	v_mfma_f32_16x16x32_bf16 v[128:131], v[152:155], v[184:187], v[128:131]
	v_mfma_f32_16x16x32_bf16 v[124:127], v[160:163], v[184:187], v[124:127]
	v_mfma_f32_16x16x32_bf16 v[112:115], v[152:155], v[196:199], v[112:115]
	v_mfma_f32_16x16x32_bf16 v[108:111], v[160:163], v[196:199], v[108:111]
	v_mfma_f32_16x16x32_bf16 v[96:99], v[152:155], v[210:213], v[96:99]
	v_mfma_f32_16x16x32_bf16 v[92:95], v[160:163], v[210:213], v[92:95]
	v_mfma_f32_16x16x32_bf16 v[80:83], v[152:155], v[232:235], v[80:83]
	v_mfma_f32_16x16x32_bf16 v[76:79], v[160:163], v[232:235], v[76:79]
	s_setprio 0
	s_setprio 1
	v_mfma_f32_16x16x32_bf16 v[120:123], v[164:167], v[180:183], v[120:123]
	v_mfma_f32_16x16x32_bf16 v[116:119], v[172:175], v[180:183], v[116:119]
	v_mfma_f32_16x16x32_bf16 v[104:107], v[164:167], v[188:191], v[104:107]
	v_mfma_f32_16x16x32_bf16 v[100:103], v[172:175], v[188:191], v[100:103]
	v_mfma_f32_16x16x32_bf16 v[88:91], v[164:167], v[206:209], v[88:91]
	v_mfma_f32_16x16x32_bf16 v[84:87], v[172:175], v[206:209], v[84:87]
	v_mfma_f32_16x16x32_bf16 v[72:75], v[164:167], v[228:231], v[72:75]
	v_mfma_f32_16x16x32_bf16 v[68:71], v[172:175], v[228:231], v[68:71]
	v_mfma_f32_16x16x32_bf16 v[120:123], v[168:171], v[184:187], v[120:123]
	v_mfma_f32_16x16x32_bf16 v[116:119], v[176:179], v[184:187], v[116:119]
	v_mfma_f32_16x16x32_bf16 v[104:107], v[168:171], v[196:199], v[104:107]
	v_mfma_f32_16x16x32_bf16 v[100:103], v[176:179], v[196:199], v[100:103]
	v_mfma_f32_16x16x32_bf16 v[88:91], v[168:171], v[210:213], v[88:91]
	v_mfma_f32_16x16x32_bf16 v[84:87], v[176:179], v[210:213], v[84:87]
	v_mfma_f32_16x16x32_bf16 v[72:75], v[168:171], v[232:235], v[72:75]
	v_mfma_f32_16x16x32_bf16 v[68:71], v[176:179], v[232:235], v[68:71]
	s_setprio 0
	s_barrier
	s_add_i32 s8, s12, s7
	v_lshl_add_u64 v[200:201], s[70:71], 0, v[136:137]
	s_mov_b32 m0, s8
	ds_read_b128 v[180:183], v147 offset:16384
	ds_read_b128 v[184:187], v147 offset:17408
	ds_read_b128 v[188:191], v147 offset:18432
	ds_read_b128 v[196:199], v147 offset:19456
	ds_read_b128 v[206:209], v147 offset:20480
	ds_read_b128 v[210:213], v147 offset:21504
	ds_read_b128 v[228:231], v147 offset:22528
	ds_read_b128 v[232:235], v147 offset:23552
	global_load_lds_dwordx4 v[200:201], off
	s_add_i32 m0, s8, 0x2000
	s_add_u32 s8, s70, 0x80000
	v_lshl_add_u64 v[236:237], s[70:71], 0, v[132:133]
	s_addc_u32 s9, s71, 0
	s_add_i32 s10, s10, s7
	global_load_lds_dwordx4 v[236:237], off
	v_lshl_add_u64 v[238:239], s[8:9], 0, v[136:137]
	s_mov_b32 m0, s10
	v_lshl_add_u64 v[240:241], s[72:73], 0, v[134:135]
	global_load_lds_dwordx4 v[238:239], off
	v_lshl_add_u64 v[238:239], s[8:9], 0, v[132:133]
	s_add_i32 m0, s10, 0x2000
	s_nop 0
	global_load_lds_dwordx4 v[238:239], off
	v_lshl_add_u64 v[238:239], s[72:73], 0, v[138:139]
	s_mov_b32 m0, s83
	s_nop 0
	global_load_lds_dwordx4 v[238:239], off
	s_mov_b32 m0, s84
	s_nop 0
	global_load_lds_dwordx4 v[240:241], off
	s_waitcnt vmcnt(8)
	s_waitcnt lgkmcnt(0)
	s_barrier
; #define PG8_STAGE2(bufoff, gbase, voff) do { _Pragma("unroll") for (int _i = 0; _i < 2; ++_i) \
;         __builtin_amdgcn_global_load_lds((const unsigned*)((const char*)(gbase) + (voff)[_i]), (LAS unsigned*)(lds + (bufoff) + ldsw + _i * 8192), 16, 0, 0); } while (0)
; #define PG8_LDA(dst, b, h) do { _Pragma("unroll") for (int m = 0; m < 4; ++m) _Pragma("unroll") for (int k = 0; k < 2; ++k) dst[m][k] = *(const LAS bf16x8*)(lds + PG8_SA(b, h) + aoff + m * 2048 + k * 1024); } while (0)
; #define PG8_LDB(dst, b, h) do { _Pragma("unroll") for (int n = 0; n < 2; ++n) _Pragma("unroll") for (int k = 0; k < 2; ++k) dst[n][k] = *(const LAS bf16x8*)(lds + PG8_SB(b, h) + boff + n * 2048 + k * 1024); } while (0)
; #define PG8_MMA(ai, bj, At, Bt) do { __builtin_amdgcn_s_setprio(1); _Pragma("unroll") for (int m = 0; m < 4; ++m) _Pragma("unroll") for (int n = 0; n < 2; ++n) _Pragma("unroll") for (int k = 0; k < 2; ++k) \
;         acc[ai][bj][m][n] = __builtin_amdgcn_mfma_f32_16x16x32_bf16(Bt[n][k], At[m][k], acc[ai][bj][m][n], 0, 0, 0); __builtin_amdgcn_s_setprio(0); } while (0)
; #define PG8_WAIT_V(n) asm volatile("s_waitcnt vmcnt(" #n ")" ::: "memory")
; #define PG8_WAIT_L(n) asm volatile("s_waitcnt lgkmcnt(" #n ")" ::: "memory")
; #define PG8_BAR __builtin_amdgcn_s_barrier()
; #define PG8_SCHED __builtin_amdgcn_sched_barrier(0)
; template <class Epi>
; __device__ __forceinline__ void gemm_phase(LAS unsigned char* lds, const Sched& S, const Epi& E) {
;     ...
;             PG8_WAIT_V(8); PG8_WAIT_L(0); PG8_BAR; PG8_MMA(1, 0, At, B0); PG8_MMA(1, 1, At, B1); PG8_BAR; PG8_SCHED;
;             PG8_LDB(B0, 1, 0); PG8_LDB(B1, 1, 1); PG8_SCHED; PG8_LDA(At, 1, 0); PG8_STAGE2(PG8_SA(0, 1), a2 + hstep, voffA);
;             PG8_WAIT_V(8); PG8_WAIT_L(0); PG8_BAR; PG8_MMA(0, 0, At, B0); PG8_MMA(0, 1, At, B1); PG8_BAR; PG8_SCHED;
	s_setprio 1
	s_waitcnt lgkmcnt(0)
	v_mfma_f32_16x16x32_bf16 v[64:67], v[148:151], v[180:183], v[64:67]
	v_mfma_f32_16x16x32_bf16 v[60:63], v[156:159], v[180:183], v[60:63]
	v_mfma_f32_16x16x32_bf16 v[48:51], v[148:151], v[188:191], v[48:51]
	v_mfma_f32_16x16x32_bf16 v[44:47], v[156:159], v[188:191], v[44:47]
	v_mfma_f32_16x16x32_bf16 v[32:35], v[148:151], v[206:209], v[32:35]
	v_mfma_f32_16x16x32_bf16 v[28:31], v[156:159], v[206:209], v[28:31]
	v_mfma_f32_16x16x32_bf16 v[16:19], v[148:151], v[228:231], v[16:19]
	v_mfma_f32_16x16x32_bf16 v[12:15], v[156:159], v[228:231], v[12:15]
	v_mfma_f32_16x16x32_bf16 v[64:67], v[152:155], v[184:187], v[64:67]
	v_mfma_f32_16x16x32_bf16 v[60:63], v[160:163], v[184:187], v[60:63]
	v_mfma_f32_16x16x32_bf16 v[48:51], v[152:155], v[196:199], v[48:51]
	v_mfma_f32_16x16x32_bf16 v[44:47], v[160:163], v[196:199], v[44:47]
	v_mfma_f32_16x16x32_bf16 v[32:35], v[152:155], v[210:213], v[32:35]
	v_mfma_f32_16x16x32_bf16 v[28:31], v[160:163], v[210:213], v[28:31]
	v_mfma_f32_16x16x32_bf16 v[16:19], v[152:155], v[232:235], v[16:19]
	v_mfma_f32_16x16x32_bf16 v[12:15], v[160:163], v[232:235], v[12:15]
	s_setprio 0
	s_setprio 1
	v_mfma_f32_16x16x32_bf16 v[56:59], v[164:167], v[180:183], v[56:59]
	v_mfma_f32_16x16x32_bf16 v[52:55], v[172:175], v[180:183], v[52:55]
	v_mfma_f32_16x16x32_bf16 v[40:43], v[164:167], v[188:191], v[40:43]
	v_mfma_f32_16x16x32_bf16 v[36:39], v[172:175], v[188:191], v[36:39]
	v_mfma_f32_16x16x32_bf16 v[24:27], v[164:167], v[206:209], v[24:27]
	v_mfma_f32_16x16x32_bf16 v[20:23], v[172:175], v[206:209], v[20:23]
	v_mfma_f32_16x16x32_bf16 v[8:11], v[164:167], v[228:231], v[8:11]
	v_mfma_f32_16x16x32_bf16 v[4:7], v[172:175], v[228:231], v[4:7]
	v_mfma_f32_16x16x32_bf16 v[56:59], v[168:171], v[184:187], v[56:59]
	v_mfma_f32_16x16x32_bf16 v[52:55], v[176:179], v[184:187], v[52:55]
	v_mfma_f32_16x16x32_bf16 v[40:43], v[168:171], v[196:199], v[40:43]
	v_mfma_f32_16x16x32_bf16 v[36:39], v[176:179], v[196:199], v[36:39]
	v_mfma_f32_16x16x32_bf16 v[24:27], v[168:171], v[210:213], v[24:27]
	v_mfma_f32_16x16x32_bf16 v[20:23], v[176:179], v[210:213], v[20:23]
	v_mfma_f32_16x16x32_bf16 v[8:11], v[168:171], v[232:235], v[8:11]
	v_mfma_f32_16x16x32_bf16 v[4:7], v[176:179], v[232:235], v[4:7]
	s_setprio 0
	s_barrier
	s_add_i32 s10, 0, 0x18000
	v_add_u32_e32 v1, s10, v146
	s_add_i32 s11, 0, 0x1c000
	ds_read_b128 v[148:151], v1
	ds_read_b128 v[152:155], v1 offset:1024
	ds_read_b128 v[156:159], v1 offset:2048
	ds_read_b128 v[160:163], v1 offset:3072
	v_add_u32_e32 v1, s11, v146
	ds_read_b128 v[164:167], v1
	ds_read_b128 v[168:171], v1 offset:1024
	ds_read_b128 v[172:175], v1 offset:2048
	ds_read_b128 v[176:179], v1 offset:3072
	s_add_u32 s8, s72, 0x80000
	s_addc_u32 s9, s73, 0
	s_mov_b32 m0, s85
	v_lshl_add_u64 v[242:243], s[8:9], 0, v[138:139]
	ds_read_b128 v[180:183], v147 offset:32768
	ds_read_b128 v[184:187], v147 offset:33792
	ds_read_b128 v[188:191], v147 offset:34816
	ds_read_b128 v[196:199], v147 offset:35840
	ds_read_b128 v[206:209], v147 offset:36864
	ds_read_b128 v[210:213], v147 offset:37888
	ds_read_b128 v[228:231], v147 offset:38912
	ds_read_b128 v[232:235], v147 offset:39936
	global_load_lds_dwordx4 v[242:243], off
	v_lshl_add_u64 v[242:243], s[8:9], 0, v[134:135]
	s_mov_b32 m0, s86
	s_nop 0
	global_load_lds_dwordx4 v[242:243], off
	s_waitcnt vmcnt(8)
	s_waitcnt lgkmcnt(0)
	s_barrier
	s_setprio 1
	s_waitcnt lgkmcnt(0)
	v_mfma_f32_16x16x32_bf16 v[128:131], v[148:151], v[180:183], v[128:131]
	v_mfma_f32_16x16x32_bf16 v[124:127], v[156:159], v[180:183], v[124:127]
	v_mfma_f32_16x16x32_bf16 v[112:115], v[148:151], v[188:191], v[112:115]
	v_mfma_f32_16x16x32_bf16 v[108:111], v[156:159], v[188:191], v[108:111]
	v_mfma_f32_16x16x32_bf16 v[96:99], v[148:151], v[206:209], v[96:99]
	v_mfma_f32_16x16x32_bf16 v[92:95], v[156:159], v[206:209], v[92:95]
	v_mfma_f32_16x16x32_bf16 v[80:83], v[148:151], v[228:231], v[80:83]
	v_mfma_f32_16x16x32_bf16 v[76:79], v[156:159], v[228:231], v[76:79]
	v_mfma_f32_16x16x32_bf16 v[128:131], v[152:155], v[184:187], v[128:131]
	v_mfma_f32_16x16x32_bf16 v[124:127], v[160:163], v[184:187], v[124:127]
	v_mfma_f32_16x16x32_bf16 v[112:115], v[152:155], v[196:199], v[112:115]
	v_mfma_f32_16x16x32_bf16 v[108:111], v[160:163], v[196:199], v[108:111]
	v_mfma_f32_16x16x32_bf16 v[96:99], v[152:155], v[210:213], v[96:99]
	v_mfma_f32_16x16x32_bf16 v[92:95], v[160:163], v[210:213], v[92:95]
	v_mfma_f32_16x16x32_bf16 v[80:83], v[152:155], v[232:235], v[80:83]
	v_mfma_f32_16x16x32_bf16 v[76:79], v[160:163], v[232:235], v[76:79]
	s_setprio 0
	s_setprio 1
	v_mfma_f32_16x16x32_bf16 v[120:123], v[164:167], v[180:183], v[120:123]
	v_mfma_f32_16x16x32_bf16 v[116:119], v[172:175], v[180:183], v[116:119]
	v_mfma_f32_16x16x32_bf16 v[104:107], v[164:167], v[188:191], v[104:107]
	v_mfma_f32_16x16x32_bf16 v[100:103], v[172:175], v[188:191], v[100:103]
	v_mfma_f32_16x16x32_bf16 v[88:91], v[164:167], v[206:209], v[88:91]
	v_mfma_f32_16x16x32_bf16 v[84:87], v[172:175], v[206:209], v[84:87]
	v_mfma_f32_16x16x32_bf16 v[72:75], v[164:167], v[228:231], v[72:75]
	v_mfma_f32_16x16x32_bf16 v[68:71], v[172:175], v[228:231], v[68:71]
	v_mfma_f32_16x16x32_bf16 v[120:123], v[168:171], v[184:187], v[120:123]
	v_mfma_f32_16x16x32_bf16 v[116:119], v[176:179], v[184:187], v[116:119]
	v_mfma_f32_16x16x32_bf16 v[104:107], v[168:171], v[196:199], v[104:107]
	v_mfma_f32_16x16x32_bf16 v[100:103], v[176:179], v[196:199], v[100:103]
	v_mfma_f32_16x16x32_bf16 v[88:91], v[168:171], v[210:213], v[88:91]
	v_mfma_f32_16x16x32_bf16 v[84:87], v[176:179], v[210:213], v[84:87]
	v_mfma_f32_16x16x32_bf16 v[72:75], v[168:171], v[232:235], v[72:75]
	v_mfma_f32_16x16x32_bf16 v[68:71], v[176:179], v[232:235], v[68:71]
	s_setprio 0
	s_barrier
; #define PG8_STAGE2(bufoff, gbase, voff) do { _Pragma("unroll") for (int _i = 0; _i < 2; ++_i) \
;         __builtin_amdgcn_global_load_lds((const unsigned*)((const char*)(gbase) + (voff)[_i]), (LAS unsigned*)(lds + (bufoff) + ldsw + _i * 8192), 16, 0, 0); } while (0)
; #define PG8_LDA(dst, b, h) do { _Pragma("unroll") for (int m = 0; m < 4; ++m) _Pragma("unroll") for (int k = 0; k < 2; ++k) dst[m][k] = *(const LAS bf16x8*)(lds + PG8_SA(b, h) + aoff + m * 2048 + k * 1024); } while (0)
; #define PG8_MMA(ai, bj, At, Bt) do { __builtin_amdgcn_s_setprio(1); _Pragma("unroll") for (int m = 0; m < 4; ++m) _Pragma("unroll") for (int n = 0; n < 2; ++n) _Pragma("unroll") for (int k = 0; k < 2; ++k) \
;         acc[ai][bj][m][n] = __builtin_amdgcn_mfma_f32_16x16x32_bf16(Bt[n][k], At[m][k], acc[ai][bj][m][n], 0, 0, 0); __builtin_amdgcn_s_setprio(0); } while (0)
; #define PG8_WAIT_V(n) asm volatile("s_waitcnt vmcnt(" #n ")" ::: "memory")
; #define PG8_WAIT_L(n) asm volatile("s_waitcnt lgkmcnt(" #n ")" ::: "memory")
; #define PG8_BAR __builtin_amdgcn_s_barrier()
; #define PG8_SCHED __builtin_amdgcn_sched_barrier(0)
; template <class Epi>
; __device__ __forceinline__ void gemm_phase(LAS unsigned char* lds, const Sched& S, const Epi& E) {
;     ...
;             PG8_LDA(At, 1, 1); PG8_STAGE2(PG8_SB(1, 0), b3, voffB); PG8_STAGE2(PG8_SB(1, 1), b3 + hstep, voffB); PG8_STAGE2(PG8_SA(1, 0), a3, voffA);
;             PG8_WAIT_V(8); PG8_WAIT_L(0); PG8_BAR; PG8_MMA(1, 0, At, B0); PG8_MMA(1, 1, At, B1); PG8_BAR; PG8_SCHED;
;         }
;         if (wr == 0) PG8_BAR;
	s_add_i32 s8, s10, s7
	v_lshl_add_u64 v[200:201], v[200:201], 0, s[22:23]
	s_mov_b32 m0, s8
	ds_read_b128 v[180:183], v147 offset:49152
	ds_read_b128 v[184:187], v147 offset:50176
	ds_read_b128 v[188:191], v147 offset:51200
	ds_read_b128 v[196:199], v147 offset:52224
	ds_read_b128 v[206:209], v147 offset:53248
	ds_read_b128 v[210:213], v147 offset:54272
	ds_read_b128 v[228:231], v147 offset:55296
	ds_read_b128 v[232:235], v147 offset:56320
	global_load_lds_dwordx4 v[200:201], off
	s_add_i32 m0, s8, 0x2000
	s_add_u32 s8, s70, 0x80080
	v_lshl_add_u64 v[200:201], v[236:237], 0, s[22:23]
	s_addc_u32 s9, s71, 0
	s_add_i32 s10, s11, s7
	global_load_lds_dwordx4 v[200:201], off
	v_lshl_add_u64 v[200:201], s[8:9], 0, v[136:137]
	s_mov_b32 m0, s10
	s_nop 0
	global_load_lds_dwordx4 v[200:201], off
	v_lshl_add_u64 v[200:201], s[8:9], 0, v[132:133]
	s_add_i32 m0, s10, 0x2000
	s_nop 0
	global_load_lds_dwordx4 v[200:201], off
	v_lshl_add_u64 v[200:201], v[238:239], 0, s[22:23]
	s_mov_b32 m0, s87
	s_nop 0
	global_load_lds_dwordx4 v[200:201], off
	v_lshl_add_u64 v[200:201], v[240:241], 0, s[22:23]
	s_mov_b32 m0, s88
	s_nop 0
	global_load_lds_dwordx4 v[200:201], off
	s_waitcnt vmcnt(8)
	s_waitcnt lgkmcnt(0)
	s_barrier
	s_setprio 1
	s_waitcnt lgkmcnt(0)
	v_mfma_f32_16x16x32_bf16 v[64:67], v[148:151], v[180:183], v[64:67]
	v_mfma_f32_16x16x32_bf16 v[60:63], v[156:159], v[180:183], v[60:63]
	v_mfma_f32_16x16x32_bf16 v[48:51], v[148:151], v[188:191], v[48:51]
	v_mfma_f32_16x16x32_bf16 v[44:47], v[156:159], v[188:191], v[44:47]
	v_mfma_f32_16x16x32_bf16 v[32:35], v[148:151], v[206:209], v[32:35]
	v_mfma_f32_16x16x32_bf16 v[28:31], v[156:159], v[206:209], v[28:31]
	v_mfma_f32_16x16x32_bf16 v[16:19], v[148:151], v[228:231], v[16:19]
	v_mfma_f32_16x16x32_bf16 v[12:15], v[156:159], v[228:231], v[12:15]
	v_mfma_f32_16x16x32_bf16 v[64:67], v[152:155], v[184:187], v[64:67]
	v_mfma_f32_16x16x32_bf16 v[60:63], v[160:163], v[184:187], v[60:63]
	v_mfma_f32_16x16x32_bf16 v[48:51], v[152:155], v[196:199], v[48:51]
	v_mfma_f32_16x16x32_bf16 v[44:47], v[160:163], v[196:199], v[44:47]
	v_mfma_f32_16x16x32_bf16 v[32:35], v[152:155], v[210:213], v[32:35]
	v_mfma_f32_16x16x32_bf16 v[28:31], v[160:163], v[210:213], v[28:31]
	v_mfma_f32_16x16x32_bf16 v[16:19], v[152:155], v[232:235], v[16:19]
	v_mfma_f32_16x16x32_bf16 v[12:15], v[160:163], v[232:235], v[12:15]
	s_setprio 0
	s_setprio 1
	v_mfma_f32_16x16x32_bf16 v[56:59], v[164:167], v[180:183], v[56:59]
	v_mfma_f32_16x16x32_bf16 v[52:55], v[172:175], v[180:183], v[52:55]
	v_mfma_f32_16x16x32_bf16 v[40:43], v[164:167], v[188:191], v[40:43]
	v_mfma_f32_16x16x32_bf16 v[36:39], v[172:175], v[188:191], v[36:39]
	v_mfma_f32_16x16x32_bf16 v[24:27], v[164:167], v[206:209], v[24:27]
	v_mfma_f32_16x16x32_bf16 v[20:23], v[172:175], v[206:209], v[20:23]
	v_mfma_f32_16x16x32_bf16 v[8:11], v[164:167], v[228:231], v[8:11]
	v_mfma_f32_16x16x32_bf16 v[4:7], v[172:175], v[228:231], v[4:7]
	v_mfma_f32_16x16x32_bf16 v[56:59], v[168:171], v[184:187], v[56:59]
	v_mfma_f32_16x16x32_bf16 v[52:55], v[176:179], v[184:187], v[52:55]
	v_mfma_f32_16x16x32_bf16 v[40:43], v[168:171], v[196:199], v[40:43]
	v_mfma_f32_16x16x32_bf16 v[36:39], v[176:179], v[196:199], v[36:39]
	v_mfma_f32_16x16x32_bf16 v[24:27], v[168:171], v[210:213], v[24:27]
	v_mfma_f32_16x16x32_bf16 v[20:23], v[176:179], v[210:213], v[20:23]
	v_mfma_f32_16x16x32_bf16 v[8:11], v[168:171], v[232:235], v[8:11]
	v_mfma_f32_16x16x32_bf16 v[4:7], v[176:179], v[232:235], v[4:7]
	s_setprio 0
	s_add_i32 vcc_hi, vcc_hi, 2
	s_add_u32 s68, s68, 0x100
	s_addc_u32 s69, s69, 0
	s_cmp_gt_u32 vcc_hi, 29
	s_barrier
	s_cbranch_scc0 .LBB0_774
	s_and_b64 vcc, exec, s[56:57]
	s_cbranch_vccz .LBB0_777
	s_barrier

; #define PG8_STAGE2(bufoff, gbase, voff) do { _Pragma("unroll") for (int _i = 0; _i < 2; ++_i) \
;         __builtin_amdgcn_global_load_lds((const unsigned*)((const char*)(gbase) + (voff)[_i]), (LAS unsigned*)(lds + (bufoff) + ldsw + _i * 8192), 16, 0, 0); } while (0)
; #define PG8_LDA(dst, b, h) do { _Pragma("unroll") for (int m = 0; m < 4; ++m) _Pragma("unroll") for (int k = 0; k < 2; ++k) dst[m][k] = *(const LAS bf16x8*)(lds + PG8_SA(b, h) + aoff + m * 2048 + k * 1024); } while (0)
; #define PG8_LDB(dst, b, h) do { _Pragma("unroll") for (int n = 0; n < 2; ++n) _Pragma("unroll") for (int k = 0; k < 2; ++k) dst[n][k] = *(const LAS bf16x8*)(lds + PG8_SB(b, h) + boff + n * 2048 + k * 1024); } while (0)
; #define PG8_MMA(ai, bj, At, Bt) do { __builtin_amdgcn_s_setprio(1); _Pragma("unroll") for (int m = 0; m < 4; ++m) _Pragma("unroll") for (int n = 0; n < 2; ++n) _Pragma("unroll") for (int k = 0; k < 2; ++k) \
;         acc[ai][bj][m][n] = __builtin_amdgcn_mfma_f32_16x16x32_bf16(Bt[n][k], At[m][k], acc[ai][bj][m][n], 0, 0, 0); __builtin_amdgcn_s_setprio(0); } while (0)
; #define PG8_WAIT_V(n) asm volatile("s_waitcnt vmcnt(" #n ")" ::: "memory")
; #define PG8_WAIT_L(n) asm volatile("s_waitcnt lgkmcnt(" #n ")" ::: "memory")
; #define PG8_BAR __builtin_amdgcn_s_barrier()
; #define PG8_SCHED __builtin_amdgcn_sched_barrier(0)
; template <class Epi>
; __device__ __forceinline__ void gemm_phase(LAS unsigned char* lds, const Sched& S, const Epi& E) {
;     ...
;         for (int t = 0; t < nt; t += 2) {
;             const bool last = (t == nt - 2);
;             const char* a1 = cA + (size_t)(t + 1) * kstep;
;             const char* a2 = last ? nA : cA + (size_t)(t + 2) * kstep; const char* b2 = last ? nB : cB + (size_t)(t + 2) * kstep;
;             const char* a3 = a2 + kstep; const char* b3 = b2 + kstep;
;             PG8_LDB(B0, 0, 0); PG8_LDB(B1, 0, 1); PG8_SCHED; PG8_LDA(At, 0, 0); PG8_STAGE2(PG8_SA(1, 1), a1 + hstep, voffA);
;             PG8_WAIT_V(8); PG8_WAIT_L(0); PG8_BAR; PG8_MMA(0, 0, At, B0); PG8_MMA(0, 1, At, B1); PG8_BAR; PG8_SCHED;
;             PG8_LDA(At, 0, 1); PG8_STAGE2(PG8_SB(0, 0), b2, voffB); PG8_STAGE2(PG8_SB(0, 1), b2 + hstep, voffB); PG8_STAGE2(PG8_SA(0, 0), a2, voffA);
.LBB0_824:
	s_add_u32 s8, s54, 0xfff80080
	s_addc_u32 s9, s55, -1
	s_add_i32 s10, 0, 0x10000
	s_cmp_eq_u32 s69, 28
	s_cselect_b32 s59, s6, s9
	s_cselect_b32 s58, s7, s8
	v_add_u32_e32 v146, s10, v148
	s_cselect_b32 s57, s35, s68
	s_cselect_b32 s56, s49, s67
	s_add_i32 s11, 0, 0x14000
	ds_read_b128 v[142:145], v146
	ds_read_b128 v[152:155], v146 offset:1024
	ds_read_b128 v[156:159], v146 offset:2048
	ds_read_b128 v[160:163], v146 offset:3072
	v_add_u32_e32 v146, s11, v148
	ds_read_b128 v[164:167], v146
	ds_read_b128 v[168:171], v146 offset:1024
	ds_read_b128 v[172:175], v146 offset:2048
	ds_read_b128 v[176:179], v146 offset:3072
	v_lshl_add_u64 v[146:147], s[54:55], 0, v[138:139]
	s_add_i32 m0, s60, 0xc000
	ds_read_b128 v[180:183], v150
	ds_read_b128 v[184:187], v150 offset:1024
	ds_read_b128 v[188:191], v150 offset:2048
	ds_read_b128 v[192:195], v150 offset:3072
	ds_read_b128 v[196:199], v150 offset:4096
	ds_read_b128 v[206:209], v150 offset:5120
	ds_read_b128 v[210:213], v150 offset:6144
	ds_read_b128 v[228:231], v150 offset:7168
	global_load_lds_dwordx4 v[146:147], off
	v_lshl_add_u64 v[146:147], s[54:55], 0, v[140:141]
	s_add_i32 m0, s60, 0xe000
	s_nop 0
	global_load_lds_dwordx4 v[146:147], off
	s_waitcnt vmcnt(8)
	s_waitcnt lgkmcnt(0)
	s_barrier
	s_setprio 1
	s_waitcnt lgkmcnt(0)
	v_mfma_f32_16x16x32_bf16 v[126:129], v[142:145], v[180:183], v[126:129]
	v_mfma_f32_16x16x32_bf16 v[122:125], v[156:159], v[180:183], v[122:125]
	v_mfma_f32_16x16x32_bf16 v[110:113], v[142:145], v[188:191], v[110:113]
	v_mfma_f32_16x16x32_bf16 v[106:109], v[156:159], v[188:191], v[106:109]
	v_mfma_f32_16x16x32_bf16 v[94:97], v[142:145], v[196:199], v[94:97]
	v_mfma_f32_16x16x32_bf16 v[90:93], v[156:159], v[196:199], v[90:93]
	v_mfma_f32_16x16x32_bf16 v[78:81], v[142:145], v[210:213], v[78:81]
	v_mfma_f32_16x16x32_bf16 v[74:77], v[156:159], v[210:213], v[74:77]
	v_mfma_f32_16x16x32_bf16 v[126:129], v[152:155], v[184:187], v[126:129]
	v_mfma_f32_16x16x32_bf16 v[122:125], v[160:163], v[184:187], v[122:125]
	v_mfma_f32_16x16x32_bf16 v[110:113], v[152:155], v[192:195], v[110:113]
	v_mfma_f32_16x16x32_bf16 v[106:109], v[160:163], v[192:195], v[106:109]
	v_mfma_f32_16x16x32_bf16 v[94:97], v[152:155], v[206:209], v[94:97]
	v_mfma_f32_16x16x32_bf16 v[90:93], v[160:163], v[206:209], v[90:93]
	v_mfma_f32_16x16x32_bf16 v[78:81], v[152:155], v[228:231], v[78:81]
	v_mfma_f32_16x16x32_bf16 v[74:77], v[160:163], v[228:231], v[74:77]
	s_setprio 0
	s_setprio 1
	v_mfma_f32_16x16x32_bf16 v[118:121], v[164:167], v[180:183], v[118:121]
	v_mfma_f32_16x16x32_bf16 v[114:117], v[172:175], v[180:183], v[114:117]
	v_mfma_f32_16x16x32_bf16 v[102:105], v[164:167], v[188:191], v[102:105]
	v_mfma_f32_16x16x32_bf16 v[98:101], v[172:175], v[188:191], v[98:101]
	v_mfma_f32_16x16x32_bf16 v[86:89], v[164:167], v[196:199], v[86:89]
	v_mfma_f32_16x16x32_bf16 v[82:85], v[172:175], v[196:199], v[82:85]
	v_mfma_f32_16x16x32_bf16 v[70:73], v[164:167], v[210:213], v[70:73]
	v_mfma_f32_16x16x32_bf16 v[66:69], v[172:175], v[210:213], v[66:69]
	v_mfma_f32_16x16x32_bf16 v[118:121], v[168:171], v[184:187], v[118:121]
	v_mfma_f32_16x16x32_bf16 v[114:117], v[176:179], v[184:187], v[114:117]
	v_mfma_f32_16x16x32_bf16 v[102:105], v[168:171], v[192:195], v[102:105]
	v_mfma_f32_16x16x32_bf16 v[98:101], v[176:179], v[192:195], v[98:101]
	v_mfma_f32_16x16x32_bf16 v[86:89], v[168:171], v[206:209], v[86:89]
	v_mfma_f32_16x16x32_bf16 v[82:85], v[176:179], v[206:209], v[82:85]
	v_mfma_f32_16x16x32_bf16 v[70:73], v[168:171], v[228:231], v[70:73]
	v_mfma_f32_16x16x32_bf16 v[66:69], v[176:179], v[228:231], v[66:69]
	s_setprio 0
	s_barrier
	s_add_i32 s8, s10, s36
	v_lshl_add_u64 v[146:147], s[56:57], 0, v[134:135]
	s_mov_b32 m0, s8
	ds_read_b128 v[180:183], v150 offset:16384
	ds_read_b128 v[184:187], v150 offset:17408
	ds_read_b128 v[188:191], v150 offset:18432
	ds_read_b128 v[192:195], v150 offset:19456
	ds_read_b128 v[196:199], v150 offset:20480
	ds_read_b128 v[206:209], v150 offset:21504
	ds_read_b128 v[210:213], v150 offset:22528
	ds_read_b128 v[228:231], v150 offset:23552
	global_load_lds_dwordx4 v[146:147], off
	s_add_i32 m0, s8, 0x2000
	s_add_u32 s8, s56, 0x80000
	v_lshl_add_u64 v[200:201], s[56:57], 0, v[130:131]
	s_addc_u32 s9, s57, 0
	s_add_i32 s10, s11, s36
	global_load_lds_dwordx4 v[200:201], off
	v_lshl_add_u64 v[232:233], s[8:9], 0, v[134:135]
	s_mov_b32 m0, s10
	v_lshl_add_u64 v[234:235], s[58:59], 0, v[132:133]
	global_load_lds_dwordx4 v[232:233], off
	v_lshl_add_u64 v[232:233], s[8:9], 0, v[130:131]
	s_add_i32 m0, s10, 0x2000
	s_nop 0
	global_load_lds_dwordx4 v[232:233], off
	v_lshl_add_u64 v[232:233], s[58:59], 0, v[136:137]
	s_mov_b32 m0, s60
	s_nop 0
	global_load_lds_dwordx4 v[232:233], off
	s_mov_b32 m0, s61
	s_nop 0
	global_load_lds_dwordx4 v[234:235], off
	s_waitcnt vmcnt(8)
	s_waitcnt lgkmcnt(0)
	s_barrier
; #define PG8_STAGE2(bufoff, gbase, voff) do { _Pragma("unroll") for (int _i = 0; _i < 2; ++_i) \
;         __builtin_amdgcn_global_load_lds((const unsigned*)((const char*)(gbase) + (voff)[_i]), (LAS unsigned*)(lds + (bufoff) + ldsw + _i * 8192), 16, 0, 0); } while (0)
; #define PG8_LDA(dst, b, h) do { _Pragma("unroll") for (int m = 0; m < 4; ++m) _Pragma("unroll") for (int k = 0; k < 2; ++k) dst[m][k] = *(const LAS bf16x8*)(lds + PG8_SA(b, h) + aoff + m * 2048 + k * 1024); } while (0)
; #define PG8_LDB(dst, b, h) do { _Pragma("unroll") for (int n = 0; n < 2; ++n) _Pragma("unroll") for (int k = 0; k < 2; ++k) dst[n][k] = *(const LAS bf16x8*)(lds + PG8_SB(b, h) + boff + n * 2048 + k * 1024); } while (0)
; #define PG8_MMA(ai, bj, At, Bt) do { __builtin_amdgcn_s_setprio(1); _Pragma("unroll") for (int m = 0; m < 4; ++m) _Pragma("unroll") for (int n = 0; n < 2; ++n) _Pragma("unroll") for (int k = 0; k < 2; ++k) \
;         acc[ai][bj][m][n] = __builtin_amdgcn_mfma_f32_16x16x32_bf16(Bt[n][k], At[m][k], acc[ai][bj][m][n], 0, 0, 0); __builtin_amdgcn_s_setprio(0); } while (0)
; #define PG8_WAIT_V(n) asm volatile("s_waitcnt vmcnt(" #n ")" ::: "memory")
; #define PG8_WAIT_L(n) asm volatile("s_waitcnt lgkmcnt(" #n ")" ::: "memory")
; #define PG8_BAR __builtin_amdgcn_s_barrier()
; #define PG8_SCHED __builtin_amdgcn_sched_barrier(0)
; template <class Epi>
; __device__ __forceinline__ void gemm_phase(LAS unsigned char* lds, const Sched& S, const Epi& E) {
;     ...
;             PG8_WAIT_V(8); PG8_WAIT_L(0); PG8_BAR; PG8_MMA(1, 0, At, B0); PG8_MMA(1, 1, At, B1); PG8_BAR; PG8_SCHED;
;             PG8_LDB(B0, 1, 0); PG8_LDB(B1, 1, 1); PG8_SCHED; PG8_LDA(At, 1, 0); PG8_STAGE2(PG8_SA(0, 1), a2 + hstep, voffA);
;             PG8_WAIT_V(8); PG8_WAIT_L(0); PG8_BAR; PG8_MMA(0, 0, At, B0); PG8_MMA(0, 1, At, B1); PG8_BAR; PG8_SCHED;
	s_setprio 1
	s_waitcnt lgkmcnt(0)
	v_mfma_f32_16x16x32_bf16 v[62:65], v[142:145], v[180:183], v[62:65]
	v_mfma_f32_16x16x32_bf16 v[58:61], v[156:159], v[180:183], v[58:61]
	v_mfma_f32_16x16x32_bf16 v[46:49], v[142:145], v[188:191], v[46:49]
	v_mfma_f32_16x16x32_bf16 v[42:45], v[156:159], v[188:191], v[42:45]
	v_mfma_f32_16x16x32_bf16 v[30:33], v[142:145], v[196:199], v[30:33]
	v_mfma_f32_16x16x32_bf16 v[26:29], v[156:159], v[196:199], v[26:29]
	v_mfma_f32_16x16x32_bf16 v[14:17], v[142:145], v[210:213], v[14:17]
	v_mfma_f32_16x16x32_bf16 v[10:13], v[156:159], v[210:213], v[10:13]
	v_mfma_f32_16x16x32_bf16 v[62:65], v[152:155], v[184:187], v[62:65]
	v_mfma_f32_16x16x32_bf16 v[58:61], v[160:163], v[184:187], v[58:61]
	v_mfma_f32_16x16x32_bf16 v[46:49], v[152:155], v[192:195], v[46:49]
	v_mfma_f32_16x16x32_bf16 v[42:45], v[160:163], v[192:195], v[42:45]
	v_mfma_f32_16x16x32_bf16 v[30:33], v[152:155], v[206:209], v[30:33]
	v_mfma_f32_16x16x32_bf16 v[26:29], v[160:163], v[206:209], v[26:29]
	v_mfma_f32_16x16x32_bf16 v[14:17], v[152:155], v[228:231], v[14:17]
	v_mfma_f32_16x16x32_bf16 v[10:13], v[160:163], v[228:231], v[10:13]
	s_setprio 0
	s_setprio 1
	v_mfma_f32_16x16x32_bf16 v[54:57], v[164:167], v[180:183], v[54:57]
	v_mfma_f32_16x16x32_bf16 v[50:53], v[172:175], v[180:183], v[50:53]
	v_mfma_f32_16x16x32_bf16 v[38:41], v[164:167], v[188:191], v[38:41]
	v_mfma_f32_16x16x32_bf16 v[34:37], v[172:175], v[188:191], v[34:37]
	v_mfma_f32_16x16x32_bf16 v[22:25], v[164:167], v[196:199], v[22:25]
	v_mfma_f32_16x16x32_bf16 v[18:21], v[172:175], v[196:199], v[18:21]
	v_mfma_f32_16x16x32_bf16 v[6:9], v[164:167], v[210:213], v[6:9]
	v_mfma_f32_16x16x32_bf16 v[2:5], v[172:175], v[210:213], v[2:5]
	v_mfma_f32_16x16x32_bf16 v[54:57], v[168:171], v[184:187], v[54:57]
	v_mfma_f32_16x16x32_bf16 v[50:53], v[176:179], v[184:187], v[50:53]
	v_mfma_f32_16x16x32_bf16 v[38:41], v[168:171], v[192:195], v[38:41]
	v_mfma_f32_16x16x32_bf16 v[34:37], v[176:179], v[192:195], v[34:37]
	v_mfma_f32_16x16x32_bf16 v[22:25], v[168:171], v[206:209], v[22:25]
	v_mfma_f32_16x16x32_bf16 v[18:21], v[176:179], v[206:209], v[18:21]
	v_mfma_f32_16x16x32_bf16 v[6:9], v[168:171], v[228:231], v[6:9]
	v_mfma_f32_16x16x32_bf16 v[2:5], v[176:179], v[228:231], v[2:5]
	s_setprio 0
	s_barrier
	s_add_i32 s10, 0, 0x18000
	v_add_u32_e32 v151, s10, v148
	s_add_i32 s11, 0, 0x1c000
	ds_read_b128 v[142:145], v151
	ds_read_b128 v[152:155], v151 offset:1024
	ds_read_b128 v[156:159], v151 offset:2048
	ds_read_b128 v[160:163], v151 offset:3072
	v_add_u32_e32 v151, s11, v148
	ds_read_b128 v[164:167], v151
	ds_read_b128 v[168:171], v151 offset:1024
	ds_read_b128 v[172:175], v151 offset:2048
	ds_read_b128 v[176:179], v151 offset:3072
	s_add_u32 s8, s58, 0x80000
	s_addc_u32 s9, s59, 0
	s_mov_b32 m0, s62
	v_lshl_add_u64 v[236:237], s[8:9], 0, v[136:137]
	ds_read_b128 v[180:183], v150 offset:32768
	ds_read_b128 v[184:187], v150 offset:33792
	ds_read_b128 v[188:191], v150 offset:34816
	ds_read_b128 v[192:195], v150 offset:35840
	ds_read_b128 v[196:199], v150 offset:36864
	ds_read_b128 v[206:209], v150 offset:37888
	ds_read_b128 v[210:213], v150 offset:38912
	ds_read_b128 v[228:231], v150 offset:39936
	global_load_lds_dwordx4 v[236:237], off
	v_lshl_add_u64 v[236:237], s[8:9], 0, v[132:133]
	s_mov_b32 m0, s63
	s_nop 0
	global_load_lds_dwordx4 v[236:237], off
	s_waitcnt vmcnt(8)
	s_waitcnt lgkmcnt(0)
	s_barrier
	s_setprio 1
	s_waitcnt lgkmcnt(0)
	v_mfma_f32_16x16x32_bf16 v[126:129], v[142:145], v[180:183], v[126:129]
	v_mfma_f32_16x16x32_bf16 v[122:125], v[156:159], v[180:183], v[122:125]
	v_mfma_f32_16x16x32_bf16 v[110:113], v[142:145], v[188:191], v[110:113]
	v_mfma_f32_16x16x32_bf16 v[106:109], v[156:159], v[188:191], v[106:109]
	v_mfma_f32_16x16x32_bf16 v[94:97], v[142:145], v[196:199], v[94:97]
	v_mfma_f32_16x16x32_bf16 v[90:93], v[156:159], v[196:199], v[90:93]
	v_mfma_f32_16x16x32_bf16 v[78:81], v[142:145], v[210:213], v[78:81]
	v_mfma_f32_16x16x32_bf16 v[74:77], v[156:159], v[210:213], v[74:77]
	v_mfma_f32_16x16x32_bf16 v[126:129], v[152:155], v[184:187], v[126:129]
	v_mfma_f32_16x16x32_bf16 v[122:125], v[160:163], v[184:187], v[122:125]
	v_mfma_f32_16x16x32_bf16 v[110:113], v[152:155], v[192:195], v[110:113]
	v_mfma_f32_16x16x32_bf16 v[106:109], v[160:163], v[192:195], v[106:109]
	v_mfma_f32_16x16x32_bf16 v[94:97], v[152:155], v[206:209], v[94:97]
	v_mfma_f32_16x16x32_bf16 v[90:93], v[160:163], v[206:209], v[90:93]
	v_mfma_f32_16x16x32_bf16 v[78:81], v[152:155], v[228:231], v[78:81]
	v_mfma_f32_16x16x32_bf16 v[74:77], v[160:163], v[228:231], v[74:77]
	s_setprio 0
	s_setprio 1
	v_mfma_f32_16x16x32_bf16 v[118:121], v[164:167], v[180:183], v[118:121]
	v_mfma_f32_16x16x32_bf16 v[114:117], v[172:175], v[180:183], v[114:117]
	v_mfma_f32_16x16x32_bf16 v[102:105], v[164:167], v[188:191], v[102:105]
	v_mfma_f32_16x16x32_bf16 v[98:101], v[172:175], v[188:191], v[98:101]
	v_mfma_f32_16x16x32_bf16 v[86:89], v[164:167], v[196:199], v[86:89]
	v_mfma_f32_16x16x32_bf16 v[82:85], v[172:175], v[196:199], v[82:85]
	v_mfma_f32_16x16x32_bf16 v[70:73], v[164:167], v[210:213], v[70:73]
	v_mfma_f32_16x16x32_bf16 v[66:69], v[172:175], v[210:213], v[66:69]
	v_mfma_f32_16x16x32_bf16 v[118:121], v[168:171], v[184:187], v[118:121]
	v_mfma_f32_16x16x32_bf16 v[114:117], v[176:179], v[184:187], v[114:117]
	v_mfma_f32_16x16x32_bf16 v[102:105], v[168:171], v[192:195], v[102:105]
	v_mfma_f32_16x16x32_bf16 v[98:101], v[176:179], v[192:195], v[98:101]
	v_mfma_f32_16x16x32_bf16 v[86:89], v[168:171], v[206:209], v[86:89]
	v_mfma_f32_16x16x32_bf16 v[82:85], v[176:179], v[206:209], v[82:85]
	v_mfma_f32_16x16x32_bf16 v[70:73], v[168:171], v[228:231], v[70:73]
	v_mfma_f32_16x16x32_bf16 v[66:69], v[176:179], v[228:231], v[66:69]
	s_setprio 0
	s_barrier
; #define PG8_STAGE2(bufoff, gbase, voff) do { _Pragma("unroll") for (int _i = 0; _i < 2; ++_i) \
;         __builtin_amdgcn_global_load_lds((const unsigned*)((const char*)(gbase) + (voff)[_i]), (LAS unsigned*)(lds + (bufoff) + ldsw + _i * 8192), 16, 0, 0); } while (0)
; #define PG8_LDA(dst, b, h) do { _Pragma("unroll") for (int m = 0; m < 4; ++m) _Pragma("unroll") for (int k = 0; k < 2; ++k) dst[m][k] = *(const LAS bf16x8*)(lds + PG8_SA(b, h) + aoff + m * 2048 + k * 1024); } while (0)
; #define PG8_MMA(ai, bj, At, Bt) do { __builtin_amdgcn_s_setprio(1); _Pragma("unroll") for (int m = 0; m < 4; ++m) _Pragma("unroll") for (int n = 0; n < 2; ++n) _Pragma("unroll") for (int k = 0; k < 2; ++k) \
;         acc[ai][bj][m][n] = __builtin_amdgcn_mfma_f32_16x16x32_bf16(Bt[n][k], At[m][k], acc[ai][bj][m][n], 0, 0, 0); __builtin_amdgcn_s_setprio(0); } while (0)
; #define PG8_WAIT_V(n) asm volatile("s_waitcnt vmcnt(" #n ")" ::: "memory")
; #define PG8_WAIT_L(n) asm volatile("s_waitcnt lgkmcnt(" #n ")" ::: "memory")
; #define PG8_BAR __builtin_amdgcn_s_barrier()
; #define PG8_SCHED __builtin_amdgcn_sched_barrier(0)
; template <class Epi>
; __device__ __forceinline__ void gemm_phase(LAS unsigned char* lds, const Sched& S, const Epi& E) {
;     ...
;             PG8_LDA(At, 1, 1); PG8_STAGE2(PG8_SB(1, 0), b3, voffB); PG8_STAGE2(PG8_SB(1, 1), b3 + hstep, voffB); PG8_STAGE2(PG8_SA(1, 0), a3, voffA);
;             PG8_WAIT_V(8); PG8_WAIT_L(0); PG8_BAR; PG8_MMA(1, 0, At, B0); PG8_MMA(1, 1, At, B1); PG8_BAR; PG8_SCHED;
;         }
;         if (wr == 0) PG8_BAR;
	s_add_i32 s8, s10, s36
	v_lshl_add_u64 v[146:147], v[146:147], 0, s[22:23]
	s_mov_b32 m0, s8
	ds_read_b128 v[180:183], v150 offset:49152
	ds_read_b128 v[184:187], v150 offset:50176
	ds_read_b128 v[188:191], v150 offset:51200
	ds_read_b128 v[192:195], v150 offset:52224
	ds_read_b128 v[196:199], v150 offset:53248
	ds_read_b128 v[206:209], v150 offset:54272
	ds_read_b128 v[210:213], v150 offset:55296
	ds_read_b128 v[228:231], v150 offset:56320
	global_load_lds_dwordx4 v[146:147], off
	s_add_i32 m0, s8, 0x2000
	s_add_u32 s8, s56, 0x80080
	v_lshl_add_u64 v[146:147], v[200:201], 0, s[22:23]
	s_addc_u32 s9, s57, 0
	s_add_i32 s10, s11, s36
	global_load_lds_dwordx4 v[146:147], off
	v_lshl_add_u64 v[146:147], s[8:9], 0, v[134:135]
	s_mov_b32 m0, s10
	s_nop 0
	global_load_lds_dwordx4 v[146:147], off
	v_lshl_add_u64 v[146:147], s[8:9], 0, v[130:131]
	s_add_i32 m0, s10, 0x2000
	s_nop 0
	global_load_lds_dwordx4 v[146:147], off
	v_lshl_add_u64 v[146:147], v[232:233], 0, s[22:23]
	s_mov_b32 m0, s64
	s_nop 0
	global_load_lds_dwordx4 v[146:147], off
	v_lshl_add_u64 v[146:147], v[234:235], 0, s[22:23]
	s_mov_b32 m0, s65
	s_nop 0
	global_load_lds_dwordx4 v[146:147], off
	s_waitcnt vmcnt(8)
	s_waitcnt lgkmcnt(0)
	s_barrier
	s_setprio 1
	s_waitcnt lgkmcnt(0)
	v_mfma_f32_16x16x32_bf16 v[62:65], v[142:145], v[180:183], v[62:65]
	v_mfma_f32_16x16x32_bf16 v[58:61], v[156:159], v[180:183], v[58:61]
	v_mfma_f32_16x16x32_bf16 v[46:49], v[142:145], v[188:191], v[46:49]
	v_mfma_f32_16x16x32_bf16 v[42:45], v[156:159], v[188:191], v[42:45]
	v_mfma_f32_16x16x32_bf16 v[30:33], v[142:145], v[196:199], v[30:33]
	v_mfma_f32_16x16x32_bf16 v[26:29], v[156:159], v[196:199], v[26:29]
	v_mfma_f32_16x16x32_bf16 v[14:17], v[142:145], v[210:213], v[14:17]
	v_mfma_f32_16x16x32_bf16 v[10:13], v[156:159], v[210:213], v[10:13]
	v_mfma_f32_16x16x32_bf16 v[62:65], v[152:155], v[184:187], v[62:65]
	v_mfma_f32_16x16x32_bf16 v[58:61], v[160:163], v[184:187], v[58:61]
	v_mfma_f32_16x16x32_bf16 v[46:49], v[152:155], v[192:195], v[46:49]
	v_mfma_f32_16x16x32_bf16 v[42:45], v[160:163], v[192:195], v[42:45]
	v_mfma_f32_16x16x32_bf16 v[30:33], v[152:155], v[206:209], v[30:33]
	v_mfma_f32_16x16x32_bf16 v[26:29], v[160:163], v[206:209], v[26:29]
	v_mfma_f32_16x16x32_bf16 v[14:17], v[152:155], v[228:231], v[14:17]
	v_mfma_f32_16x16x32_bf16 v[10:13], v[160:163], v[228:231], v[10:13]
	s_setprio 0
	s_setprio 1
	v_mfma_f32_16x16x32_bf16 v[54:57], v[164:167], v[180:183], v[54:57]
	v_mfma_f32_16x16x32_bf16 v[50:53], v[172:175], v[180:183], v[50:53]
	v_mfma_f32_16x16x32_bf16 v[38:41], v[164:167], v[188:191], v[38:41]
	v_mfma_f32_16x16x32_bf16 v[34:37], v[172:175], v[188:191], v[34:37]
	v_mfma_f32_16x16x32_bf16 v[22:25], v[164:167], v[196:199], v[22:25]
	v_mfma_f32_16x16x32_bf16 v[18:21], v[172:175], v[196:199], v[18:21]
	v_mfma_f32_16x16x32_bf16 v[6:9], v[164:167], v[210:213], v[6:9]
	v_mfma_f32_16x16x32_bf16 v[2:5], v[172:175], v[210:213], v[2:5]
	v_mfma_f32_16x16x32_bf16 v[54:57], v[168:171], v[184:187], v[54:57]
	v_mfma_f32_16x16x32_bf16 v[50:53], v[176:179], v[184:187], v[50:53]
	v_mfma_f32_16x16x32_bf16 v[38:41], v[168:171], v[192:195], v[38:41]
	v_mfma_f32_16x16x32_bf16 v[34:37], v[176:179], v[192:195], v[34:37]
	v_mfma_f32_16x16x32_bf16 v[22:25], v[168:171], v[206:209], v[22:25]
	v_mfma_f32_16x16x32_bf16 v[18:21], v[176:179], v[206:209], v[18:21]
	v_mfma_f32_16x16x32_bf16 v[6:9], v[168:171], v[228:231], v[6:9]
	v_mfma_f32_16x16x32_bf16 v[2:5], v[176:179], v[228:231], v[2:5]
	s_setprio 0
	s_add_i32 s69, s69, 2
	s_add_u32 s54, s54, 0x100
	s_addc_u32 s55, s55, 0
	s_add_u32 s67, s67, 0x100
	s_addc_u32 s68, s68, 0
	s_cmp_gt_u32 s69, 29
	s_barrier
	s_cbranch_scc0 .LBB0_824
	s_and_b64 vcc, exec, s[28:29]
	s_cbranch_vccz .LBB0_827
	s_barrier

; #define PG8_STAGE2(bufoff, gbase, voff) do { _Pragma("unroll") for (int _i = 0; _i < 2; ++_i) \
;         __builtin_amdgcn_global_load_lds((const unsigned*)((const char*)(gbase) + (voff)[_i]), (LAS unsigned*)(lds + (bufoff) + ldsw + _i * 8192), 16, 0, 0); } while (0)
; #define PG8_LDA(dst, b, h) do { _Pragma("unroll") for (int m = 0; m < 4; ++m) _Pragma("unroll") for (int k = 0; k < 2; ++k) dst[m][k] = *(const LAS bf16x8*)(lds + PG8_SA(b, h) + aoff + m * 2048 + k * 1024); } while (0)
; #define PG8_LDB(dst, b, h) do { _Pragma("unroll") for (int n = 0; n < 2; ++n) _Pragma("unroll") for (int k = 0; k < 2; ++k) dst[n][k] = *(const LAS bf16x8*)(lds + PG8_SB(b, h) + boff + n * 2048 + k * 1024); } while (0)
; #define PG8_MMA(ai, bj, At, Bt) do { __builtin_amdgcn_s_setprio(1); _Pragma("unroll") for (int m = 0; m < 4; ++m) _Pragma("unroll") for (int n = 0; n < 2; ++n) _Pragma("unroll") for (int k = 0; k < 2; ++k) \
;         acc[ai][bj][m][n] = __builtin_amdgcn_mfma_f32_16x16x32_bf16(Bt[n][k], At[m][k], acc[ai][bj][m][n], 0, 0, 0); __builtin_amdgcn_s_setprio(0); } while (0)
; #define PG8_WAIT_V(n) asm volatile("s_waitcnt vmcnt(" #n ")" ::: "memory")
; #define PG8_WAIT_L(n) asm volatile("s_waitcnt lgkmcnt(" #n ")" ::: "memory")
; #define PG8_BAR __builtin_amdgcn_s_barrier()
; #define PG8_SCHED __builtin_amdgcn_sched_barrier(0)
; template <class Epi>
; __device__ __forceinline__ void gemm_phase(LAS unsigned char* lds, const Sched& S, const Epi& E) {
;     ...
;         for (int t = 0; t < nt; t += 2) {
;             const bool last = (t == nt - 2);
;             const char* a1 = cA + (size_t)(t + 1) * kstep;
;             const char* a2 = last ? nA : cA + (size_t)(t + 2) * kstep; const char* b2 = last ? nB : cB + (size_t)(t + 2) * kstep;
;             const char* a3 = a2 + kstep; const char* b3 = b2 + kstep;
;             PG8_LDB(B0, 0, 0); PG8_LDB(B1, 0, 1); PG8_SCHED; PG8_LDA(At, 0, 0); PG8_STAGE2(PG8_SA(1, 1), a1 + hstep, voffA);
;             PG8_WAIT_V(8); PG8_WAIT_L(0); PG8_BAR; PG8_MMA(0, 0, At, B0); PG8_MMA(0, 1, At, B1); PG8_BAR; PG8_SCHED;
;             PG8_LDA(At, 0, 1); PG8_STAGE2(PG8_SB(0, 0), b2, voffB); PG8_STAGE2(PG8_SB(0, 1), b2 + hstep, voffB); PG8_STAGE2(PG8_SA(0, 0), a2, voffA);
.LBB0_955:
	s_add_u32 s8, s56, 0xfff80080
	s_addc_u32 s9, s57, -1
	s_add_i32 s10, 0, 0x10000
	s_cmp_eq_u32 s73, 28
	s_cselect_b32 s61, s51, s9
	s_cselect_b32 s60, s69, s8
	v_add_u32_e32 v149, s10, v146
	s_cselect_b32 s59, s49, s72
	s_cselect_b32 s58, s70, s71
	s_add_i32 s11, 0, 0x14000
	ds_read_b128 v[142:145], v149
	ds_read_b128 v[150:153], v149 offset:1024
	ds_read_b128 v[154:157], v149 offset:2048
	ds_read_b128 v[158:161], v149 offset:3072
	v_add_u32_e32 v149, s11, v146
	ds_read_b128 v[162:165], v149
	ds_read_b128 v[166:169], v149 offset:1024
	ds_read_b128 v[170:173], v149 offset:2048
	ds_read_b128 v[174:177], v149 offset:3072
	v_lshl_add_u64 v[228:229], s[56:57], 0, v[138:139]
	s_add_i32 m0, s40, 0xc000
	ds_read_b128 v[178:181], v148
	ds_read_b128 v[182:185], v148 offset:1024
	ds_read_b128 v[186:189], v148 offset:2048
	ds_read_b128 v[190:193], v148 offset:3072
	ds_read_b128 v[194:197], v148 offset:4096
	ds_read_b128 v[198:201], v148 offset:5120
	ds_read_b128 v[206:209], v148 offset:6144
	ds_read_b128 v[210:213], v148 offset:7168
	global_load_lds_dwordx4 v[228:229], off
	v_lshl_add_u64 v[228:229], s[56:57], 0, v[140:141]
	s_add_i32 m0, s40, 0xe000
	s_nop 0
	global_load_lds_dwordx4 v[228:229], off
	s_waitcnt vmcnt(8)
	s_waitcnt lgkmcnt(0)
	s_barrier
	s_setprio 1
	s_waitcnt lgkmcnt(0)
	v_mfma_f32_16x16x32_bf16 v[126:129], v[142:145], v[178:181], v[126:129]
	v_mfma_f32_16x16x32_bf16 v[122:125], v[154:157], v[178:181], v[122:125]
	v_mfma_f32_16x16x32_bf16 v[110:113], v[142:145], v[186:189], v[110:113]
	v_mfma_f32_16x16x32_bf16 v[106:109], v[154:157], v[186:189], v[106:109]
	v_mfma_f32_16x16x32_bf16 v[94:97], v[142:145], v[194:197], v[94:97]
	v_mfma_f32_16x16x32_bf16 v[90:93], v[154:157], v[194:197], v[90:93]
	v_mfma_f32_16x16x32_bf16 v[78:81], v[142:145], v[206:209], v[78:81]
	v_mfma_f32_16x16x32_bf16 v[74:77], v[154:157], v[206:209], v[74:77]
	v_mfma_f32_16x16x32_bf16 v[126:129], v[150:153], v[182:185], v[126:129]
	v_mfma_f32_16x16x32_bf16 v[122:125], v[158:161], v[182:185], v[122:125]
	v_mfma_f32_16x16x32_bf16 v[110:113], v[150:153], v[190:193], v[110:113]
	v_mfma_f32_16x16x32_bf16 v[106:109], v[158:161], v[190:193], v[106:109]
	v_mfma_f32_16x16x32_bf16 v[94:97], v[150:153], v[198:201], v[94:97]
	v_mfma_f32_16x16x32_bf16 v[90:93], v[158:161], v[198:201], v[90:93]
	v_mfma_f32_16x16x32_bf16 v[78:81], v[150:153], v[210:213], v[78:81]
	v_mfma_f32_16x16x32_bf16 v[74:77], v[158:161], v[210:213], v[74:77]
	s_setprio 0
	s_setprio 1
	v_mfma_f32_16x16x32_bf16 v[118:121], v[162:165], v[178:181], v[118:121]
	v_mfma_f32_16x16x32_bf16 v[114:117], v[170:173], v[178:181], v[114:117]
	v_mfma_f32_16x16x32_bf16 v[102:105], v[162:165], v[186:189], v[102:105]
	v_mfma_f32_16x16x32_bf16 v[98:101], v[170:173], v[186:189], v[98:101]
	v_mfma_f32_16x16x32_bf16 v[86:89], v[162:165], v[194:197], v[86:89]
	v_mfma_f32_16x16x32_bf16 v[82:85], v[170:173], v[194:197], v[82:85]
	v_mfma_f32_16x16x32_bf16 v[70:73], v[162:165], v[206:209], v[70:73]
	v_mfma_f32_16x16x32_bf16 v[66:69], v[170:173], v[206:209], v[66:69]
	v_mfma_f32_16x16x32_bf16 v[118:121], v[166:169], v[182:185], v[118:121]
	v_mfma_f32_16x16x32_bf16 v[114:117], v[174:177], v[182:185], v[114:117]
	v_mfma_f32_16x16x32_bf16 v[102:105], v[166:169], v[190:193], v[102:105]
	v_mfma_f32_16x16x32_bf16 v[98:101], v[174:177], v[190:193], v[98:101]
	v_mfma_f32_16x16x32_bf16 v[86:89], v[166:169], v[198:201], v[86:89]
	v_mfma_f32_16x16x32_bf16 v[82:85], v[174:177], v[198:201], v[82:85]
	v_mfma_f32_16x16x32_bf16 v[70:73], v[166:169], v[210:213], v[70:73]
	v_mfma_f32_16x16x32_bf16 v[66:69], v[174:177], v[210:213], v[66:69]
	s_setprio 0
	s_barrier
	s_add_i32 s8, s10, s36
	v_lshl_add_u64 v[228:229], s[58:59], 0, v[134:135]
	s_mov_b32 m0, s8
	ds_read_b128 v[178:181], v148 offset:16384
	ds_read_b128 v[182:185], v148 offset:17408
	ds_read_b128 v[186:189], v148 offset:18432
	ds_read_b128 v[190:193], v148 offset:19456
	ds_read_b128 v[194:197], v148 offset:20480
	ds_read_b128 v[198:201], v148 offset:21504
	ds_read_b128 v[206:209], v148 offset:22528
	ds_read_b128 v[210:213], v148 offset:23552
	global_load_lds_dwordx4 v[228:229], off
	s_add_i32 m0, s8, 0x2000
	s_add_u32 s8, s58, 0x80000
	v_lshl_add_u64 v[230:231], s[58:59], 0, v[130:131]
	s_addc_u32 s9, s59, 0
	s_add_i32 s10, s11, s36
	global_load_lds_dwordx4 v[230:231], off
	v_lshl_add_u64 v[232:233], s[8:9], 0, v[134:135]
	s_mov_b32 m0, s10
	v_lshl_add_u64 v[234:235], s[60:61], 0, v[132:133]
	global_load_lds_dwordx4 v[232:233], off
	v_lshl_add_u64 v[232:233], s[8:9], 0, v[130:131]
	s_add_i32 m0, s10, 0x2000
	s_nop 0
	global_load_lds_dwordx4 v[232:233], off
	v_lshl_add_u64 v[232:233], s[60:61], 0, v[136:137]
	s_mov_b32 m0, s40
	s_nop 0
	global_load_lds_dwordx4 v[232:233], off
	s_mov_b32 m0, s41
	s_nop 0
	global_load_lds_dwordx4 v[234:235], off
	s_waitcnt vmcnt(8)
	s_waitcnt lgkmcnt(0)
	s_barrier
; #define PG8_STAGE2(bufoff, gbase, voff) do { _Pragma("unroll") for (int _i = 0; _i < 2; ++_i) \
;         __builtin_amdgcn_global_load_lds((const unsigned*)((const char*)(gbase) + (voff)[_i]), (LAS unsigned*)(lds + (bufoff) + ldsw + _i * 8192), 16, 0, 0); } while (0)
; #define PG8_LDA(dst, b, h) do { _Pragma("unroll") for (int m = 0; m < 4; ++m) _Pragma("unroll") for (int k = 0; k < 2; ++k) dst[m][k] = *(const LAS bf16x8*)(lds + PG8_SA(b, h) + aoff + m * 2048 + k * 1024); } while (0)
; #define PG8_LDB(dst, b, h) do { _Pragma("unroll") for (int n = 0; n < 2; ++n) _Pragma("unroll") for (int k = 0; k < 2; ++k) dst[n][k] = *(const LAS bf16x8*)(lds + PG8_SB(b, h) + boff + n * 2048 + k * 1024); } while (0)
; #define PG8_MMA(ai, bj, At, Bt) do { __builtin_amdgcn_s_setprio(1); _Pragma("unroll") for (int m = 0; m < 4; ++m) _Pragma("unroll") for (int n = 0; n < 2; ++n) _Pragma("unroll") for (int k = 0; k < 2; ++k) \
;         acc[ai][bj][m][n] = __builtin_amdgcn_mfma_f32_16x16x32_bf16(Bt[n][k], At[m][k], acc[ai][bj][m][n], 0, 0, 0); __builtin_amdgcn_s_setprio(0); } while (0)
; #define PG8_WAIT_V(n) asm volatile("s_waitcnt vmcnt(" #n ")" ::: "memory")
; #define PG8_WAIT_L(n) asm volatile("s_waitcnt lgkmcnt(" #n ")" ::: "memory")
; #define PG8_BAR __builtin_amdgcn_s_barrier()
; #define PG8_SCHED __builtin_amdgcn_sched_barrier(0)
; template <class Epi>
; __device__ __forceinline__ void gemm_phase(LAS unsigned char* lds, const Sched& S, const Epi& E) {
;     ...
;             PG8_WAIT_V(8); PG8_WAIT_L(0); PG8_BAR; PG8_MMA(1, 0, At, B0); PG8_MMA(1, 1, At, B1); PG8_BAR; PG8_SCHED;
;             PG8_LDB(B0, 1, 0); PG8_LDB(B1, 1, 1); PG8_SCHED; PG8_LDA(At, 1, 0); PG8_STAGE2(PG8_SA(0, 1), a2 + hstep, voffA);
;             PG8_WAIT_V(8); PG8_WAIT_L(0); PG8_BAR; PG8_MMA(0, 0, At, B0); PG8_MMA(0, 1, At, B1); PG8_BAR; PG8_SCHED;
	s_setprio 1
	s_waitcnt lgkmcnt(0)
	v_mfma_f32_16x16x32_bf16 v[62:65], v[142:145], v[178:181], v[62:65]
	v_mfma_f32_16x16x32_bf16 v[58:61], v[154:157], v[178:181], v[58:61]
	v_mfma_f32_16x16x32_bf16 v[46:49], v[142:145], v[186:189], v[46:49]
	v_mfma_f32_16x16x32_bf16 v[42:45], v[154:157], v[186:189], v[42:45]
	v_mfma_f32_16x16x32_bf16 v[30:33], v[142:145], v[194:197], v[30:33]
	v_mfma_f32_16x16x32_bf16 v[26:29], v[154:157], v[194:197], v[26:29]
	v_mfma_f32_16x16x32_bf16 v[14:17], v[142:145], v[206:209], v[14:17]
	v_mfma_f32_16x16x32_bf16 v[10:13], v[154:157], v[206:209], v[10:13]
	v_mfma_f32_16x16x32_bf16 v[62:65], v[150:153], v[182:185], v[62:65]
	v_mfma_f32_16x16x32_bf16 v[58:61], v[158:161], v[182:185], v[58:61]
	v_mfma_f32_16x16x32_bf16 v[46:49], v[150:153], v[190:193], v[46:49]
	v_mfma_f32_16x16x32_bf16 v[42:45], v[158:161], v[190:193], v[42:45]
	v_mfma_f32_16x16x32_bf16 v[30:33], v[150:153], v[198:201], v[30:33]
	v_mfma_f32_16x16x32_bf16 v[26:29], v[158:161], v[198:201], v[26:29]
	v_mfma_f32_16x16x32_bf16 v[14:17], v[150:153], v[210:213], v[14:17]
	v_mfma_f32_16x16x32_bf16 v[10:13], v[158:161], v[210:213], v[10:13]
	s_setprio 0
	s_setprio 1
	v_mfma_f32_16x16x32_bf16 v[54:57], v[162:165], v[178:181], v[54:57]
	v_mfma_f32_16x16x32_bf16 v[50:53], v[170:173], v[178:181], v[50:53]
	v_mfma_f32_16x16x32_bf16 v[38:41], v[162:165], v[186:189], v[38:41]
	v_mfma_f32_16x16x32_bf16 v[34:37], v[170:173], v[186:189], v[34:37]
	v_mfma_f32_16x16x32_bf16 v[22:25], v[162:165], v[194:197], v[22:25]
	v_mfma_f32_16x16x32_bf16 v[18:21], v[170:173], v[194:197], v[18:21]
	v_mfma_f32_16x16x32_bf16 v[6:9], v[162:165], v[206:209], v[6:9]
	v_mfma_f32_16x16x32_bf16 v[2:5], v[170:173], v[206:209], v[2:5]
	v_mfma_f32_16x16x32_bf16 v[54:57], v[166:169], v[182:185], v[54:57]
	v_mfma_f32_16x16x32_bf16 v[50:53], v[174:177], v[182:185], v[50:53]
	v_mfma_f32_16x16x32_bf16 v[38:41], v[166:169], v[190:193], v[38:41]
	v_mfma_f32_16x16x32_bf16 v[34:37], v[174:177], v[190:193], v[34:37]
	v_mfma_f32_16x16x32_bf16 v[22:25], v[166:169], v[198:201], v[22:25]
	v_mfma_f32_16x16x32_bf16 v[18:21], v[174:177], v[198:201], v[18:21]
	v_mfma_f32_16x16x32_bf16 v[6:9], v[166:169], v[210:213], v[6:9]
	v_mfma_f32_16x16x32_bf16 v[2:5], v[174:177], v[210:213], v[2:5]
	s_setprio 0
	s_barrier
	s_add_i32 s10, 0, 0x18000
	v_add_u32_e32 v149, s10, v146
	s_add_i32 s11, 0, 0x1c000
	ds_read_b128 v[142:145], v149
	ds_read_b128 v[150:153], v149 offset:1024
	ds_read_b128 v[154:157], v149 offset:2048
	ds_read_b128 v[158:161], v149 offset:3072
	v_add_u32_e32 v149, s11, v146
	ds_read_b128 v[162:165], v149
	ds_read_b128 v[166:169], v149 offset:1024
	ds_read_b128 v[170:173], v149 offset:2048
	ds_read_b128 v[174:177], v149 offset:3072
	s_add_u32 s8, s60, 0x80000
	s_addc_u32 s9, s61, 0
	s_mov_b32 m0, s62
	v_lshl_add_u64 v[236:237], s[8:9], 0, v[136:137]
	ds_read_b128 v[178:181], v148 offset:32768
	ds_read_b128 v[182:185], v148 offset:33792
	ds_read_b128 v[186:189], v148 offset:34816
	ds_read_b128 v[190:193], v148 offset:35840
	ds_read_b128 v[194:197], v148 offset:36864
	ds_read_b128 v[198:201], v148 offset:37888
	ds_read_b128 v[206:209], v148 offset:38912
	ds_read_b128 v[210:213], v148 offset:39936
	global_load_lds_dwordx4 v[236:237], off
	v_lshl_add_u64 v[236:237], s[8:9], 0, v[132:133]
	s_mov_b32 m0, s63
	s_nop 0
	global_load_lds_dwordx4 v[236:237], off
	s_waitcnt vmcnt(8)
	s_waitcnt lgkmcnt(0)
	s_barrier
	s_setprio 1
	s_waitcnt lgkmcnt(0)
	v_mfma_f32_16x16x32_bf16 v[126:129], v[142:145], v[178:181], v[126:129]
	v_mfma_f32_16x16x32_bf16 v[122:125], v[154:157], v[178:181], v[122:125]
	v_mfma_f32_16x16x32_bf16 v[110:113], v[142:145], v[186:189], v[110:113]
	v_mfma_f32_16x16x32_bf16 v[106:109], v[154:157], v[186:189], v[106:109]
	v_mfma_f32_16x16x32_bf16 v[94:97], v[142:145], v[194:197], v[94:97]
	v_mfma_f32_16x16x32_bf16 v[90:93], v[154:157], v[194:197], v[90:93]
	v_mfma_f32_16x16x32_bf16 v[78:81], v[142:145], v[206:209], v[78:81]
	v_mfma_f32_16x16x32_bf16 v[74:77], v[154:157], v[206:209], v[74:77]
	v_mfma_f32_16x16x32_bf16 v[126:129], v[150:153], v[182:185], v[126:129]
	v_mfma_f32_16x16x32_bf16 v[122:125], v[158:161], v[182:185], v[122:125]
	v_mfma_f32_16x16x32_bf16 v[110:113], v[150:153], v[190:193], v[110:113]
	v_mfma_f32_16x16x32_bf16 v[106:109], v[158:161], v[190:193], v[106:109]
	v_mfma_f32_16x16x32_bf16 v[94:97], v[150:153], v[198:201], v[94:97]
	v_mfma_f32_16x16x32_bf16 v[90:93], v[158:161], v[198:201], v[90:93]
	v_mfma_f32_16x16x32_bf16 v[78:81], v[150:153], v[210:213], v[78:81]
	v_mfma_f32_16x16x32_bf16 v[74:77], v[158:161], v[210:213], v[74:77]
	s_setprio 0
	s_setprio 1
	v_mfma_f32_16x16x32_bf16 v[118:121], v[162:165], v[178:181], v[118:121]
	v_mfma_f32_16x16x32_bf16 v[114:117], v[170:173], v[178:181], v[114:117]
	v_mfma_f32_16x16x32_bf16 v[102:105], v[162:165], v[186:189], v[102:105]
	v_mfma_f32_16x16x32_bf16 v[98:101], v[170:173], v[186:189], v[98:101]
	v_mfma_f32_16x16x32_bf16 v[86:89], v[162:165], v[194:197], v[86:89]
	v_mfma_f32_16x16x32_bf16 v[82:85], v[170:173], v[194:197], v[82:85]
	v_mfma_f32_16x16x32_bf16 v[70:73], v[162:165], v[206:209], v[70:73]
	v_mfma_f32_16x16x32_bf16 v[66:69], v[170:173], v[206:209], v[66:69]
	v_mfma_f32_16x16x32_bf16 v[118:121], v[166:169], v[182:185], v[118:121]
	v_mfma_f32_16x16x32_bf16 v[114:117], v[174:177], v[182:185], v[114:117]
	v_mfma_f32_16x16x32_bf16 v[102:105], v[166:169], v[190:193], v[102:105]
	v_mfma_f32_16x16x32_bf16 v[98:101], v[174:177], v[190:193], v[98:101]
	v_mfma_f32_16x16x32_bf16 v[86:89], v[166:169], v[198:201], v[86:89]
	v_mfma_f32_16x16x32_bf16 v[82:85], v[174:177], v[198:201], v[82:85]
	v_mfma_f32_16x16x32_bf16 v[70:73], v[166:169], v[210:213], v[70:73]
	v_mfma_f32_16x16x32_bf16 v[66:69], v[174:177], v[210:213], v[66:69]
	s_setprio 0
	s_barrier
; #define PG8_STAGE2(bufoff, gbase, voff) do { _Pragma("unroll") for (int _i = 0; _i < 2; ++_i) \
;         __builtin_amdgcn_global_load_lds((const unsigned*)((const char*)(gbase) + (voff)[_i]), (LAS unsigned*)(lds + (bufoff) + ldsw + _i * 8192), 16, 0, 0); } while (0)
; #define PG8_LDA(dst, b, h) do { _Pragma("unroll") for (int m = 0; m < 4; ++m) _Pragma("unroll") for (int k = 0; k < 2; ++k) dst[m][k] = *(const LAS bf16x8*)(lds + PG8_SA(b, h) + aoff + m * 2048 + k * 1024); } while (0)
; #define PG8_MMA(ai, bj, At, Bt) do { __builtin_amdgcn_s_setprio(1); _Pragma("unroll") for (int m = 0; m < 4; ++m) _Pragma("unroll") for (int n = 0; n < 2; ++n) _Pragma("unroll") for (int k = 0; k < 2; ++k) \
;         acc[ai][bj][m][n] = __builtin_amdgcn_mfma_f32_16x16x32_bf16(Bt[n][k], At[m][k], acc[ai][bj][m][n], 0, 0, 0); __builtin_amdgcn_s_setprio(0); } while (0)
; #define PG8_WAIT_V(n) asm volatile("s_waitcnt vmcnt(" #n ")" ::: "memory")
; #define PG8_WAIT_L(n) asm volatile("s_waitcnt lgkmcnt(" #n ")" ::: "memory")
; #define PG8_BAR __builtin_amdgcn_s_barrier()
; #define PG8_SCHED __builtin_amdgcn_sched_barrier(0)
; template <class Epi>
; __device__ __forceinline__ void gemm_phase(LAS unsigned char* lds, const Sched& S, const Epi& E) {
;     ...
;             PG8_LDA(At, 1, 1); PG8_STAGE2(PG8_SB(1, 0), b3, voffB); PG8_STAGE2(PG8_SB(1, 1), b3 + hstep, voffB); PG8_STAGE2(PG8_SA(1, 0), a3, voffA);
;             PG8_WAIT_V(8); PG8_WAIT_L(0); PG8_BAR; PG8_MMA(1, 0, At, B0); PG8_MMA(1, 1, At, B1); PG8_BAR; PG8_SCHED;
;         }
	s_add_i32 s8, s10, s36
	v_lshl_add_u64 v[228:229], v[228:229], 0, s[22:23]
	s_mov_b32 m0, s8
	ds_read_b128 v[178:181], v148 offset:49152
	ds_read_b128 v[182:185], v148 offset:50176
	ds_read_b128 v[186:189], v148 offset:51200
	ds_read_b128 v[190:193], v148 offset:52224
	ds_read_b128 v[194:197], v148 offset:53248
	ds_read_b128 v[198:201], v148 offset:54272
	ds_read_b128 v[206:209], v148 offset:55296
	ds_read_b128 v[210:213], v148 offset:56320
	global_load_lds_dwordx4 v[228:229], off
	s_add_i32 m0, s8, 0x2000
	s_add_u32 s8, s58, 0x80080
	v_lshl_add_u64 v[228:229], v[230:231], 0, s[22:23]
	s_addc_u32 s9, s59, 0
	s_add_i32 s10, s11, s36
	global_load_lds_dwordx4 v[228:229], off
	v_lshl_add_u64 v[228:229], s[8:9], 0, v[134:135]
	s_mov_b32 m0, s10
	s_nop 0
	global_load_lds_dwordx4 v[228:229], off
	v_lshl_add_u64 v[228:229], s[8:9], 0, v[130:131]
	s_add_i32 m0, s10, 0x2000
	s_nop 0
	global_load_lds_dwordx4 v[228:229], off
	v_lshl_add_u64 v[228:229], v[232:233], 0, s[22:23]
	s_mov_b32 m0, s64
	s_nop 0
	global_load_lds_dwordx4 v[228:229], off
	v_lshl_add_u64 v[228:229], v[234:235], 0, s[22:23]
	s_mov_b32 m0, s65
	s_nop 0
	global_load_lds_dwordx4 v[228:229], off
	s_waitcnt vmcnt(8)
	s_waitcnt lgkmcnt(0)
	s_barrier
	s_setprio 1
	s_waitcnt lgkmcnt(0)
	v_mfma_f32_16x16x32_bf16 v[62:65], v[142:145], v[178:181], v[62:65]
	v_mfma_f32_16x16x32_bf16 v[58:61], v[154:157], v[178:181], v[58:61]
	v_mfma_f32_16x16x32_bf16 v[46:49], v[142:145], v[186:189], v[46:49]
	v_mfma_f32_16x16x32_bf16 v[42:45], v[154:157], v[186:189], v[42:45]
	v_mfma_f32_16x16x32_bf16 v[30:33], v[142:145], v[194:197], v[30:33]
	v_mfma_f32_16x16x32_bf16 v[26:29], v[154:157], v[194:197], v[26:29]
	v_mfma_f32_16x16x32_bf16 v[14:17], v[142:145], v[206:209], v[14:17]
	v_mfma_f32_16x16x32_bf16 v[10:13], v[154:157], v[206:209], v[10:13]
	v_mfma_f32_16x16x32_bf16 v[62:65], v[150:153], v[182:185], v[62:65]
	v_mfma_f32_16x16x32_bf16 v[58:61], v[158:161], v[182:185], v[58:61]
	v_mfma_f32_16x16x32_bf16 v[46:49], v[150:153], v[190:193], v[46:49]
	v_mfma_f32_16x16x32_bf16 v[42:45], v[158:161], v[190:193], v[42:45]
	v_mfma_f32_16x16x32_bf16 v[30:33], v[150:153], v[198:201], v[30:33]
	v_mfma_f32_16x16x32_bf16 v[26:29], v[158:161], v[198:201], v[26:29]
	v_mfma_f32_16x16x32_bf16 v[14:17], v[150:153], v[210:213], v[14:17]
	v_mfma_f32_16x16x32_bf16 v[10:13], v[158:161], v[210:213], v[10:13]
	s_setprio 0
	s_setprio 1
	v_mfma_f32_16x16x32_bf16 v[54:57], v[162:165], v[178:181], v[54:57]
	v_mfma_f32_16x16x32_bf16 v[50:53], v[170:173], v[178:181], v[50:53]
	v_mfma_f32_16x16x32_bf16 v[38:41], v[162:165], v[186:189], v[38:41]
	v_mfma_f32_16x16x32_bf16 v[34:37], v[170:173], v[186:189], v[34:37]
	v_mfma_f32_16x16x32_bf16 v[22:25], v[162:165], v[194:197], v[22:25]
	v_mfma_f32_16x16x32_bf16 v[18:21], v[170:173], v[194:197], v[18:21]
	v_mfma_f32_16x16x32_bf16 v[6:9], v[162:165], v[206:209], v[6:9]
	v_mfma_f32_16x16x32_bf16 v[2:5], v[170:173], v[206:209], v[2:5]
	v_mfma_f32_16x16x32_bf16 v[54:57], v[166:169], v[182:185], v[54:57]
	v_mfma_f32_16x16x32_bf16 v[50:53], v[174:177], v[182:185], v[50:53]
	v_mfma_f32_16x16x32_bf16 v[38:41], v[166:169], v[190:193], v[38:41]
	v_mfma_f32_16x16x32_bf16 v[34:37], v[174:177], v[190:193], v[34:37]
	v_mfma_f32_16x16x32_bf16 v[22:25], v[166:169], v[198:201], v[22:25]
	v_mfma_f32_16x16x32_bf16 v[18:21], v[174:177], v[198:201], v[18:21]
	v_mfma_f32_16x16x32_bf16 v[6:9], v[166:169], v[210:213], v[6:9]
	v_mfma_f32_16x16x32_bf16 v[2:5], v[174:177], v[210:213], v[2:5]
	s_setprio 0
	s_add_i32 s73, s73, 2
	s_add_u32 s56, s56, 0x100
	s_addc_u32 s57, s57, 0
	s_add_u32 s71, s71, 0x100
	s_addc_u32 s72, s72, 0
	s_cmp_gt_u32 s73, 29
	s_barrier
	s_cbranch_scc0 .LBB0_955
	s_and_b64 vcc, exec, s[46:47]
	s_cbranch_vccz .LBB0_958
	s_barrier

; #define PG8_STAGE2(bufoff, gbase, voff) do { _Pragma("unroll") for (int _i = 0; _i < 2; ++_i) \
;         __builtin_amdgcn_global_load_lds((const unsigned*)((const char*)(gbase) + (voff)[_i]), (LAS unsigned*)(lds + (bufoff) + ldsw + _i * 8192), 16, 0, 0); } while (0)
; #define PG8_LDA(dst, b, h) do { _Pragma("unroll") for (int m = 0; m < 4; ++m) _Pragma("unroll") for (int k = 0; k < 2; ++k) dst[m][k] = *(const LAS bf16x8*)(lds + PG8_SA(b, h) + aoff + m * 2048 + k * 1024); } while (0)
; #define PG8_LDB(dst, b, h) do { _Pragma("unroll") for (int n = 0; n < 2; ++n) _Pragma("unroll") for (int k = 0; k < 2; ++k) dst[n][k] = *(const LAS bf16x8*)(lds + PG8_SB(b, h) + boff + n * 2048 + k * 1024); } while (0)
; #define PG8_MMA(ai, bj, At, Bt) do { __builtin_amdgcn_s_setprio(1); _Pragma("unroll") for (int m = 0; m < 4; ++m) _Pragma("unroll") for (int n = 0; n < 2; ++n) _Pragma("unroll") for (int k = 0; k < 2; ++k) \
;         acc[ai][bj][m][n] = __builtin_amdgcn_mfma_f32_16x16x32_bf16(Bt[n][k], At[m][k], acc[ai][bj][m][n], 0, 0, 0); __builtin_amdgcn_s_setprio(0); } while (0)
; #define PG8_WAIT_V(n) asm volatile("s_waitcnt vmcnt(" #n ")" ::: "memory")
; #define PG8_WAIT_L(n) asm volatile("s_waitcnt lgkmcnt(" #n ")" ::: "memory")
; #define PG8_BAR __builtin_amdgcn_s_barrier()
; #define PG8_SCHED __builtin_amdgcn_sched_barrier(0)
; template <class Epi>
; __device__ __forceinline__ void gemm_phase(LAS unsigned char* lds, const Sched& S, const Epi& E) {
;     ...
;             const bool last = (t == nt - 2);
;             const char* a1 = cA + (size_t)(t + 1) * kstep;
;             const char* a2 = last ? nA : cA + (size_t)(t + 2) * kstep; const char* b2 = last ? nB : cB + (size_t)(t + 2) * kstep;
;             const char* a3 = a2 + kstep; const char* b3 = b2 + kstep;
;             PG8_LDB(B0, 0, 0); PG8_LDB(B1, 0, 1); PG8_SCHED; PG8_LDA(At, 0, 0); PG8_STAGE2(PG8_SA(1, 1), a1 + hstep, voffA);
;             PG8_WAIT_V(8); PG8_WAIT_L(0); PG8_BAR; PG8_MMA(0, 0, At, B0); PG8_MMA(0, 1, At, B1); PG8_BAR; PG8_SCHED;
;             PG8_LDA(At, 0, 1); PG8_STAGE2(PG8_SB(0, 0), b2, voffB); PG8_STAGE2(PG8_SB(0, 1), b2 + hstep, voffB); PG8_STAGE2(PG8_SA(0, 0), a2, voffA);
;             PG8_WAIT_V(8); PG8_WAIT_L(0); PG8_BAR; PG8_MMA(1, 0, At, B0); PG8_MMA(1, 1, At, B1); PG8_BAR; PG8_SCHED;
.LBB0_1029:
	s_add_u32 s8, s70, s72
	s_addc_u32 s9, s71, s73
	s_add_u32 s8, s8, 0x100
	s_addc_u32 s9, s9, 0
	s_add_u32 s10, s39, s72
	s_addc_u32 s11, s42, s73
	s_add_i32 s12, 0, 0x10000
	s_cmpk_eq_i32 s72, 0x3f00
	s_cselect_b32 s81, s43, s9
	s_cselect_b32 s80, s65, s8
	v_add_u32_e32 v1, s12, v146
	s_cselect_b32 s77, s63, s11
	s_cselect_b32 s76, vcc_lo, s10
	s_add_i32 s10, 0, 0x14000
	ds_read_b128 v[148:151], v1
	ds_read_b128 v[152:155], v1 offset:1024
	ds_read_b128 v[156:159], v1 offset:2048
	ds_read_b128 v[160:163], v1 offset:3072
	v_add_u32_e32 v1, s10, v146
	ds_read_b128 v[164:167], v1
	ds_read_b128 v[168:171], v1 offset:1024
	ds_read_b128 v[172:175], v1 offset:2048
	ds_read_b128 v[176:179], v1 offset:3072
	v_lshl_add_u64 v[200:201], v[2:3], 0, s[72:73]
	s_add_i32 m0, s82, 0xc000
	ds_read_b128 v[180:183], v147
	ds_read_b128 v[184:187], v147 offset:1024
	ds_read_b128 v[192:195], v147 offset:2048
	ds_read_b128 v[196:199], v147 offset:3072
	ds_read_b128 v[206:209], v147 offset:4096
	ds_read_b128 v[210:213], v147 offset:5120
	ds_read_b128 v[228:231], v147 offset:6144
	ds_read_b128 v[232:235], v147 offset:7168
	global_load_lds_dwordx4 v[200:201], off
	v_lshl_add_u64 v[200:201], v[144:145], 0, s[72:73]
	s_add_i32 m0, s82, 0xe000
	s_nop 0
	global_load_lds_dwordx4 v[200:201], off
	s_waitcnt vmcnt(8)
	s_waitcnt lgkmcnt(0)
	s_barrier
	s_setprio 1
	s_waitcnt lgkmcnt(0)
	v_mfma_f32_16x16x32_bf16 v[128:131], v[148:151], v[180:183], v[128:131]
	v_mfma_f32_16x16x32_bf16 v[124:127], v[156:159], v[180:183], v[124:127]
	v_mfma_f32_16x16x32_bf16 v[112:115], v[148:151], v[192:195], v[112:115]
	v_mfma_f32_16x16x32_bf16 v[108:111], v[156:159], v[192:195], v[108:111]
	v_mfma_f32_16x16x32_bf16 v[96:99], v[148:151], v[206:209], v[96:99]
	v_mfma_f32_16x16x32_bf16 v[92:95], v[156:159], v[206:209], v[92:95]
	v_mfma_f32_16x16x32_bf16 v[80:83], v[148:151], v[228:231], v[80:83]
	v_mfma_f32_16x16x32_bf16 v[76:79], v[156:159], v[228:231], v[76:79]
	v_mfma_f32_16x16x32_bf16 v[128:131], v[152:155], v[184:187], v[128:131]
	v_mfma_f32_16x16x32_bf16 v[124:127], v[160:163], v[184:187], v[124:127]
	v_mfma_f32_16x16x32_bf16 v[112:115], v[152:155], v[196:199], v[112:115]
	v_mfma_f32_16x16x32_bf16 v[108:111], v[160:163], v[196:199], v[108:111]
	v_mfma_f32_16x16x32_bf16 v[96:99], v[152:155], v[210:213], v[96:99]
	v_mfma_f32_16x16x32_bf16 v[92:95], v[160:163], v[210:213], v[92:95]
	v_mfma_f32_16x16x32_bf16 v[80:83], v[152:155], v[232:235], v[80:83]
	v_mfma_f32_16x16x32_bf16 v[76:79], v[160:163], v[232:235], v[76:79]
	s_setprio 0
	s_setprio 1
	v_mfma_f32_16x16x32_bf16 v[120:123], v[164:167], v[180:183], v[120:123]
	v_mfma_f32_16x16x32_bf16 v[116:119], v[172:175], v[180:183], v[116:119]
	v_mfma_f32_16x16x32_bf16 v[104:107], v[164:167], v[192:195], v[104:107]
	v_mfma_f32_16x16x32_bf16 v[100:103], v[172:175], v[192:195], v[100:103]
	v_mfma_f32_16x16x32_bf16 v[88:91], v[164:167], v[206:209], v[88:91]
	v_mfma_f32_16x16x32_bf16 v[84:87], v[172:175], v[206:209], v[84:87]
	v_mfma_f32_16x16x32_bf16 v[72:75], v[164:167], v[228:231], v[72:75]
	v_mfma_f32_16x16x32_bf16 v[68:71], v[172:175], v[228:231], v[68:71]
	v_mfma_f32_16x16x32_bf16 v[120:123], v[168:171], v[184:187], v[120:123]
	v_mfma_f32_16x16x32_bf16 v[116:119], v[176:179], v[184:187], v[116:119]
	v_mfma_f32_16x16x32_bf16 v[104:107], v[168:171], v[196:199], v[104:107]
	v_mfma_f32_16x16x32_bf16 v[100:103], v[176:179], v[196:199], v[100:103]
	v_mfma_f32_16x16x32_bf16 v[88:91], v[168:171], v[210:213], v[88:91]
	v_mfma_f32_16x16x32_bf16 v[84:87], v[176:179], v[210:213], v[84:87]
	v_mfma_f32_16x16x32_bf16 v[72:75], v[168:171], v[232:235], v[72:75]
	v_mfma_f32_16x16x32_bf16 v[68:71], v[176:179], v[232:235], v[68:71]
	s_setprio 0
	s_barrier
	s_add_i32 s8, s12, s7
	v_lshl_add_u64 v[200:201], s[76:77], 0, v[136:137]
	s_mov_b32 m0, s8
	ds_read_b128 v[180:183], v147 offset:16384
	ds_read_b128 v[184:187], v147 offset:17408
	ds_read_b128 v[192:195], v147 offset:18432
	ds_read_b128 v[196:199], v147 offset:19456
	ds_read_b128 v[206:209], v147 offset:20480
	ds_read_b128 v[210:213], v147 offset:21504
	ds_read_b128 v[228:231], v147 offset:22528
	ds_read_b128 v[232:235], v147 offset:23552
	global_load_lds_dwordx4 v[200:201], off
	s_add_i32 m0, s8, 0x2000
	s_add_u32 s8, s76, 0x200000
	v_lshl_add_u64 v[236:237], s[76:77], 0, v[132:133]
	s_addc_u32 s9, s77, 0
	s_add_i32 s10, s10, s7
	global_load_lds_dwordx4 v[236:237], off
	v_lshl_add_u64 v[238:239], s[8:9], 0, v[136:137]
	s_mov_b32 m0, s10
	v_lshl_add_u64 v[240:241], s[80:81], 0, v[134:135]
	global_load_lds_dwordx4 v[238:239], off
	v_lshl_add_u64 v[238:239], s[8:9], 0, v[132:133]
	s_add_i32 m0, s10, 0x2000
	s_nop 0
	global_load_lds_dwordx4 v[238:239], off
	v_lshl_add_u64 v[238:239], s[80:81], 0, v[138:139]
	s_mov_b32 m0, s82
	s_nop 0
	global_load_lds_dwordx4 v[238:239], off
	s_mov_b32 m0, s83
	s_nop 0
	global_load_lds_dwordx4 v[240:241], off
	s_waitcnt vmcnt(8)
	s_waitcnt lgkmcnt(0)
	s_barrier
; #define PG8_STAGE2(bufoff, gbase, voff) do { _Pragma("unroll") for (int _i = 0; _i < 2; ++_i) \
;         __builtin_amdgcn_global_load_lds((const unsigned*)((const char*)(gbase) + (voff)[_i]), (LAS unsigned*)(lds + (bufoff) + ldsw + _i * 8192), 16, 0, 0); } while (0)
; #define PG8_LDA(dst, b, h) do { _Pragma("unroll") for (int m = 0; m < 4; ++m) _Pragma("unroll") for (int k = 0; k < 2; ++k) dst[m][k] = *(const LAS bf16x8*)(lds + PG8_SA(b, h) + aoff + m * 2048 + k * 1024); } while (0)
; #define PG8_LDB(dst, b, h) do { _Pragma("unroll") for (int n = 0; n < 2; ++n) _Pragma("unroll") for (int k = 0; k < 2; ++k) dst[n][k] = *(const LAS bf16x8*)(lds + PG8_SB(b, h) + boff + n * 2048 + k * 1024); } while (0)
; #define PG8_MMA(ai, bj, At, Bt) do { __builtin_amdgcn_s_setprio(1); _Pragma("unroll") for (int m = 0; m < 4; ++m) _Pragma("unroll") for (int n = 0; n < 2; ++n) _Pragma("unroll") for (int k = 0; k < 2; ++k) \
;         acc[ai][bj][m][n] = __builtin_amdgcn_mfma_f32_16x16x32_bf16(Bt[n][k], At[m][k], acc[ai][bj][m][n], 0, 0, 0); __builtin_amdgcn_s_setprio(0); } while (0)
; #define PG8_WAIT_V(n) asm volatile("s_waitcnt vmcnt(" #n ")" ::: "memory")
; #define PG8_WAIT_L(n) asm volatile("s_waitcnt lgkmcnt(" #n ")" ::: "memory")
; #define PG8_BAR __builtin_amdgcn_s_barrier()
; #define PG8_SCHED __builtin_amdgcn_sched_barrier(0)
; template <class Epi>
; __device__ __forceinline__ void gemm_phase(LAS unsigned char* lds, const Sched& S, const Epi& E) {
;     ...
;             PG8_WAIT_V(8); PG8_WAIT_L(0); PG8_BAR; PG8_MMA(1, 0, At, B0); PG8_MMA(1, 1, At, B1); PG8_BAR; PG8_SCHED;
;             PG8_LDB(B0, 1, 0); PG8_LDB(B1, 1, 1); PG8_SCHED; PG8_LDA(At, 1, 0); PG8_STAGE2(PG8_SA(0, 1), a2 + hstep, voffA);
;             PG8_WAIT_V(8); PG8_WAIT_L(0); PG8_BAR; PG8_MMA(0, 0, At, B0); PG8_MMA(0, 1, At, B1); PG8_BAR; PG8_SCHED;
;             PG8_LDA(At, 1, 1); PG8_STAGE2(PG8_SB(1, 0), b3, voffB); PG8_STAGE2(PG8_SB(1, 1), b3 + hstep, voffB); PG8_STAGE2(PG8_SA(1, 0), a3, voffA);
	s_setprio 1
	s_waitcnt lgkmcnt(0)
	v_mfma_f32_16x16x32_bf16 v[64:67], v[148:151], v[180:183], v[64:67]
	v_mfma_f32_16x16x32_bf16 v[60:63], v[156:159], v[180:183], v[60:63]
	v_mfma_f32_16x16x32_bf16 v[48:51], v[148:151], v[192:195], v[48:51]
	v_mfma_f32_16x16x32_bf16 v[44:47], v[156:159], v[192:195], v[44:47]
	v_mfma_f32_16x16x32_bf16 v[32:35], v[148:151], v[206:209], v[32:35]
	v_mfma_f32_16x16x32_bf16 v[28:31], v[156:159], v[206:209], v[28:31]
	v_mfma_f32_16x16x32_bf16 v[16:19], v[148:151], v[228:231], v[16:19]
	v_mfma_f32_16x16x32_bf16 v[12:15], v[156:159], v[228:231], v[12:15]
	v_mfma_f32_16x16x32_bf16 v[64:67], v[152:155], v[184:187], v[64:67]
	v_mfma_f32_16x16x32_bf16 v[60:63], v[160:163], v[184:187], v[60:63]
	v_mfma_f32_16x16x32_bf16 v[48:51], v[152:155], v[196:199], v[48:51]
	v_mfma_f32_16x16x32_bf16 v[44:47], v[160:163], v[196:199], v[44:47]
	v_mfma_f32_16x16x32_bf16 v[32:35], v[152:155], v[210:213], v[32:35]
	v_mfma_f32_16x16x32_bf16 v[28:31], v[160:163], v[210:213], v[28:31]
	v_mfma_f32_16x16x32_bf16 v[16:19], v[152:155], v[232:235], v[16:19]
	v_mfma_f32_16x16x32_bf16 v[12:15], v[160:163], v[232:235], v[12:15]
	s_setprio 0
	s_setprio 1
	v_mfma_f32_16x16x32_bf16 v[56:59], v[164:167], v[180:183], v[56:59]
	v_mfma_f32_16x16x32_bf16 v[52:55], v[172:175], v[180:183], v[52:55]
	v_mfma_f32_16x16x32_bf16 v[40:43], v[164:167], v[192:195], v[40:43]
	v_mfma_f32_16x16x32_bf16 v[36:39], v[172:175], v[192:195], v[36:39]
	v_mfma_f32_16x16x32_bf16 v[24:27], v[164:167], v[206:209], v[24:27]
	v_mfma_f32_16x16x32_bf16 v[20:23], v[172:175], v[206:209], v[20:23]
	v_mfma_f32_16x16x32_bf16 v[8:11], v[164:167], v[228:231], v[8:11]
	v_mfma_f32_16x16x32_bf16 v[4:7], v[172:175], v[228:231], v[4:7]
	v_mfma_f32_16x16x32_bf16 v[56:59], v[168:171], v[184:187], v[56:59]
	v_mfma_f32_16x16x32_bf16 v[52:55], v[176:179], v[184:187], v[52:55]
	v_mfma_f32_16x16x32_bf16 v[40:43], v[168:171], v[196:199], v[40:43]
	v_mfma_f32_16x16x32_bf16 v[36:39], v[176:179], v[196:199], v[36:39]
	v_mfma_f32_16x16x32_bf16 v[24:27], v[168:171], v[210:213], v[24:27]
	v_mfma_f32_16x16x32_bf16 v[20:23], v[176:179], v[210:213], v[20:23]
	v_mfma_f32_16x16x32_bf16 v[8:11], v[168:171], v[232:235], v[8:11]
	v_mfma_f32_16x16x32_bf16 v[4:7], v[176:179], v[232:235], v[4:7]
	s_setprio 0
	s_barrier
	s_add_i32 s10, 0, 0x18000
	v_add_u32_e32 v1, s10, v146
	s_add_i32 s11, 0, 0x1c000
	ds_read_b128 v[148:151], v1
	ds_read_b128 v[152:155], v1 offset:1024
	ds_read_b128 v[156:159], v1 offset:2048
	ds_read_b128 v[160:163], v1 offset:3072
	v_add_u32_e32 v1, s11, v146
	ds_read_b128 v[164:167], v1
	ds_read_b128 v[168:171], v1 offset:1024
	ds_read_b128 v[172:175], v1 offset:2048
	ds_read_b128 v[176:179], v1 offset:3072
	s_add_u32 s8, s80, 0x200000
	s_addc_u32 s9, s81, 0
	s_mov_b32 m0, s84
	v_lshl_add_u64 v[242:243], s[8:9], 0, v[138:139]
	ds_read_b128 v[180:183], v147 offset:32768
	ds_read_b128 v[184:187], v147 offset:33792
	ds_read_b128 v[192:195], v147 offset:34816
	ds_read_b128 v[196:199], v147 offset:35840
	ds_read_b128 v[206:209], v147 offset:36864
	ds_read_b128 v[210:213], v147 offset:37888
	ds_read_b128 v[228:231], v147 offset:38912
	ds_read_b128 v[232:235], v147 offset:39936
	global_load_lds_dwordx4 v[242:243], off
	v_lshl_add_u64 v[242:243], s[8:9], 0, v[134:135]
	s_mov_b32 m0, s85
	s_nop 0
	global_load_lds_dwordx4 v[242:243], off
	s_waitcnt vmcnt(8)
	s_waitcnt lgkmcnt(0)
	s_barrier
	s_setprio 1
	s_waitcnt lgkmcnt(0)
	v_mfma_f32_16x16x32_bf16 v[128:131], v[148:151], v[180:183], v[128:131]
	v_mfma_f32_16x16x32_bf16 v[124:127], v[156:159], v[180:183], v[124:127]
	v_mfma_f32_16x16x32_bf16 v[112:115], v[148:151], v[192:195], v[112:115]
	v_mfma_f32_16x16x32_bf16 v[108:111], v[156:159], v[192:195], v[108:111]
	v_mfma_f32_16x16x32_bf16 v[96:99], v[148:151], v[206:209], v[96:99]
	v_mfma_f32_16x16x32_bf16 v[92:95], v[156:159], v[206:209], v[92:95]
	v_mfma_f32_16x16x32_bf16 v[80:83], v[148:151], v[228:231], v[80:83]
	v_mfma_f32_16x16x32_bf16 v[76:79], v[156:159], v[228:231], v[76:79]
	v_mfma_f32_16x16x32_bf16 v[128:131], v[152:155], v[184:187], v[128:131]
	v_mfma_f32_16x16x32_bf16 v[124:127], v[160:163], v[184:187], v[124:127]
	v_mfma_f32_16x16x32_bf16 v[112:115], v[152:155], v[196:199], v[112:115]
	v_mfma_f32_16x16x32_bf16 v[108:111], v[160:163], v[196:199], v[108:111]
	v_mfma_f32_16x16x32_bf16 v[96:99], v[152:155], v[210:213], v[96:99]
	v_mfma_f32_16x16x32_bf16 v[92:95], v[160:163], v[210:213], v[92:95]
	v_mfma_f32_16x16x32_bf16 v[80:83], v[152:155], v[232:235], v[80:83]
	v_mfma_f32_16x16x32_bf16 v[76:79], v[160:163], v[232:235], v[76:79]
	s_setprio 0
	s_setprio 1
	v_mfma_f32_16x16x32_bf16 v[120:123], v[164:167], v[180:183], v[120:123]
	v_mfma_f32_16x16x32_bf16 v[116:119], v[172:175], v[180:183], v[116:119]
	v_mfma_f32_16x16x32_bf16 v[104:107], v[164:167], v[192:195], v[104:107]
	v_mfma_f32_16x16x32_bf16 v[100:103], v[172:175], v[192:195], v[100:103]
	v_mfma_f32_16x16x32_bf16 v[88:91], v[164:167], v[206:209], v[88:91]
	v_mfma_f32_16x16x32_bf16 v[84:87], v[172:175], v[206:209], v[84:87]
	v_mfma_f32_16x16x32_bf16 v[72:75], v[164:167], v[228:231], v[72:75]
	v_mfma_f32_16x16x32_bf16 v[68:71], v[172:175], v[228:231], v[68:71]
	v_mfma_f32_16x16x32_bf16 v[120:123], v[168:171], v[184:187], v[120:123]
	v_mfma_f32_16x16x32_bf16 v[116:119], v[176:179], v[184:187], v[116:119]
	v_mfma_f32_16x16x32_bf16 v[104:107], v[168:171], v[196:199], v[104:107]
	v_mfma_f32_16x16x32_bf16 v[100:103], v[176:179], v[196:199], v[100:103]
	v_mfma_f32_16x16x32_bf16 v[88:91], v[168:171], v[210:213], v[88:91]
	v_mfma_f32_16x16x32_bf16 v[84:87], v[176:179], v[210:213], v[84:87]
	v_mfma_f32_16x16x32_bf16 v[72:75], v[168:171], v[232:235], v[72:75]
	v_mfma_f32_16x16x32_bf16 v[68:71], v[176:179], v[232:235], v[68:71]
	s_setprio 0
	s_barrier
; #define PG8_STAGE2(bufoff, gbase, voff) do { _Pragma("unroll") for (int _i = 0; _i < 2; ++_i) \
;         __builtin_amdgcn_global_load_lds((const unsigned*)((const char*)(gbase) + (voff)[_i]), (LAS unsigned*)(lds + (bufoff) + ldsw + _i * 8192), 16, 0, 0); } while (0)
; #define PG8_LDA(dst, b, h) do { _Pragma("unroll") for (int m = 0; m < 4; ++m) _Pragma("unroll") for (int k = 0; k < 2; ++k) dst[m][k] = *(const LAS bf16x8*)(lds + PG8_SA(b, h) + aoff + m * 2048 + k * 1024); } while (0)
; #define PG8_MMA(ai, bj, At, Bt) do { __builtin_amdgcn_s_setprio(1); _Pragma("unroll") for (int m = 0; m < 4; ++m) _Pragma("unroll") for (int n = 0; n < 2; ++n) _Pragma("unroll") for (int k = 0; k < 2; ++k) \
;         acc[ai][bj][m][n] = __builtin_amdgcn_mfma_f32_16x16x32_bf16(Bt[n][k], At[m][k], acc[ai][bj][m][n], 0, 0, 0); __builtin_amdgcn_s_setprio(0); } while (0)
; #define PG8_WAIT_V(n) asm volatile("s_waitcnt vmcnt(" #n ")" ::: "memory")
; #define PG8_WAIT_L(n) asm volatile("s_waitcnt lgkmcnt(" #n ")" ::: "memory")
; #define PG8_BAR __builtin_amdgcn_s_barrier()
; #define PG8_SCHED __builtin_amdgcn_sched_barrier(0)
; template <class Epi>
; __device__ __forceinline__ void gemm_phase(LAS unsigned char* lds, const Sched& S, const Epi& E) {
;     ...
;             PG8_LDA(At, 1, 1); PG8_STAGE2(PG8_SB(1, 0), b3, voffB); PG8_STAGE2(PG8_SB(1, 1), b3 + hstep, voffB); PG8_STAGE2(PG8_SA(1, 0), a3, voffA);
;             PG8_WAIT_V(8); PG8_WAIT_L(0); PG8_BAR; PG8_MMA(1, 0, At, B0); PG8_MMA(1, 1, At, B1); PG8_BAR; PG8_SCHED;
;         }
	s_add_i32 s8, s10, s7
	v_lshl_add_u64 v[200:201], v[200:201], 0, s[22:23]
	s_mov_b32 m0, s8
	ds_read_b128 v[180:183], v147 offset:49152
	ds_read_b128 v[184:187], v147 offset:50176
	ds_read_b128 v[192:195], v147 offset:51200
	ds_read_b128 v[196:199], v147 offset:52224
	ds_read_b128 v[206:209], v147 offset:53248
	ds_read_b128 v[210:213], v147 offset:54272
	ds_read_b128 v[228:231], v147 offset:55296
	ds_read_b128 v[232:235], v147 offset:56320
	global_load_lds_dwordx4 v[200:201], off
	s_add_i32 m0, s8, 0x2000
	s_add_u32 s8, s76, 0x200080
	v_lshl_add_u64 v[200:201], v[236:237], 0, s[22:23]
	s_addc_u32 s9, s77, 0
	s_add_i32 s10, s11, s7
	global_load_lds_dwordx4 v[200:201], off
	v_lshl_add_u64 v[200:201], s[8:9], 0, v[136:137]
	s_mov_b32 m0, s10
	s_nop 0
	global_load_lds_dwordx4 v[200:201], off
	v_lshl_add_u64 v[200:201], s[8:9], 0, v[132:133]
	s_add_i32 m0, s10, 0x2000
	s_nop 0
	global_load_lds_dwordx4 v[200:201], off
	v_lshl_add_u64 v[200:201], v[238:239], 0, s[22:23]
	s_mov_b32 m0, s87
	s_nop 0
	global_load_lds_dwordx4 v[200:201], off
	v_lshl_add_u64 v[200:201], v[240:241], 0, s[22:23]
	s_mov_b32 m0, s88
	s_nop 0
	global_load_lds_dwordx4 v[200:201], off
	s_waitcnt vmcnt(8)
	s_waitcnt lgkmcnt(0)
	s_barrier
	s_setprio 1
	s_waitcnt lgkmcnt(0)
	v_mfma_f32_16x16x32_bf16 v[64:67], v[148:151], v[180:183], v[64:67]
	v_mfma_f32_16x16x32_bf16 v[60:63], v[156:159], v[180:183], v[60:63]
	v_mfma_f32_16x16x32_bf16 v[48:51], v[148:151], v[192:195], v[48:51]
	v_mfma_f32_16x16x32_bf16 v[44:47], v[156:159], v[192:195], v[44:47]
	v_mfma_f32_16x16x32_bf16 v[32:35], v[148:151], v[206:209], v[32:35]
	v_mfma_f32_16x16x32_bf16 v[28:31], v[156:159], v[206:209], v[28:31]
	v_mfma_f32_16x16x32_bf16 v[16:19], v[148:151], v[228:231], v[16:19]
	v_mfma_f32_16x16x32_bf16 v[12:15], v[156:159], v[228:231], v[12:15]
	v_mfma_f32_16x16x32_bf16 v[64:67], v[152:155], v[184:187], v[64:67]
	v_mfma_f32_16x16x32_bf16 v[60:63], v[160:163], v[184:187], v[60:63]
	v_mfma_f32_16x16x32_bf16 v[48:51], v[152:155], v[196:199], v[48:51]
	v_mfma_f32_16x16x32_bf16 v[44:47], v[160:163], v[196:199], v[44:47]
	v_mfma_f32_16x16x32_bf16 v[32:35], v[152:155], v[210:213], v[32:35]
	v_mfma_f32_16x16x32_bf16 v[28:31], v[160:163], v[210:213], v[28:31]
	v_mfma_f32_16x16x32_bf16 v[16:19], v[152:155], v[232:235], v[16:19]
	v_mfma_f32_16x16x32_bf16 v[12:15], v[160:163], v[232:235], v[12:15]
	s_setprio 0
	s_setprio 1
	v_mfma_f32_16x16x32_bf16 v[56:59], v[164:167], v[180:183], v[56:59]
	v_mfma_f32_16x16x32_bf16 v[52:55], v[172:175], v[180:183], v[52:55]
	v_mfma_f32_16x16x32_bf16 v[40:43], v[164:167], v[192:195], v[40:43]
	v_mfma_f32_16x16x32_bf16 v[36:39], v[172:175], v[192:195], v[36:39]
	v_mfma_f32_16x16x32_bf16 v[24:27], v[164:167], v[206:209], v[24:27]
	v_mfma_f32_16x16x32_bf16 v[20:23], v[172:175], v[206:209], v[20:23]
	v_mfma_f32_16x16x32_bf16 v[8:11], v[164:167], v[228:231], v[8:11]
	v_mfma_f32_16x16x32_bf16 v[4:7], v[172:175], v[228:231], v[4:7]
	v_mfma_f32_16x16x32_bf16 v[56:59], v[168:171], v[184:187], v[56:59]
	v_mfma_f32_16x16x32_bf16 v[52:55], v[176:179], v[184:187], v[52:55]
	v_mfma_f32_16x16x32_bf16 v[40:43], v[168:171], v[196:199], v[40:43]
	v_mfma_f32_16x16x32_bf16 v[36:39], v[176:179], v[196:199], v[36:39]
	v_mfma_f32_16x16x32_bf16 v[24:27], v[168:171], v[210:213], v[24:27]
	v_mfma_f32_16x16x32_bf16 v[20:23], v[176:179], v[210:213], v[20:23]
	v_mfma_f32_16x16x32_bf16 v[8:11], v[168:171], v[232:235], v[8:11]
	v_mfma_f32_16x16x32_bf16 v[4:7], v[176:179], v[232:235], v[4:7]
	s_setprio 0
	s_add_i32 vcc_hi, vcc_hi, 2
	s_add_u32 s72, s72, 0x100
	s_addc_u32 s73, s73, 0
	s_cmpk_gt_u32 vcc_hi, 0x7d
	s_barrier
	s_cbranch_scc0 .LBB0_1029
	s_and_b64 vcc, exec, s[60:61]
	s_cbranch_vccz .LBB0_1032
	s_barrier

; #define PG8_STAGE2(bufoff, gbase, voff) do { _Pragma("unroll") for (int _i = 0; _i < 2; ++_i) \
;         __builtin_amdgcn_global_load_lds((const unsigned*)((const char*)(gbase) + (voff)[_i]), (LAS unsigned*)(lds + (bufoff) + ldsw + _i * 8192), 16, 0, 0); } while (0)
; #define PG8_LDA(dst, b, h) do { _Pragma("unroll") for (int m = 0; m < 4; ++m) _Pragma("unroll") for (int k = 0; k < 2; ++k) dst[m][k] = *(const LAS bf16x8*)(lds + PG8_SA(b, h) + aoff + m * 2048 + k * 1024); } while (0)
; #define PG8_LDB(dst, b, h) do { _Pragma("unroll") for (int n = 0; n < 2; ++n) _Pragma("unroll") for (int k = 0; k < 2; ++k) dst[n][k] = *(const LAS bf16x8*)(lds + PG8_SB(b, h) + boff + n * 2048 + k * 1024); } while (0)
; #define PG8_MMA(ai, bj, At, Bt) do { __builtin_amdgcn_s_setprio(1); _Pragma("unroll") for (int m = 0; m < 4; ++m) _Pragma("unroll") for (int n = 0; n < 2; ++n) _Pragma("unroll") for (int k = 0; k < 2; ++k) \
;         acc[ai][bj][m][n] = __builtin_amdgcn_mfma_f32_16x16x32_bf16(Bt[n][k], At[m][k], acc[ai][bj][m][n], 0, 0, 0); __builtin_amdgcn_s_setprio(0); } while (0)
; #define PG8_WAIT_V(n) asm volatile("s_waitcnt vmcnt(" #n ")" ::: "memory")
; #define PG8_WAIT_L(n) asm volatile("s_waitcnt lgkmcnt(" #n ")" ::: "memory")
; #define PG8_BAR __builtin_amdgcn_s_barrier()
; #define PG8_SCHED __builtin_amdgcn_sched_barrier(0)
; template <class Epi>
; __device__ __forceinline__ void gemm_phase(LAS unsigned char* lds, const Sched& S, const Epi& E) {
;     ...
;             const bool last = (t == nt - 2);
;             const char* a1 = cA + (size_t)(t + 1) * kstep;
;             const char* a2 = last ? nA : cA + (size_t)(t + 2) * kstep; const char* b2 = last ? nB : cB + (size_t)(t + 2) * kstep;
;             const char* a3 = a2 + kstep; const char* b3 = b2 + kstep;
;             PG8_LDB(B0, 0, 0); PG8_LDB(B1, 0, 1); PG8_SCHED; PG8_LDA(At, 0, 0); PG8_STAGE2(PG8_SA(1, 1), a1 + hstep, voffA);
;             PG8_WAIT_V(8); PG8_WAIT_L(0); PG8_BAR; PG8_MMA(0, 0, At, B0); PG8_MMA(0, 1, At, B1); PG8_BAR; PG8_SCHED;
;             PG8_LDA(At, 0, 1); PG8_STAGE2(PG8_SB(0, 0), b2, voffB); PG8_STAGE2(PG8_SB(0, 1), b2 + hstep, voffB); PG8_STAGE2(PG8_SA(0, 0), a2, voffA);
;             PG8_WAIT_V(8); PG8_WAIT_L(0); PG8_BAR; PG8_MMA(1, 0, At, B0); PG8_MMA(1, 1, At, B1); PG8_BAR; PG8_SCHED;
.LBB0_1080:
	s_add_u32 s8, s80, s84
	s_addc_u32 s9, s81, s85
	s_add_u32 s8, s8, 0x100
	s_addc_u32 s9, s9, 0
	s_add_u32 s10, s39, s84
	s_addc_u32 s11, s42, s85
	s_add_i32 s12, 0, 0x10000
	s_cmpk_eq_i32 s84, 0x3f00
	s_cselect_b32 s89, s43, s9
	s_cselect_b32 s88, s71, s8
	v_add_u32_e32 v1, s12, v146
	s_cselect_b32 s87, s69, s11
	s_cselect_b32 s86, vcc_lo, s10
	s_add_i32 s10, 0, 0x14000
	ds_read_b128 v[148:151], v1
	ds_read_b128 v[152:155], v1 offset:1024
	ds_read_b128 v[156:159], v1 offset:2048
	ds_read_b128 v[160:163], v1 offset:3072
	v_add_u32_e32 v1, s10, v146
	ds_read_b128 v[164:167], v1
	ds_read_b128 v[168:171], v1 offset:1024
	ds_read_b128 v[172:175], v1 offset:2048
	ds_read_b128 v[176:179], v1 offset:3072
	v_lshl_add_u64 v[200:201], v[2:3], 0, s[84:85]
	s_add_i32 m0, s7, 0xc000
	ds_read_b128 v[180:183], v147
	ds_read_b128 v[184:187], v147 offset:1024
	ds_read_b128 v[188:191], v147 offset:2048
	ds_read_b128 v[192:195], v147 offset:3072
	ds_read_b128 v[196:199], v147 offset:4096
	ds_read_b128 v[206:209], v147 offset:5120
	ds_read_b128 v[210:213], v147 offset:6144
	ds_read_b128 v[230:233], v147 offset:7168
	global_load_lds_dwordx4 v[200:201], off
	v_lshl_add_u64 v[200:201], v[144:145], 0, s[84:85]
	s_add_i32 m0, s7, 0xe000
	s_nop 0
	global_load_lds_dwordx4 v[200:201], off
	s_waitcnt vmcnt(8)
	s_waitcnt lgkmcnt(0)
	s_barrier
	s_setprio 1
	s_waitcnt lgkmcnt(0)
	v_mfma_f32_16x16x32_bf16 v[128:131], v[148:151], v[180:183], v[128:131]
	v_mfma_f32_16x16x32_bf16 v[124:127], v[156:159], v[180:183], v[124:127]
	v_mfma_f32_16x16x32_bf16 v[112:115], v[148:151], v[188:191], v[112:115]
	v_mfma_f32_16x16x32_bf16 v[108:111], v[156:159], v[188:191], v[108:111]
	v_mfma_f32_16x16x32_bf16 v[96:99], v[148:151], v[196:199], v[96:99]
	v_mfma_f32_16x16x32_bf16 v[92:95], v[156:159], v[196:199], v[92:95]
	v_mfma_f32_16x16x32_bf16 v[80:83], v[148:151], v[210:213], v[80:83]
	v_mfma_f32_16x16x32_bf16 v[76:79], v[156:159], v[210:213], v[76:79]
	v_mfma_f32_16x16x32_bf16 v[128:131], v[152:155], v[184:187], v[128:131]
	v_mfma_f32_16x16x32_bf16 v[124:127], v[160:163], v[184:187], v[124:127]
	v_mfma_f32_16x16x32_bf16 v[112:115], v[152:155], v[192:195], v[112:115]
	v_mfma_f32_16x16x32_bf16 v[108:111], v[160:163], v[192:195], v[108:111]
	v_mfma_f32_16x16x32_bf16 v[96:99], v[152:155], v[206:209], v[96:99]
	v_mfma_f32_16x16x32_bf16 v[92:95], v[160:163], v[206:209], v[92:95]
	v_mfma_f32_16x16x32_bf16 v[80:83], v[152:155], v[230:233], v[80:83]
	v_mfma_f32_16x16x32_bf16 v[76:79], v[160:163], v[230:233], v[76:79]
	s_setprio 0
	s_setprio 1
	v_mfma_f32_16x16x32_bf16 v[120:123], v[164:167], v[180:183], v[120:123]
	v_mfma_f32_16x16x32_bf16 v[116:119], v[172:175], v[180:183], v[116:119]
	v_mfma_f32_16x16x32_bf16 v[104:107], v[164:167], v[188:191], v[104:107]
	v_mfma_f32_16x16x32_bf16 v[100:103], v[172:175], v[188:191], v[100:103]
	v_mfma_f32_16x16x32_bf16 v[88:91], v[164:167], v[196:199], v[88:91]
	v_mfma_f32_16x16x32_bf16 v[84:87], v[172:175], v[196:199], v[84:87]
	v_mfma_f32_16x16x32_bf16 v[72:75], v[164:167], v[210:213], v[72:75]
	v_mfma_f32_16x16x32_bf16 v[68:71], v[172:175], v[210:213], v[68:71]
	v_mfma_f32_16x16x32_bf16 v[120:123], v[168:171], v[184:187], v[120:123]
	v_mfma_f32_16x16x32_bf16 v[116:119], v[176:179], v[184:187], v[116:119]
	v_mfma_f32_16x16x32_bf16 v[104:107], v[168:171], v[192:195], v[104:107]
	v_mfma_f32_16x16x32_bf16 v[100:103], v[176:179], v[192:195], v[100:103]
	v_mfma_f32_16x16x32_bf16 v[88:91], v[168:171], v[206:209], v[88:91]
	v_mfma_f32_16x16x32_bf16 v[84:87], v[176:179], v[206:209], v[84:87]
	v_mfma_f32_16x16x32_bf16 v[72:75], v[168:171], v[230:233], v[72:75]
	v_mfma_f32_16x16x32_bf16 v[68:71], v[176:179], v[230:233], v[68:71]
	s_setprio 0
	s_barrier
	s_add_i32 s8, s12, s4
	v_lshl_add_u64 v[200:201], s[86:87], 0, v[136:137]
	s_mov_b32 m0, s8
	ds_read_b128 v[180:183], v147 offset:16384
	ds_read_b128 v[184:187], v147 offset:17408
	ds_read_b128 v[188:191], v147 offset:18432
	ds_read_b128 v[192:195], v147 offset:19456
	ds_read_b128 v[196:199], v147 offset:20480
	ds_read_b128 v[206:209], v147 offset:21504
	ds_read_b128 v[210:213], v147 offset:22528
	ds_read_b128 v[230:233], v147 offset:23552
	global_load_lds_dwordx4 v[200:201], off
	s_add_i32 m0, s8, 0x2000
	s_add_u32 s8, s86, 0x200000
	v_lshl_add_u64 v[234:235], s[86:87], 0, v[132:133]
	s_addc_u32 s9, s87, 0
	s_add_i32 s10, s10, s4
	global_load_lds_dwordx4 v[234:235], off
	v_lshl_add_u64 v[236:237], s[8:9], 0, v[136:137]
	s_mov_b32 m0, s10
	v_lshl_add_u64 v[238:239], s[88:89], 0, v[134:135]
	global_load_lds_dwordx4 v[236:237], off
	v_lshl_add_u64 v[236:237], s[8:9], 0, v[132:133]
	s_add_i32 m0, s10, 0x2000
	s_nop 0
	global_load_lds_dwordx4 v[236:237], off
	v_lshl_add_u64 v[236:237], s[88:89], 0, v[138:139]
	s_mov_b32 m0, s7
	s_nop 0
	global_load_lds_dwordx4 v[236:237], off
	s_mov_b32 m0, s36
	s_nop 0
	global_load_lds_dwordx4 v[238:239], off
	s_waitcnt vmcnt(8)
	s_waitcnt lgkmcnt(0)
	s_barrier
; #define PG8_STAGE2(bufoff, gbase, voff) do { _Pragma("unroll") for (int _i = 0; _i < 2; ++_i) \
;         __builtin_amdgcn_global_load_lds((const unsigned*)((const char*)(gbase) + (voff)[_i]), (LAS unsigned*)(lds + (bufoff) + ldsw + _i * 8192), 16, 0, 0); } while (0)
; #define PG8_LDA(dst, b, h) do { _Pragma("unroll") for (int m = 0; m < 4; ++m) _Pragma("unroll") for (int k = 0; k < 2; ++k) dst[m][k] = *(const LAS bf16x8*)(lds + PG8_SA(b, h) + aoff + m * 2048 + k * 1024); } while (0)
; #define PG8_LDB(dst, b, h) do { _Pragma("unroll") for (int n = 0; n < 2; ++n) _Pragma("unroll") for (int k = 0; k < 2; ++k) dst[n][k] = *(const LAS bf16x8*)(lds + PG8_SB(b, h) + boff + n * 2048 + k * 1024); } while (0)
; #define PG8_MMA(ai, bj, At, Bt) do { __builtin_amdgcn_s_setprio(1); _Pragma("unroll") for (int m = 0; m < 4; ++m) _Pragma("unroll") for (int n = 0; n < 2; ++n) _Pragma("unroll") for (int k = 0; k < 2; ++k) \
;         acc[ai][bj][m][n] = __builtin_amdgcn_mfma_f32_16x16x32_bf16(Bt[n][k], At[m][k], acc[ai][bj][m][n], 0, 0, 0); __builtin_amdgcn_s_setprio(0); } while (0)
; #define PG8_WAIT_V(n) asm volatile("s_waitcnt vmcnt(" #n ")" ::: "memory")
; #define PG8_WAIT_L(n) asm volatile("s_waitcnt lgkmcnt(" #n ")" ::: "memory")
; #define PG8_BAR __builtin_amdgcn_s_barrier()
; #define PG8_SCHED __builtin_amdgcn_sched_barrier(0)
; template <class Epi>
; __device__ __forceinline__ void gemm_phase(LAS unsigned char* lds, const Sched& S, const Epi& E) {
;     ...
;             PG8_WAIT_V(8); PG8_WAIT_L(0); PG8_BAR; PG8_MMA(1, 0, At, B0); PG8_MMA(1, 1, At, B1); PG8_BAR; PG8_SCHED;
;             PG8_LDB(B0, 1, 0); PG8_LDB(B1, 1, 1); PG8_SCHED; PG8_LDA(At, 1, 0); PG8_STAGE2(PG8_SA(0, 1), a2 + hstep, voffA);
;             PG8_WAIT_V(8); PG8_WAIT_L(0); PG8_BAR; PG8_MMA(0, 0, At, B0); PG8_MMA(0, 1, At, B1); PG8_BAR; PG8_SCHED;
;             PG8_LDA(At, 1, 1); PG8_STAGE2(PG8_SB(1, 0), b3, voffB); PG8_STAGE2(PG8_SB(1, 1), b3 + hstep, voffB); PG8_STAGE2(PG8_SA(1, 0), a3, voffA);
	s_setprio 1
	s_waitcnt lgkmcnt(0)
	v_mfma_f32_16x16x32_bf16 v[64:67], v[148:151], v[180:183], v[64:67]
	v_mfma_f32_16x16x32_bf16 v[60:63], v[156:159], v[180:183], v[60:63]
	v_mfma_f32_16x16x32_bf16 v[48:51], v[148:151], v[188:191], v[48:51]
	v_mfma_f32_16x16x32_bf16 v[44:47], v[156:159], v[188:191], v[44:47]
	v_mfma_f32_16x16x32_bf16 v[32:35], v[148:151], v[196:199], v[32:35]
	v_mfma_f32_16x16x32_bf16 v[28:31], v[156:159], v[196:199], v[28:31]
	v_mfma_f32_16x16x32_bf16 v[16:19], v[148:151], v[210:213], v[16:19]
	v_mfma_f32_16x16x32_bf16 v[12:15], v[156:159], v[210:213], v[12:15]
	v_mfma_f32_16x16x32_bf16 v[64:67], v[152:155], v[184:187], v[64:67]
	v_mfma_f32_16x16x32_bf16 v[60:63], v[160:163], v[184:187], v[60:63]
	v_mfma_f32_16x16x32_bf16 v[48:51], v[152:155], v[192:195], v[48:51]
	v_mfma_f32_16x16x32_bf16 v[44:47], v[160:163], v[192:195], v[44:47]
	v_mfma_f32_16x16x32_bf16 v[32:35], v[152:155], v[206:209], v[32:35]
	v_mfma_f32_16x16x32_bf16 v[28:31], v[160:163], v[206:209], v[28:31]
	v_mfma_f32_16x16x32_bf16 v[16:19], v[152:155], v[230:233], v[16:19]
	v_mfma_f32_16x16x32_bf16 v[12:15], v[160:163], v[230:233], v[12:15]
	s_setprio 0
	s_setprio 1
	v_mfma_f32_16x16x32_bf16 v[56:59], v[164:167], v[180:183], v[56:59]
	v_mfma_f32_16x16x32_bf16 v[52:55], v[172:175], v[180:183], v[52:55]
	v_mfma_f32_16x16x32_bf16 v[40:43], v[164:167], v[188:191], v[40:43]
	v_mfma_f32_16x16x32_bf16 v[36:39], v[172:175], v[188:191], v[36:39]
	v_mfma_f32_16x16x32_bf16 v[24:27], v[164:167], v[196:199], v[24:27]
	v_mfma_f32_16x16x32_bf16 v[20:23], v[172:175], v[196:199], v[20:23]
	v_mfma_f32_16x16x32_bf16 v[8:11], v[164:167], v[210:213], v[8:11]
	v_mfma_f32_16x16x32_bf16 v[4:7], v[172:175], v[210:213], v[4:7]
	v_mfma_f32_16x16x32_bf16 v[56:59], v[168:171], v[184:187], v[56:59]
	v_mfma_f32_16x16x32_bf16 v[52:55], v[176:179], v[184:187], v[52:55]
	v_mfma_f32_16x16x32_bf16 v[40:43], v[168:171], v[192:195], v[40:43]
	v_mfma_f32_16x16x32_bf16 v[36:39], v[176:179], v[192:195], v[36:39]
	v_mfma_f32_16x16x32_bf16 v[24:27], v[168:171], v[206:209], v[24:27]
	v_mfma_f32_16x16x32_bf16 v[20:23], v[176:179], v[206:209], v[20:23]
	v_mfma_f32_16x16x32_bf16 v[8:11], v[168:171], v[230:233], v[8:11]
	v_mfma_f32_16x16x32_bf16 v[4:7], v[176:179], v[230:233], v[4:7]
	s_setprio 0
	s_barrier
	s_add_i32 s10, 0, 0x18000
	v_add_u32_e32 v1, s10, v146
	s_add_i32 s11, 0, 0x1c000
	ds_read_b128 v[148:151], v1
	ds_read_b128 v[152:155], v1 offset:1024
	ds_read_b128 v[156:159], v1 offset:2048
	ds_read_b128 v[160:163], v1 offset:3072
	v_add_u32_e32 v1, s11, v146
	ds_read_b128 v[164:167], v1
	ds_read_b128 v[168:171], v1 offset:1024
	ds_read_b128 v[172:175], v1 offset:2048
	ds_read_b128 v[176:179], v1 offset:3072
	s_add_u32 s8, s88, 0x200000
	s_addc_u32 s9, s89, 0
	s_mov_b32 m0, s54
	v_lshl_add_u64 v[240:241], s[8:9], 0, v[138:139]
	ds_read_b128 v[180:183], v147 offset:32768
	ds_read_b128 v[184:187], v147 offset:33792
	ds_read_b128 v[188:191], v147 offset:34816
	ds_read_b128 v[192:195], v147 offset:35840
	ds_read_b128 v[196:199], v147 offset:36864
	ds_read_b128 v[206:209], v147 offset:37888
	ds_read_b128 v[210:213], v147 offset:38912
	ds_read_b128 v[230:233], v147 offset:39936
	global_load_lds_dwordx4 v[240:241], off
	v_lshl_add_u64 v[240:241], s[8:9], 0, v[134:135]
	s_mov_b32 m0, s55
	s_nop 0
	global_load_lds_dwordx4 v[240:241], off
	s_waitcnt vmcnt(8)
	s_waitcnt lgkmcnt(0)
	s_barrier
	s_setprio 1
	s_waitcnt lgkmcnt(0)
	v_mfma_f32_16x16x32_bf16 v[128:131], v[148:151], v[180:183], v[128:131]
	v_mfma_f32_16x16x32_bf16 v[124:127], v[156:159], v[180:183], v[124:127]
	v_mfma_f32_16x16x32_bf16 v[112:115], v[148:151], v[188:191], v[112:115]
	v_mfma_f32_16x16x32_bf16 v[108:111], v[156:159], v[188:191], v[108:111]
	v_mfma_f32_16x16x32_bf16 v[96:99], v[148:151], v[196:199], v[96:99]
	v_mfma_f32_16x16x32_bf16 v[92:95], v[156:159], v[196:199], v[92:95]
	v_mfma_f32_16x16x32_bf16 v[80:83], v[148:151], v[210:213], v[80:83]
	v_mfma_f32_16x16x32_bf16 v[76:79], v[156:159], v[210:213], v[76:79]
	v_mfma_f32_16x16x32_bf16 v[128:131], v[152:155], v[184:187], v[128:131]
	v_mfma_f32_16x16x32_bf16 v[124:127], v[160:163], v[184:187], v[124:127]
	v_mfma_f32_16x16x32_bf16 v[112:115], v[152:155], v[192:195], v[112:115]
	v_mfma_f32_16x16x32_bf16 v[108:111], v[160:163], v[192:195], v[108:111]
	v_mfma_f32_16x16x32_bf16 v[96:99], v[152:155], v[206:209], v[96:99]
	v_mfma_f32_16x16x32_bf16 v[92:95], v[160:163], v[206:209], v[92:95]
	v_mfma_f32_16x16x32_bf16 v[80:83], v[152:155], v[230:233], v[80:83]
	v_mfma_f32_16x16x32_bf16 v[76:79], v[160:163], v[230:233], v[76:79]
	s_setprio 0
	s_setprio 1
	v_mfma_f32_16x16x32_bf16 v[120:123], v[164:167], v[180:183], v[120:123]
	v_mfma_f32_16x16x32_bf16 v[116:119], v[172:175], v[180:183], v[116:119]
	v_mfma_f32_16x16x32_bf16 v[104:107], v[164:167], v[188:191], v[104:107]
	v_mfma_f32_16x16x32_bf16 v[100:103], v[172:175], v[188:191], v[100:103]
	v_mfma_f32_16x16x32_bf16 v[88:91], v[164:167], v[196:199], v[88:91]
	v_mfma_f32_16x16x32_bf16 v[84:87], v[172:175], v[196:199], v[84:87]
	v_mfma_f32_16x16x32_bf16 v[72:75], v[164:167], v[210:213], v[72:75]
	v_mfma_f32_16x16x32_bf16 v[68:71], v[172:175], v[210:213], v[68:71]
	v_mfma_f32_16x16x32_bf16 v[120:123], v[168:171], v[184:187], v[120:123]
	v_mfma_f32_16x16x32_bf16 v[116:119], v[176:179], v[184:187], v[116:119]
	v_mfma_f32_16x16x32_bf16 v[104:107], v[168:171], v[192:195], v[104:107]
	v_mfma_f32_16x16x32_bf16 v[100:103], v[176:179], v[192:195], v[100:103]
	v_mfma_f32_16x16x32_bf16 v[88:91], v[168:171], v[206:209], v[88:91]
	v_mfma_f32_16x16x32_bf16 v[84:87], v[176:179], v[206:209], v[84:87]
	v_mfma_f32_16x16x32_bf16 v[72:75], v[168:171], v[230:233], v[72:75]
	v_mfma_f32_16x16x32_bf16 v[68:71], v[176:179], v[230:233], v[68:71]
	s_setprio 0
	s_barrier
; #define PG8_STAGE2(bufoff, gbase, voff) do { _Pragma("unroll") for (int _i = 0; _i < 2; ++_i) \
;         __builtin_amdgcn_global_load_lds((const unsigned*)((const char*)(gbase) + (voff)[_i]), (LAS unsigned*)(lds + (bufoff) + ldsw + _i * 8192), 16, 0, 0); } while (0)
; #define PG8_LDA(dst, b, h) do { _Pragma("unroll") for (int m = 0; m < 4; ++m) _Pragma("unroll") for (int k = 0; k < 2; ++k) dst[m][k] = *(const LAS bf16x8*)(lds + PG8_SA(b, h) + aoff + m * 2048 + k * 1024); } while (0)
; #define PG8_MMA(ai, bj, At, Bt) do { __builtin_amdgcn_s_setprio(1); _Pragma("unroll") for (int m = 0; m < 4; ++m) _Pragma("unroll") for (int n = 0; n < 2; ++n) _Pragma("unroll") for (int k = 0; k < 2; ++k) \
;         acc[ai][bj][m][n] = __builtin_amdgcn_mfma_f32_16x16x32_bf16(Bt[n][k], At[m][k], acc[ai][bj][m][n], 0, 0, 0); __builtin_amdgcn_s_setprio(0); } while (0)
; #define PG8_WAIT_V(n) asm volatile("s_waitcnt vmcnt(" #n ")" ::: "memory")
; #define PG8_WAIT_L(n) asm volatile("s_waitcnt lgkmcnt(" #n ")" ::: "memory")
; #define PG8_BAR __builtin_amdgcn_s_barrier()
; #define PG8_SCHED __builtin_amdgcn_sched_barrier(0)
; template <class Epi>
; __device__ __forceinline__ void gemm_phase(LAS unsigned char* lds, const Sched& S, const Epi& E) {
;     ...
;             PG8_LDA(At, 1, 1); PG8_STAGE2(PG8_SB(1, 0), b3, voffB); PG8_STAGE2(PG8_SB(1, 1), b3 + hstep, voffB); PG8_STAGE2(PG8_SA(1, 0), a3, voffA);
;             PG8_WAIT_V(8); PG8_WAIT_L(0); PG8_BAR; PG8_MMA(1, 0, At, B0); PG8_MMA(1, 1, At, B1); PG8_BAR; PG8_SCHED;
;         }
	s_add_i32 s8, s10, s4
	v_lshl_add_u64 v[200:201], v[200:201], 0, s[22:23]
	s_mov_b32 m0, s8
	ds_read_b128 v[180:183], v147 offset:49152
	ds_read_b128 v[184:187], v147 offset:50176
	ds_read_b128 v[188:191], v147 offset:51200
	ds_read_b128 v[192:195], v147 offset:52224
	ds_read_b128 v[196:199], v147 offset:53248
	ds_read_b128 v[206:209], v147 offset:54272
	ds_read_b128 v[210:213], v147 offset:55296
	ds_read_b128 v[230:233], v147 offset:56320
	global_load_lds_dwordx4 v[200:201], off
	s_add_i32 m0, s8, 0x2000
	s_add_u32 s8, s86, 0x200080
	v_lshl_add_u64 v[200:201], v[234:235], 0, s[22:23]
	s_addc_u32 s9, s87, 0
	s_add_i32 s10, s11, s4
	global_load_lds_dwordx4 v[200:201], off
	v_lshl_add_u64 v[200:201], s[8:9], 0, v[136:137]
	s_mov_b32 m0, s10
	s_nop 0
	global_load_lds_dwordx4 v[200:201], off
	v_lshl_add_u64 v[200:201], s[8:9], 0, v[132:133]
	s_add_i32 m0, s10, 0x2000
	s_nop 0
	global_load_lds_dwordx4 v[200:201], off
	v_lshl_add_u64 v[200:201], v[236:237], 0, s[22:23]
	s_mov_b32 m0, s50
	s_nop 0
	global_load_lds_dwordx4 v[200:201], off
	v_lshl_add_u64 v[200:201], v[238:239], 0, s[22:23]
	s_mov_b32 m0, s51
	s_nop 0
	global_load_lds_dwordx4 v[200:201], off
	s_waitcnt vmcnt(8)
	s_waitcnt lgkmcnt(0)
	s_barrier
	s_setprio 1
	s_waitcnt lgkmcnt(0)
	v_mfma_f32_16x16x32_bf16 v[64:67], v[148:151], v[180:183], v[64:67]
	v_mfma_f32_16x16x32_bf16 v[60:63], v[156:159], v[180:183], v[60:63]
	v_mfma_f32_16x16x32_bf16 v[48:51], v[148:151], v[188:191], v[48:51]
	v_mfma_f32_16x16x32_bf16 v[44:47], v[156:159], v[188:191], v[44:47]
	v_mfma_f32_16x16x32_bf16 v[32:35], v[148:151], v[196:199], v[32:35]
	v_mfma_f32_16x16x32_bf16 v[28:31], v[156:159], v[196:199], v[28:31]
	v_mfma_f32_16x16x32_bf16 v[16:19], v[148:151], v[210:213], v[16:19]
	v_mfma_f32_16x16x32_bf16 v[12:15], v[156:159], v[210:213], v[12:15]
	v_mfma_f32_16x16x32_bf16 v[64:67], v[152:155], v[184:187], v[64:67]
	v_mfma_f32_16x16x32_bf16 v[60:63], v[160:163], v[184:187], v[60:63]
	v_mfma_f32_16x16x32_bf16 v[48:51], v[152:155], v[192:195], v[48:51]
	v_mfma_f32_16x16x32_bf16 v[44:47], v[160:163], v[192:195], v[44:47]
	v_mfma_f32_16x16x32_bf16 v[32:35], v[152:155], v[206:209], v[32:35]
	v_mfma_f32_16x16x32_bf16 v[28:31], v[160:163], v[206:209], v[28:31]
	v_mfma_f32_16x16x32_bf16 v[16:19], v[152:155], v[230:233], v[16:19]
	v_mfma_f32_16x16x32_bf16 v[12:15], v[160:163], v[230:233], v[12:15]
	s_setprio 0
	s_setprio 1
	v_mfma_f32_16x16x32_bf16 v[56:59], v[164:167], v[180:183], v[56:59]
	v_mfma_f32_16x16x32_bf16 v[52:55], v[172:175], v[180:183], v[52:55]
	v_mfma_f32_16x16x32_bf16 v[40:43], v[164:167], v[188:191], v[40:43]
	v_mfma_f32_16x16x32_bf16 v[36:39], v[172:175], v[188:191], v[36:39]
	v_mfma_f32_16x16x32_bf16 v[24:27], v[164:167], v[196:199], v[24:27]
	v_mfma_f32_16x16x32_bf16 v[20:23], v[172:175], v[196:199], v[20:23]
	v_mfma_f32_16x16x32_bf16 v[8:11], v[164:167], v[210:213], v[8:11]
	v_mfma_f32_16x16x32_bf16 v[4:7], v[172:175], v[210:213], v[4:7]
	v_mfma_f32_16x16x32_bf16 v[56:59], v[168:171], v[184:187], v[56:59]
	v_mfma_f32_16x16x32_bf16 v[52:55], v[176:179], v[184:187], v[52:55]
	v_mfma_f32_16x16x32_bf16 v[40:43], v[168:171], v[192:195], v[40:43]
	v_mfma_f32_16x16x32_bf16 v[36:39], v[176:179], v[192:195], v[36:39]
	v_mfma_f32_16x16x32_bf16 v[24:27], v[168:171], v[206:209], v[24:27]
	v_mfma_f32_16x16x32_bf16 v[20:23], v[176:179], v[206:209], v[20:23]
	v_mfma_f32_16x16x32_bf16 v[8:11], v[168:171], v[230:233], v[8:11]
	v_mfma_f32_16x16x32_bf16 v[4:7], v[176:179], v[230:233], v[4:7]
	s_setprio 0
	s_add_i32 vcc_hi, vcc_hi, 2
	s_add_u32 s84, s84, 0x100
	s_addc_u32 s85, s85, 0
	s_cmpk_gt_u32 vcc_hi, 0x7d
	s_barrier
	s_cbranch_scc0 .LBB0_1080
	s_and_b64 vcc, exec, s[66:67]
	s_cbranch_vccz .LBB0_1083
	s_barrier

; #define PG8_STAGE2(bufoff, gbase, voff) do { _Pragma("unroll") for (int _i = 0; _i < 2; ++_i) \
;         __builtin_amdgcn_global_load_lds((const unsigned*)((const char*)(gbase) + (voff)[_i]), (LAS unsigned*)(lds + (bufoff) + ldsw + _i * 8192), 16, 0, 0); } while (0)
; #define PG8_LDA(dst, b, h) do { _Pragma("unroll") for (int m = 0; m < 4; ++m) _Pragma("unroll") for (int k = 0; k < 2; ++k) dst[m][k] = *(const LAS bf16x8*)(lds + PG8_SA(b, h) + aoff + m * 2048 + k * 1024); } while (0)
; #define PG8_LDB(dst, b, h) do { _Pragma("unroll") for (int n = 0; n < 2; ++n) _Pragma("unroll") for (int k = 0; k < 2; ++k) dst[n][k] = *(const LAS bf16x8*)(lds + PG8_SB(b, h) + boff + n * 2048 + k * 1024); } while (0)
; #define PG8_MMA(ai, bj, At, Bt) do { __builtin_amdgcn_s_setprio(1); _Pragma("unroll") for (int m = 0; m < 4; ++m) _Pragma("unroll") for (int n = 0; n < 2; ++n) _Pragma("unroll") for (int k = 0; k < 2; ++k) \
;         acc[ai][bj][m][n] = __builtin_amdgcn_mfma_f32_16x16x32_bf16(Bt[n][k], At[m][k], acc[ai][bj][m][n], 0, 0, 0); __builtin_amdgcn_s_setprio(0); } while (0)
; #define PG8_WAIT_V(n) asm volatile("s_waitcnt vmcnt(" #n ")" ::: "memory")
; #define PG8_WAIT_L(n) asm volatile("s_waitcnt lgkmcnt(" #n ")" ::: "memory")
; #define PG8_BAR __builtin_amdgcn_s_barrier()
; #define PG8_SCHED __builtin_amdgcn_sched_barrier(0)
; template <class Epi>
; __device__ __forceinline__ void gemm_phase(LAS unsigned char* lds, const Sched& S, const Epi& E) {
;     ...
;             const bool last = (t == nt - 2);
;             const char* a1 = cA + (size_t)(t + 1) * kstep;
;             const char* a2 = last ? nA : cA + (size_t)(t + 2) * kstep; const char* b2 = last ? nB : cB + (size_t)(t + 2) * kstep;
;             const char* a3 = a2 + kstep; const char* b3 = b2 + kstep;
;             PG8_LDB(B0, 0, 0); PG8_LDB(B1, 0, 1); PG8_SCHED; PG8_LDA(At, 0, 0); PG8_STAGE2(PG8_SA(1, 1), a1 + hstep, voffA);
;             PG8_WAIT_V(8); PG8_WAIT_L(0); PG8_BAR; PG8_MMA(0, 0, At, B0); PG8_MMA(0, 1, At, B1); PG8_BAR; PG8_SCHED;
;             PG8_LDA(At, 0, 1); PG8_STAGE2(PG8_SB(0, 0), b2, voffB); PG8_STAGE2(PG8_SB(0, 1), b2 + hstep, voffB); PG8_STAGE2(PG8_SA(0, 0), a2, voffA);
;             PG8_WAIT_V(8); PG8_WAIT_L(0); PG8_BAR; PG8_MMA(1, 0, At, B0); PG8_MMA(1, 1, At, B1); PG8_BAR; PG8_SCHED;
.LBB0_1158:
	s_add_u32 s8, s56, 0xffe00080
	s_addc_u32 s9, s57, -1
	s_add_i32 s10, 0, 0x10000
	s_cmpk_eq_i32 s71, 0x7c
	s_cselect_b32 s61, s6, s9
	s_cselect_b32 s60, s7, s8
	v_add_u32_e32 v146, s10, v148
	s_cselect_b32 s59, s35, s70
	s_cselect_b32 s58, s51, s69
	s_add_i32 s11, 0, 0x14000
	ds_read_b128 v[142:145], v146
	ds_read_b128 v[152:155], v146 offset:1024
	ds_read_b128 v[156:159], v146 offset:2048
	ds_read_b128 v[160:163], v146 offset:3072
	v_add_u32_e32 v146, s11, v148
	ds_read_b128 v[164:167], v146
	ds_read_b128 v[168:171], v146 offset:1024
	ds_read_b128 v[172:175], v146 offset:2048
	ds_read_b128 v[176:179], v146 offset:3072
	v_lshl_add_u64 v[146:147], s[56:57], 0, v[138:139]
	s_add_i32 m0, s62, 0xc000
	ds_read_b128 v[180:183], v150
	ds_read_b128 v[184:187], v150 offset:1024
	ds_read_b128 v[188:191], v150 offset:2048
	ds_read_b128 v[192:195], v150 offset:3072
	ds_read_b128 v[196:199], v150 offset:4096
	ds_read_b128 v[206:209], v150 offset:5120
	ds_read_b128 v[210:213], v150 offset:6144
	ds_read_b128 v[228:231], v150 offset:7168
	global_load_lds_dwordx4 v[146:147], off
	v_lshl_add_u64 v[146:147], s[56:57], 0, v[140:141]
	s_add_i32 m0, s62, 0xe000
	s_nop 0
	global_load_lds_dwordx4 v[146:147], off
	s_waitcnt vmcnt(8)
	s_waitcnt lgkmcnt(0)
	s_barrier
	s_setprio 1
	s_waitcnt lgkmcnt(0)
	v_mfma_f32_16x16x32_bf16 v[126:129], v[142:145], v[180:183], v[126:129]
	v_mfma_f32_16x16x32_bf16 v[122:125], v[156:159], v[180:183], v[122:125]
	v_mfma_f32_16x16x32_bf16 v[110:113], v[142:145], v[188:191], v[110:113]
	v_mfma_f32_16x16x32_bf16 v[106:109], v[156:159], v[188:191], v[106:109]
	v_mfma_f32_16x16x32_bf16 v[94:97], v[142:145], v[196:199], v[94:97]
	v_mfma_f32_16x16x32_bf16 v[90:93], v[156:159], v[196:199], v[90:93]
	v_mfma_f32_16x16x32_bf16 v[78:81], v[142:145], v[210:213], v[78:81]
	v_mfma_f32_16x16x32_bf16 v[74:77], v[156:159], v[210:213], v[74:77]
	v_mfma_f32_16x16x32_bf16 v[126:129], v[152:155], v[184:187], v[126:129]
	v_mfma_f32_16x16x32_bf16 v[122:125], v[160:163], v[184:187], v[122:125]
	v_mfma_f32_16x16x32_bf16 v[110:113], v[152:155], v[192:195], v[110:113]
	v_mfma_f32_16x16x32_bf16 v[106:109], v[160:163], v[192:195], v[106:109]
	v_mfma_f32_16x16x32_bf16 v[94:97], v[152:155], v[206:209], v[94:97]
	v_mfma_f32_16x16x32_bf16 v[90:93], v[160:163], v[206:209], v[90:93]
	v_mfma_f32_16x16x32_bf16 v[78:81], v[152:155], v[228:231], v[78:81]
	v_mfma_f32_16x16x32_bf16 v[74:77], v[160:163], v[228:231], v[74:77]
	s_setprio 0
	s_setprio 1
	v_mfma_f32_16x16x32_bf16 v[118:121], v[164:167], v[180:183], v[118:121]
	v_mfma_f32_16x16x32_bf16 v[114:117], v[172:175], v[180:183], v[114:117]
	v_mfma_f32_16x16x32_bf16 v[102:105], v[164:167], v[188:191], v[102:105]
	v_mfma_f32_16x16x32_bf16 v[98:101], v[172:175], v[188:191], v[98:101]
	v_mfma_f32_16x16x32_bf16 v[86:89], v[164:167], v[196:199], v[86:89]
	v_mfma_f32_16x16x32_bf16 v[82:85], v[172:175], v[196:199], v[82:85]
	v_mfma_f32_16x16x32_bf16 v[70:73], v[164:167], v[210:213], v[70:73]
	v_mfma_f32_16x16x32_bf16 v[66:69], v[172:175], v[210:213], v[66:69]
	v_mfma_f32_16x16x32_bf16 v[118:121], v[168:171], v[184:187], v[118:121]
	v_mfma_f32_16x16x32_bf16 v[114:117], v[176:179], v[184:187], v[114:117]
	v_mfma_f32_16x16x32_bf16 v[102:105], v[168:171], v[192:195], v[102:105]
	v_mfma_f32_16x16x32_bf16 v[98:101], v[176:179], v[192:195], v[98:101]
	v_mfma_f32_16x16x32_bf16 v[86:89], v[168:171], v[206:209], v[86:89]
	v_mfma_f32_16x16x32_bf16 v[82:85], v[176:179], v[206:209], v[82:85]
	v_mfma_f32_16x16x32_bf16 v[70:73], v[168:171], v[228:231], v[70:73]
	v_mfma_f32_16x16x32_bf16 v[66:69], v[176:179], v[228:231], v[66:69]
	s_setprio 0
	s_barrier
	s_add_i32 s8, s10, s36
	v_lshl_add_u64 v[146:147], s[58:59], 0, v[134:135]
	s_mov_b32 m0, s8
	ds_read_b128 v[180:183], v150 offset:16384
	ds_read_b128 v[184:187], v150 offset:17408
	ds_read_b128 v[188:191], v150 offset:18432
	ds_read_b128 v[192:195], v150 offset:19456
	ds_read_b128 v[196:199], v150 offset:20480
	ds_read_b128 v[206:209], v150 offset:21504
	ds_read_b128 v[210:213], v150 offset:22528
	ds_read_b128 v[228:231], v150 offset:23552
	global_load_lds_dwordx4 v[146:147], off
	s_add_i32 m0, s8, 0x2000
	s_add_u32 s8, s58, 0x200000
	v_lshl_add_u64 v[200:201], s[58:59], 0, v[130:131]
	s_addc_u32 s9, s59, 0
	s_add_i32 s10, s11, s36
	global_load_lds_dwordx4 v[200:201], off
	v_lshl_add_u64 v[232:233], s[8:9], 0, v[134:135]
	s_mov_b32 m0, s10
	v_lshl_add_u64 v[234:235], s[60:61], 0, v[132:133]
	global_load_lds_dwordx4 v[232:233], off
	v_lshl_add_u64 v[232:233], s[8:9], 0, v[130:131]
	s_add_i32 m0, s10, 0x2000
	s_nop 0
	global_load_lds_dwordx4 v[232:233], off
	v_lshl_add_u64 v[232:233], s[60:61], 0, v[136:137]
	s_mov_b32 m0, s62
	s_nop 0
	global_load_lds_dwordx4 v[232:233], off
	s_mov_b32 m0, s63
	s_nop 0
	global_load_lds_dwordx4 v[234:235], off
	s_waitcnt vmcnt(8)
	s_waitcnt lgkmcnt(0)
	s_barrier
; #define PG8_STAGE2(bufoff, gbase, voff) do { _Pragma("unroll") for (int _i = 0; _i < 2; ++_i) \
;         __builtin_amdgcn_global_load_lds((const unsigned*)((const char*)(gbase) + (voff)[_i]), (LAS unsigned*)(lds + (bufoff) + ldsw + _i * 8192), 16, 0, 0); } while (0)
; #define PG8_LDA(dst, b, h) do { _Pragma("unroll") for (int m = 0; m < 4; ++m) _Pragma("unroll") for (int k = 0; k < 2; ++k) dst[m][k] = *(const LAS bf16x8*)(lds + PG8_SA(b, h) + aoff + m * 2048 + k * 1024); } while (0)
; #define PG8_LDB(dst, b, h) do { _Pragma("unroll") for (int n = 0; n < 2; ++n) _Pragma("unroll") for (int k = 0; k < 2; ++k) dst[n][k] = *(const LAS bf16x8*)(lds + PG8_SB(b, h) + boff + n * 2048 + k * 1024); } while (0)
; #define PG8_MMA(ai, bj, At, Bt) do { __builtin_amdgcn_s_setprio(1); _Pragma("unroll") for (int m = 0; m < 4; ++m) _Pragma("unroll") for (int n = 0; n < 2; ++n) _Pragma("unroll") for (int k = 0; k < 2; ++k) \
;         acc[ai][bj][m][n] = __builtin_amdgcn_mfma_f32_16x16x32_bf16(Bt[n][k], At[m][k], acc[ai][bj][m][n], 0, 0, 0); __builtin_amdgcn_s_setprio(0); } while (0)
; #define PG8_WAIT_V(n) asm volatile("s_waitcnt vmcnt(" #n ")" ::: "memory")
; #define PG8_WAIT_L(n) asm volatile("s_waitcnt lgkmcnt(" #n ")" ::: "memory")
; #define PG8_BAR __builtin_amdgcn_s_barrier()
; #define PG8_SCHED __builtin_amdgcn_sched_barrier(0)
; template <class Epi>
; __device__ __forceinline__ void gemm_phase(LAS unsigned char* lds, const Sched& S, const Epi& E) {
;     ...
;             PG8_WAIT_V(8); PG8_WAIT_L(0); PG8_BAR; PG8_MMA(1, 0, At, B0); PG8_MMA(1, 1, At, B1); PG8_BAR; PG8_SCHED;
;             PG8_LDB(B0, 1, 0); PG8_LDB(B1, 1, 1); PG8_SCHED; PG8_LDA(At, 1, 0); PG8_STAGE2(PG8_SA(0, 1), a2 + hstep, voffA);
;             PG8_WAIT_V(8); PG8_WAIT_L(0); PG8_BAR; PG8_MMA(0, 0, At, B0); PG8_MMA(0, 1, At, B1); PG8_BAR; PG8_SCHED;
;             PG8_LDA(At, 1, 1); PG8_STAGE2(PG8_SB(1, 0), b3, voffB); PG8_STAGE2(PG8_SB(1, 1), b3 + hstep, voffB); PG8_STAGE2(PG8_SA(1, 0), a3, voffA);
	s_setprio 1
	s_waitcnt lgkmcnt(0)
	v_mfma_f32_16x16x32_bf16 v[62:65], v[142:145], v[180:183], v[62:65]
	v_mfma_f32_16x16x32_bf16 v[58:61], v[156:159], v[180:183], v[58:61]
	v_mfma_f32_16x16x32_bf16 v[46:49], v[142:145], v[188:191], v[46:49]
	v_mfma_f32_16x16x32_bf16 v[42:45], v[156:159], v[188:191], v[42:45]
	v_mfma_f32_16x16x32_bf16 v[30:33], v[142:145], v[196:199], v[30:33]
	v_mfma_f32_16x16x32_bf16 v[26:29], v[156:159], v[196:199], v[26:29]
	v_mfma_f32_16x16x32_bf16 v[14:17], v[142:145], v[210:213], v[14:17]
	v_mfma_f32_16x16x32_bf16 v[10:13], v[156:159], v[210:213], v[10:13]
	v_mfma_f32_16x16x32_bf16 v[62:65], v[152:155], v[184:187], v[62:65]
	v_mfma_f32_16x16x32_bf16 v[58:61], v[160:163], v[184:187], v[58:61]
	v_mfma_f32_16x16x32_bf16 v[46:49], v[152:155], v[192:195], v[46:49]
	v_mfma_f32_16x16x32_bf16 v[42:45], v[160:163], v[192:195], v[42:45]
	v_mfma_f32_16x16x32_bf16 v[30:33], v[152:155], v[206:209], v[30:33]
	v_mfma_f32_16x16x32_bf16 v[26:29], v[160:163], v[206:209], v[26:29]
	v_mfma_f32_16x16x32_bf16 v[14:17], v[152:155], v[228:231], v[14:17]
	v_mfma_f32_16x16x32_bf16 v[10:13], v[160:163], v[228:231], v[10:13]
	s_setprio 0
	s_setprio 1
	v_mfma_f32_16x16x32_bf16 v[54:57], v[164:167], v[180:183], v[54:57]
	v_mfma_f32_16x16x32_bf16 v[50:53], v[172:175], v[180:183], v[50:53]
	v_mfma_f32_16x16x32_bf16 v[38:41], v[164:167], v[188:191], v[38:41]
	v_mfma_f32_16x16x32_bf16 v[34:37], v[172:175], v[188:191], v[34:37]
	v_mfma_f32_16x16x32_bf16 v[22:25], v[164:167], v[196:199], v[22:25]
	v_mfma_f32_16x16x32_bf16 v[18:21], v[172:175], v[196:199], v[18:21]
	v_mfma_f32_16x16x32_bf16 v[6:9], v[164:167], v[210:213], v[6:9]
	v_mfma_f32_16x16x32_bf16 v[2:5], v[172:175], v[210:213], v[2:5]
	v_mfma_f32_16x16x32_bf16 v[54:57], v[168:171], v[184:187], v[54:57]
	v_mfma_f32_16x16x32_bf16 v[50:53], v[176:179], v[184:187], v[50:53]
	v_mfma_f32_16x16x32_bf16 v[38:41], v[168:171], v[192:195], v[38:41]
	v_mfma_f32_16x16x32_bf16 v[34:37], v[176:179], v[192:195], v[34:37]
	v_mfma_f32_16x16x32_bf16 v[22:25], v[168:171], v[206:209], v[22:25]
	v_mfma_f32_16x16x32_bf16 v[18:21], v[176:179], v[206:209], v[18:21]
	v_mfma_f32_16x16x32_bf16 v[6:9], v[168:171], v[228:231], v[6:9]
	v_mfma_f32_16x16x32_bf16 v[2:5], v[176:179], v[228:231], v[2:5]
	s_setprio 0
	s_barrier
	s_add_i32 s10, 0, 0x18000
	v_add_u32_e32 v151, s10, v148
	s_add_i32 s11, 0, 0x1c000
	ds_read_b128 v[142:145], v151
	ds_read_b128 v[152:155], v151 offset:1024
	ds_read_b128 v[156:159], v151 offset:2048
	ds_read_b128 v[160:163], v151 offset:3072
	v_add_u32_e32 v151, s11, v148
	ds_read_b128 v[164:167], v151
	ds_read_b128 v[168:171], v151 offset:1024
	ds_read_b128 v[172:175], v151 offset:2048
	ds_read_b128 v[176:179], v151 offset:3072
	s_add_u32 s8, s60, 0x200000
	s_addc_u32 s9, s61, 0
	s_mov_b32 m0, s64
	v_lshl_add_u64 v[236:237], s[8:9], 0, v[136:137]
	ds_read_b128 v[180:183], v150 offset:32768
	ds_read_b128 v[184:187], v150 offset:33792
	ds_read_b128 v[188:191], v150 offset:34816
	ds_read_b128 v[192:195], v150 offset:35840
	ds_read_b128 v[196:199], v150 offset:36864
	ds_read_b128 v[206:209], v150 offset:37888
	ds_read_b128 v[210:213], v150 offset:38912
	ds_read_b128 v[228:231], v150 offset:39936
	global_load_lds_dwordx4 v[236:237], off
	v_lshl_add_u64 v[236:237], s[8:9], 0, v[132:133]
	s_mov_b32 m0, s65
	s_nop 0
	global_load_lds_dwordx4 v[236:237], off
	s_waitcnt vmcnt(8)
	s_waitcnt lgkmcnt(0)
	s_barrier
	s_setprio 1
	s_waitcnt lgkmcnt(0)
	v_mfma_f32_16x16x32_bf16 v[126:129], v[142:145], v[180:183], v[126:129]
	v_mfma_f32_16x16x32_bf16 v[122:125], v[156:159], v[180:183], v[122:125]
	v_mfma_f32_16x16x32_bf16 v[110:113], v[142:145], v[188:191], v[110:113]
	v_mfma_f32_16x16x32_bf16 v[106:109], v[156:159], v[188:191], v[106:109]
	v_mfma_f32_16x16x32_bf16 v[94:97], v[142:145], v[196:199], v[94:97]
	v_mfma_f32_16x16x32_bf16 v[90:93], v[156:159], v[196:199], v[90:93]
	v_mfma_f32_16x16x32_bf16 v[78:81], v[142:145], v[210:213], v[78:81]
	v_mfma_f32_16x16x32_bf16 v[74:77], v[156:159], v[210:213], v[74:77]
	v_mfma_f32_16x16x32_bf16 v[126:129], v[152:155], v[184:187], v[126:129]
	v_mfma_f32_16x16x32_bf16 v[122:125], v[160:163], v[184:187], v[122:125]
	v_mfma_f32_16x16x32_bf16 v[110:113], v[152:155], v[192:195], v[110:113]
	v_mfma_f32_16x16x32_bf16 v[106:109], v[160:163], v[192:195], v[106:109]
	v_mfma_f32_16x16x32_bf16 v[94:97], v[152:155], v[206:209], v[94:97]
	v_mfma_f32_16x16x32_bf16 v[90:93], v[160:163], v[206:209], v[90:93]
	v_mfma_f32_16x16x32_bf16 v[78:81], v[152:155], v[228:231], v[78:81]
	v_mfma_f32_16x16x32_bf16 v[74:77], v[160:163], v[228:231], v[74:77]
	s_setprio 0
	s_setprio 1
	v_mfma_f32_16x16x32_bf16 v[118:121], v[164:167], v[180:183], v[118:121]
	v_mfma_f32_16x16x32_bf16 v[114:117], v[172:175], v[180:183], v[114:117]
	v_mfma_f32_16x16x32_bf16 v[102:105], v[164:167], v[188:191], v[102:105]
	v_mfma_f32_16x16x32_bf16 v[98:101], v[172:175], v[188:191], v[98:101]
	v_mfma_f32_16x16x32_bf16 v[86:89], v[164:167], v[196:199], v[86:89]
	v_mfma_f32_16x16x32_bf16 v[82:85], v[172:175], v[196:199], v[82:85]
	v_mfma_f32_16x16x32_bf16 v[70:73], v[164:167], v[210:213], v[70:73]
	v_mfma_f32_16x16x32_bf16 v[66:69], v[172:175], v[210:213], v[66:69]
	v_mfma_f32_16x16x32_bf16 v[118:121], v[168:171], v[184:187], v[118:121]
	v_mfma_f32_16x16x32_bf16 v[114:117], v[176:179], v[184:187], v[114:117]
	v_mfma_f32_16x16x32_bf16 v[102:105], v[168:171], v[192:195], v[102:105]
	v_mfma_f32_16x16x32_bf16 v[98:101], v[176:179], v[192:195], v[98:101]
	v_mfma_f32_16x16x32_bf16 v[86:89], v[168:171], v[206:209], v[86:89]
	v_mfma_f32_16x16x32_bf16 v[82:85], v[176:179], v[206:209], v[82:85]
	v_mfma_f32_16x16x32_bf16 v[70:73], v[168:171], v[228:231], v[70:73]
	v_mfma_f32_16x16x32_bf16 v[66:69], v[176:179], v[228:231], v[66:69]
	s_setprio 0
	s_barrier
; #define PG8_STAGE2(bufoff, gbase, voff) do { _Pragma("unroll") for (int _i = 0; _i < 2; ++_i) \
;         __builtin_amdgcn_global_load_lds((const unsigned*)((const char*)(gbase) + (voff)[_i]), (LAS unsigned*)(lds + (bufoff) + ldsw + _i * 8192), 16, 0, 0); } while (0)
; #define PG8_LDA(dst, b, h) do { _Pragma("unroll") for (int m = 0; m < 4; ++m) _Pragma("unroll") for (int k = 0; k < 2; ++k) dst[m][k] = *(const LAS bf16x8*)(lds + PG8_SA(b, h) + aoff + m * 2048 + k * 1024); } while (0)
; #define PG8_MMA(ai, bj, At, Bt) do { __builtin_amdgcn_s_setprio(1); _Pragma("unroll") for (int m = 0; m < 4; ++m) _Pragma("unroll") for (int n = 0; n < 2; ++n) _Pragma("unroll") for (int k = 0; k < 2; ++k) \
;         acc[ai][bj][m][n] = __builtin_amdgcn_mfma_f32_16x16x32_bf16(Bt[n][k], At[m][k], acc[ai][bj][m][n], 0, 0, 0); __builtin_amdgcn_s_setprio(0); } while (0)
; #define PG8_WAIT_V(n) asm volatile("s_waitcnt vmcnt(" #n ")" ::: "memory")
; #define PG8_WAIT_L(n) asm volatile("s_waitcnt lgkmcnt(" #n ")" ::: "memory")
; #define PG8_BAR __builtin_amdgcn_s_barrier()
; #define PG8_SCHED __builtin_amdgcn_sched_barrier(0)
; template <class Epi>
; __device__ __forceinline__ void gemm_phase(LAS unsigned char* lds, const Sched& S, const Epi& E) {
;     ...
;             PG8_LDA(At, 1, 1); PG8_STAGE2(PG8_SB(1, 0), b3, voffB); PG8_STAGE2(PG8_SB(1, 1), b3 + hstep, voffB); PG8_STAGE2(PG8_SA(1, 0), a3, voffA);
;             PG8_WAIT_V(8); PG8_WAIT_L(0); PG8_BAR; PG8_MMA(1, 0, At, B0); PG8_MMA(1, 1, At, B1); PG8_BAR; PG8_SCHED;
;         }
	s_add_i32 s8, s10, s36
	v_lshl_add_u64 v[146:147], v[146:147], 0, s[22:23]
	s_mov_b32 m0, s8
	ds_read_b128 v[180:183], v150 offset:49152
	ds_read_b128 v[184:187], v150 offset:50176
	ds_read_b128 v[188:191], v150 offset:51200
	ds_read_b128 v[192:195], v150 offset:52224
	ds_read_b128 v[196:199], v150 offset:53248
	ds_read_b128 v[206:209], v150 offset:54272
	ds_read_b128 v[210:213], v150 offset:55296
	ds_read_b128 v[228:231], v150 offset:56320
	global_load_lds_dwordx4 v[146:147], off
	s_add_i32 m0, s8, 0x2000
	s_add_u32 s8, s58, 0x200080
	v_lshl_add_u64 v[146:147], v[200:201], 0, s[22:23]
	s_addc_u32 s9, s59, 0
	s_add_i32 s10, s11, s36
	global_load_lds_dwordx4 v[146:147], off
	v_lshl_add_u64 v[146:147], s[8:9], 0, v[134:135]
	s_mov_b32 m0, s10
	s_nop 0
	global_load_lds_dwordx4 v[146:147], off
	v_lshl_add_u64 v[146:147], s[8:9], 0, v[130:131]
	s_add_i32 m0, s10, 0x2000
	s_nop 0
	global_load_lds_dwordx4 v[146:147], off
	v_lshl_add_u64 v[146:147], v[232:233], 0, s[22:23]
	s_mov_b32 m0, s66
	s_nop 0
	global_load_lds_dwordx4 v[146:147], off
	v_lshl_add_u64 v[146:147], v[234:235], 0, s[22:23]
	s_mov_b32 m0, s67
	s_nop 0
	global_load_lds_dwordx4 v[146:147], off
	s_waitcnt vmcnt(8)
	s_waitcnt lgkmcnt(0)
	s_barrier
	s_setprio 1
	s_waitcnt lgkmcnt(0)
	v_mfma_f32_16x16x32_bf16 v[62:65], v[142:145], v[180:183], v[62:65]
	v_mfma_f32_16x16x32_bf16 v[58:61], v[156:159], v[180:183], v[58:61]
	v_mfma_f32_16x16x32_bf16 v[46:49], v[142:145], v[188:191], v[46:49]
	v_mfma_f32_16x16x32_bf16 v[42:45], v[156:159], v[188:191], v[42:45]
	v_mfma_f32_16x16x32_bf16 v[30:33], v[142:145], v[196:199], v[30:33]
	v_mfma_f32_16x16x32_bf16 v[26:29], v[156:159], v[196:199], v[26:29]
	v_mfma_f32_16x16x32_bf16 v[14:17], v[142:145], v[210:213], v[14:17]
	v_mfma_f32_16x16x32_bf16 v[10:13], v[156:159], v[210:213], v[10:13]
	v_mfma_f32_16x16x32_bf16 v[62:65], v[152:155], v[184:187], v[62:65]
	v_mfma_f32_16x16x32_bf16 v[58:61], v[160:163], v[184:187], v[58:61]
	v_mfma_f32_16x16x32_bf16 v[46:49], v[152:155], v[192:195], v[46:49]
	v_mfma_f32_16x16x32_bf16 v[42:45], v[160:163], v[192:195], v[42:45]
	v_mfma_f32_16x16x32_bf16 v[30:33], v[152:155], v[206:209], v[30:33]
	v_mfma_f32_16x16x32_bf16 v[26:29], v[160:163], v[206:209], v[26:29]
	v_mfma_f32_16x16x32_bf16 v[14:17], v[152:155], v[228:231], v[14:17]
	v_mfma_f32_16x16x32_bf16 v[10:13], v[160:163], v[228:231], v[10:13]
	s_setprio 0
	s_setprio 1
	v_mfma_f32_16x16x32_bf16 v[54:57], v[164:167], v[180:183], v[54:57]
	v_mfma_f32_16x16x32_bf16 v[50:53], v[172:175], v[180:183], v[50:53]
	v_mfma_f32_16x16x32_bf16 v[38:41], v[164:167], v[188:191], v[38:41]
	v_mfma_f32_16x16x32_bf16 v[34:37], v[172:175], v[188:191], v[34:37]
	v_mfma_f32_16x16x32_bf16 v[22:25], v[164:167], v[196:199], v[22:25]
	v_mfma_f32_16x16x32_bf16 v[18:21], v[172:175], v[196:199], v[18:21]
	v_mfma_f32_16x16x32_bf16 v[6:9], v[164:167], v[210:213], v[6:9]
	v_mfma_f32_16x16x32_bf16 v[2:5], v[172:175], v[210:213], v[2:5]
	v_mfma_f32_16x16x32_bf16 v[54:57], v[168:171], v[184:187], v[54:57]
	v_mfma_f32_16x16x32_bf16 v[50:53], v[176:179], v[184:187], v[50:53]
	v_mfma_f32_16x16x32_bf16 v[38:41], v[168:171], v[192:195], v[38:41]
	v_mfma_f32_16x16x32_bf16 v[34:37], v[176:179], v[192:195], v[34:37]
	v_mfma_f32_16x16x32_bf16 v[22:25], v[168:171], v[206:209], v[22:25]
	v_mfma_f32_16x16x32_bf16 v[18:21], v[176:179], v[206:209], v[18:21]
	v_mfma_f32_16x16x32_bf16 v[6:9], v[168:171], v[228:231], v[6:9]
	v_mfma_f32_16x16x32_bf16 v[2:5], v[176:179], v[228:231], v[2:5]
	s_setprio 0
	s_add_i32 s71, s71, 2
	s_add_u32 s56, s56, 0x100
	s_addc_u32 s57, s57, 0
	s_add_u32 s69, s69, 0x100
	s_addc_u32 s70, s70, 0
	s_cmpk_gt_u32 s71, 0x7d
	s_barrier
	s_cbranch_scc0 .LBB0_1158
	s_and_b64 vcc, exec, s[28:29]
	s_cbranch_vccz .LBB0_1161
	s_barrier
